# GEMM K-loops: LDS-DMA loads use SGPR base + 32-bit lane offset (drops 6 of the 64-bit VALU address adds per iteration per loop)
# baseline (speedup 1.0000x reference)
; #define PG8_STAGE(bufoff, gbase, voff) do { _Pragma("unroll") for (int _i = 0; _i < 2; ++_i) \
;         __builtin_amdgcn_global_load_lds((const unsigned*)((const char*)(gbase) + (voff)[_i]), (LAS unsigned*)(lds + (bufoff) + ldsw + _i * 8192), 16, 0, 0); } while (0)
; #define PG8_LDA(dst, b, h) do { _Pragma("unroll") for (int m = 0; m < 4; ++m) _Pragma("unroll") for (int k = 0; k < 2; ++k) dst[m][k] = *(const LAS bf16x8*)(lds + PG8_SA(b, h) + aoff + m * 2048 + k * 1024); } while (0)
; #define PG8_LDB(dst, b, h) do { _Pragma("unroll") for (int n = 0; n < 2; ++n) _Pragma("unroll") for (int k = 0; k < 2; ++k) dst[n][k] = *(const LAS bf16x8*)(lds + PG8_SB(b, h) + boff + n * 2048 + k * 1024); } while (0)
; #define PG8_MMA(ai, bj, At, Bt) do { __builtin_amdgcn_s_setprio(1); _Pragma("unroll") for (int m = 0; m < 4; ++m) _Pragma("unroll") for (int n = 0; n < 2; ++n) _Pragma("unroll") for (int k = 0; k < 2; ++k) \
;         acc[ai][bj][m][n] = __builtin_amdgcn_mfma_f32_16x16x32_bf16(Bt[n][k], At[m][k], acc[ai][bj][m][n], 0, 0, 0); __builtin_amdgcn_s_setprio(0); } while (0)
; #define PG8_WAIT_V(n) asm volatile("s_waitcnt vmcnt(" #n ")" ::: "memory")
; #define PG8_WAIT_L(n) asm volatile("s_waitcnt lgkmcnt(" #n ")" ::: "memory")
; #define PG8_BAR __builtin_amdgcn_s_barrier()
; #define PG8_SCHED __builtin_amdgcn_sched_barrier(0)
; template <class Epi, bool KS0 = false>
; __device__ __forceinline__ void gemm_phase(const int WID, LAS unsigned char* lds, const Gemm g, const StaticOrder& S, const Epi& E) {
;     ...
;             PG8_LDB(B0, 0, 0); PG8_SCHED; PG8_LDA(At, 0, 0); PG8_STAGE(PG8_SA(1, 1), a1 + hstep, voffA);
;             PG8_WAIT_L(8); PG8_BAR; PG8_WAIT_L(0); PG8_MMA(0, 0, At, B0); PG8_BAR; PG8_SCHED;
;             PG8_LDB(B1, 0, 1); PG8_STAGE(PG8_SB(0, 0), b2, voffB);
;             PG8_BAR; PG8_WAIT_L(0); PG8_MMA(0, 1, At, B1); PG8_BAR;
;             PG8_LDA(At, 0, 1); PG8_STAGE(PG8_SA(0, 0), a2, voffA);
;             PG8_BAR; PG8_WAIT_L(0); PG8_MMA(1, 0, At, B0); PG8_BAR; PG8_SCHED;
;             PG8_STAGE(PG8_SB(0, 1), b2 + hstep, voffB);
;             PG8_WAIT_V(6); PG8_BAR; PG8_MMA(1, 1, At, B1); PG8_BAR;
.LBB0_86:
	ds_read_b128 v[152:155], v148
	ds_read_b128 v[156:159], v148 offset:1024
	ds_read_b128 v[160:163], v148 offset:2048
	ds_read_b128 v[164:167], v148 offset:3072
	s_add_u32 s22, s20, 0xfff80080
	s_addc_u32 s23, s21, -1
	s_cmp_eq_u32 s50, 28
	s_cselect_b32 s25, s15, s23
	s_cselect_b32 s24, s46, s22
	s_cselect_b32 s23, s13, s49
	s_cselect_b32 s22, s47, s48
	v_lshl_add_u64 v[144:145], s[20:21], 0, v[136:137]
	s_add_i32 m0, s34, 0xc000
	ds_read_b128 v[168:171], v149
	ds_read_b128 v[172:175], v149 offset:1024
	ds_read_b128 v[176:179], v149 offset:2048
	ds_read_b128 v[180:183], v149 offset:3072
	ds_read_b128 v[184:187], v149 offset:4096
	ds_read_b128 v[188:191], v149 offset:5120
	ds_read_b128 v[192:195], v149 offset:6144
	ds_read_b128 v[196:199], v149 offset:7168
	global_load_lds_dwordx4 v[144:145], off
	s_add_i32 m0, s34, 0xe000
	s_nop 0
	global_load_lds_dwordx4 v138, s[20:21]
	s_waitcnt lgkmcnt(8)
	s_barrier
	s_waitcnt lgkmcnt(0)
	v_mfma_f32_16x16x32_bf16 v[124:127], v[152:155], v[168:171], v[124:127]
	v_mfma_f32_16x16x32_bf16 v[120:123], v[160:163], v[168:171], v[120:123]
	v_mfma_f32_16x16x32_bf16 v[112:115], v[152:155], v[176:179], v[112:115]
	v_mfma_f32_16x16x32_bf16 v[104:107], v[160:163], v[176:179], v[104:107]
	v_mfma_f32_16x16x32_bf16 v[100:103], v[152:155], v[184:187], v[100:103]
	v_mfma_f32_16x16x32_bf16 v[92:95], v[160:163], v[184:187], v[92:95]
	v_mfma_f32_16x16x32_bf16 v[84:87], v[152:155], v[192:195], v[84:87]
	v_mfma_f32_16x16x32_bf16 v[76:79], v[160:163], v[192:195], v[76:79]
	v_mfma_f32_16x16x32_bf16 v[124:127], v[156:159], v[172:175], v[124:127]
	v_mfma_f32_16x16x32_bf16 v[120:123], v[164:167], v[172:175], v[120:123]
	v_mfma_f32_16x16x32_bf16 v[112:115], v[156:159], v[180:183], v[112:115]
	v_mfma_f32_16x16x32_bf16 v[104:107], v[164:167], v[180:183], v[104:107]
	v_mfma_f32_16x16x32_bf16 v[100:103], v[156:159], v[188:191], v[100:103]
	v_mfma_f32_16x16x32_bf16 v[92:95], v[164:167], v[188:191], v[92:95]
	v_mfma_f32_16x16x32_bf16 v[84:87], v[156:159], v[196:199], v[84:87]
	v_mfma_f32_16x16x32_bf16 v[76:79], v[164:167], v[196:199], v[76:79]
	s_barrier
	s_add_i32 s51, s42, s26
	v_lshl_add_u64 v[144:145], s[22:23], 0, v[132:133]
	s_mov_b32 m0, s51
	ds_read_b128 v[200:203], v150
	ds_read_b128 v[204:207], v150 offset:1024
	ds_read_b128 v[208:211], v150 offset:2048
	ds_read_b128 v[212:215], v150 offset:3072
	global_load_lds_dwordx4 v[144:145], off
	v_lshl_add_u64 v[216:217], s[22:23], 0, v[128:129]
	s_add_i32 m0, s51, 0x2000
	s_nop 0
	global_load_lds_dwordx4 v[216:217], off
	s_barrier
	s_waitcnt lgkmcnt(0)
	v_mfma_f32_16x16x32_bf16 v[116:119], v[200:203], v[168:171], v[116:119]
	v_mfma_f32_16x16x32_bf16 v[108:111], v[208:211], v[168:171], v[108:111]
	v_mfma_f32_16x16x32_bf16 v[96:99], v[200:203], v[176:179], v[96:99]
	v_mfma_f32_16x16x32_bf16 v[88:91], v[208:211], v[176:179], v[88:91]
	v_mfma_f32_16x16x32_bf16 v[80:83], v[200:203], v[184:187], v[80:83]
	v_mfma_f32_16x16x32_bf16 v[72:75], v[208:211], v[184:187], v[72:75]
	v_mfma_f32_16x16x32_bf16 v[68:71], v[200:203], v[192:195], v[68:71]
	v_mfma_f32_16x16x32_bf16 v[64:67], v[208:211], v[192:195], v[64:67]
	v_mfma_f32_16x16x32_bf16 v[116:119], v[204:207], v[172:175], v[116:119]
	v_mfma_f32_16x16x32_bf16 v[108:111], v[212:215], v[172:175], v[108:111]
	v_mfma_f32_16x16x32_bf16 v[96:99], v[204:207], v[180:183], v[96:99]
	v_mfma_f32_16x16x32_bf16 v[88:91], v[212:215], v[180:183], v[88:91]
	v_mfma_f32_16x16x32_bf16 v[80:83], v[204:207], v[188:191], v[80:83]
	v_mfma_f32_16x16x32_bf16 v[72:75], v[212:215], v[188:191], v[72:75]
	v_mfma_f32_16x16x32_bf16 v[68:71], v[204:207], v[196:199], v[68:71]
	v_mfma_f32_16x16x32_bf16 v[64:67], v[212:215], v[196:199], v[64:67]
	s_mov_b32 m0, s34
	v_lshl_add_u64 v[218:219], s[24:25], 0, v[134:135]
	s_barrier
	ds_read_b128 v[168:171], v149 offset:16384
	ds_read_b128 v[172:175], v149 offset:17408
	ds_read_b128 v[176:179], v149 offset:18432
	ds_read_b128 v[180:183], v149 offset:19456
	ds_read_b128 v[184:187], v149 offset:20480
	ds_read_b128 v[188:191], v149 offset:21504
	ds_read_b128 v[192:195], v149 offset:22528
	ds_read_b128 v[196:199], v149 offset:23552
	global_load_lds_dwordx4 v[218:219], off
	v_lshl_add_u64 v[220:221], s[24:25], 0, v[130:131]
	s_mov_b32 m0, s35
	s_nop 0
	global_load_lds_dwordx4 v[220:221], off
	s_barrier
	s_waitcnt lgkmcnt(0)
	v_mfma_f32_16x16x32_bf16 v[60:63], v[152:155], v[168:171], v[60:63]
	v_mfma_f32_16x16x32_bf16 v[56:59], v[160:163], v[168:171], v[56:59]
	v_mfma_f32_16x16x32_bf16 v[52:55], v[152:155], v[176:179], v[52:55]
	v_mfma_f32_16x16x32_bf16 v[44:47], v[160:163], v[176:179], v[44:47]
	v_mfma_f32_16x16x32_bf16 v[36:39], v[152:155], v[184:187], v[36:39]
	v_mfma_f32_16x16x32_bf16 v[28:31], v[160:163], v[184:187], v[28:31]
	v_mfma_f32_16x16x32_bf16 v[20:23], v[152:155], v[192:195], v[20:23]
	v_mfma_f32_16x16x32_bf16 v[12:15], v[160:163], v[192:195], v[12:15]
	v_mfma_f32_16x16x32_bf16 v[60:63], v[156:159], v[172:175], v[60:63]
	v_mfma_f32_16x16x32_bf16 v[56:59], v[164:167], v[172:175], v[56:59]
	v_mfma_f32_16x16x32_bf16 v[52:55], v[156:159], v[180:183], v[52:55]
	v_mfma_f32_16x16x32_bf16 v[44:47], v[164:167], v[180:183], v[44:47]
	v_mfma_f32_16x16x32_bf16 v[36:39], v[156:159], v[188:191], v[36:39]
	v_mfma_f32_16x16x32_bf16 v[28:31], v[164:167], v[188:191], v[28:31]
	v_mfma_f32_16x16x32_bf16 v[20:23], v[156:159], v[196:199], v[20:23]
	v_mfma_f32_16x16x32_bf16 v[12:15], v[164:167], v[196:199], v[12:15]
	s_barrier
	s_add_u32 s52, s22, 0x80000
	s_addc_u32 s53, s23, 0
	s_add_i32 s51, s43, s26
	s_mov_b32 m0, s51
	s_nop 0
	global_load_lds_dwordx4 v132, s[52:53]
	s_add_i32 m0, s51, 0x2000
	s_nop 0
	global_load_lds_dwordx4 v128, s[52:53]
	s_waitcnt vmcnt(6)
	s_barrier
; #define PG8_STAGE(bufoff, gbase, voff) do { _Pragma("unroll") for (int _i = 0; _i < 2; ++_i) \
;         __builtin_amdgcn_global_load_lds((const unsigned*)((const char*)(gbase) + (voff)[_i]), (LAS unsigned*)(lds + (bufoff) + ldsw + _i * 8192), 16, 0, 0); } while (0)
; #define PG8_LDA(dst, b, h) do { _Pragma("unroll") for (int m = 0; m < 4; ++m) _Pragma("unroll") for (int k = 0; k < 2; ++k) dst[m][k] = *(const LAS bf16x8*)(lds + PG8_SA(b, h) + aoff + m * 2048 + k * 1024); } while (0)
; #define PG8_LDB(dst, b, h) do { _Pragma("unroll") for (int n = 0; n < 2; ++n) _Pragma("unroll") for (int k = 0; k < 2; ++k) dst[n][k] = *(const LAS bf16x8*)(lds + PG8_SB(b, h) + boff + n * 2048 + k * 1024); } while (0)
; #define PG8_MMA(ai, bj, At, Bt) do { __builtin_amdgcn_s_setprio(1); _Pragma("unroll") for (int m = 0; m < 4; ++m) _Pragma("unroll") for (int n = 0; n < 2; ++n) _Pragma("unroll") for (int k = 0; k < 2; ++k) \
;         acc[ai][bj][m][n] = __builtin_amdgcn_mfma_f32_16x16x32_bf16(Bt[n][k], At[m][k], acc[ai][bj][m][n], 0, 0, 0); __builtin_amdgcn_s_setprio(0); } while (0)
; #define PG8_WAIT_V(n) asm volatile("s_waitcnt vmcnt(" #n ")" ::: "memory")
; #define PG8_WAIT_L(n) asm volatile("s_waitcnt lgkmcnt(" #n ")" ::: "memory")
; #define PG8_BAR __builtin_amdgcn_s_barrier()
; #define PG8_SCHED __builtin_amdgcn_sched_barrier(0)
; template <class Epi, bool KS0 = false>
; __device__ __forceinline__ void gemm_phase(const int WID, LAS unsigned char* lds, const Gemm g, const StaticOrder& S, const Epi& E) {
;     ...
;             PG8_WAIT_V(6); PG8_BAR; PG8_MMA(1, 1, At, B1); PG8_BAR;
;             PG8_LDB(B0, 1, 0); PG8_SCHED; PG8_LDA(At, 1, 0); PG8_STAGE(PG8_SA(0, 1), a2 + hstep, voffA);
;             PG8_WAIT_L(8); PG8_BAR; PG8_WAIT_L(0); PG8_MMA(0, 0, At, B0); PG8_BAR; PG8_SCHED;
;             PG8_LDB(B1, 1, 1); PG8_STAGE(PG8_SB(1, 0), b3, voffB);
	v_mfma_f32_16x16x32_bf16 v[48:51], v[200:203], v[168:171], v[48:51]
	v_mfma_f32_16x16x32_bf16 v[40:43], v[208:211], v[168:171], v[40:43]
	v_mfma_f32_16x16x32_bf16 v[32:35], v[200:203], v[176:179], v[32:35]
	v_mfma_f32_16x16x32_bf16 v[24:27], v[208:211], v[176:179], v[24:27]
	v_mfma_f32_16x16x32_bf16 v[16:19], v[200:203], v[184:187], v[16:19]
	v_mfma_f32_16x16x32_bf16 v[8:11], v[208:211], v[184:187], v[8:11]
	v_mfma_f32_16x16x32_bf16 v[4:7], v[200:203], v[192:195], v[4:7]
	v_mfma_f32_16x16x32_bf16 v[0:3], v[208:211], v[192:195], v[0:3]
	v_mfma_f32_16x16x32_bf16 v[48:51], v[204:207], v[172:175], v[48:51]
	v_mfma_f32_16x16x32_bf16 v[40:43], v[212:215], v[172:175], v[40:43]
	v_mfma_f32_16x16x32_bf16 v[32:35], v[204:207], v[180:183], v[32:35]
	v_mfma_f32_16x16x32_bf16 v[24:27], v[212:215], v[180:183], v[24:27]
	v_mfma_f32_16x16x32_bf16 v[16:19], v[204:207], v[188:191], v[16:19]
	v_mfma_f32_16x16x32_bf16 v[8:11], v[212:215], v[188:191], v[8:11]
	v_mfma_f32_16x16x32_bf16 v[4:7], v[204:207], v[196:199], v[4:7]
	v_mfma_f32_16x16x32_bf16 v[0:3], v[212:215], v[196:199], v[0:3]
	s_add_i32 s51, 0, 0x18000
	v_add_u32_e32 v151, s51, v147
	s_barrier
	ds_read_b128 v[152:155], v151
	ds_read_b128 v[156:159], v151 offset:1024
	ds_read_b128 v[160:163], v151 offset:2048
	ds_read_b128 v[164:167], v151 offset:3072
	s_add_u32 s24, s24, 0x80000
	s_addc_u32 s25, s25, 0
	s_mov_b32 m0, s38
	v_lshl_add_u64 v[200:201], s[24:25], 0, v[134:135]
	ds_read_b128 v[168:171], v149 offset:32768
	ds_read_b128 v[172:175], v149 offset:33792
	ds_read_b128 v[176:179], v149 offset:34816
	ds_read_b128 v[180:183], v149 offset:35840
	ds_read_b128 v[184:187], v149 offset:36864
	ds_read_b128 v[188:191], v149 offset:37888
	ds_read_b128 v[192:195], v149 offset:38912
	ds_read_b128 v[196:199], v149 offset:39936
	global_load_lds_dwordx4 v[200:201], off
	s_mov_b32 m0, s39
	s_nop 0
	global_load_lds_dwordx4 v130, s[24:25]
	s_waitcnt lgkmcnt(8)
	s_barrier
	s_waitcnt lgkmcnt(0)
	v_mfma_f32_16x16x32_bf16 v[124:127], v[152:155], v[168:171], v[124:127]
	v_mfma_f32_16x16x32_bf16 v[120:123], v[160:163], v[168:171], v[120:123]
	v_mfma_f32_16x16x32_bf16 v[112:115], v[152:155], v[176:179], v[112:115]
	v_mfma_f32_16x16x32_bf16 v[104:107], v[160:163], v[176:179], v[104:107]
	v_mfma_f32_16x16x32_bf16 v[100:103], v[152:155], v[184:187], v[100:103]
	v_mfma_f32_16x16x32_bf16 v[92:95], v[160:163], v[184:187], v[92:95]
	v_mfma_f32_16x16x32_bf16 v[84:87], v[152:155], v[192:195], v[84:87]
	v_mfma_f32_16x16x32_bf16 v[76:79], v[160:163], v[192:195], v[76:79]
	v_mfma_f32_16x16x32_bf16 v[124:127], v[156:159], v[172:175], v[124:127]
	v_mfma_f32_16x16x32_bf16 v[120:123], v[164:167], v[172:175], v[120:123]
	v_mfma_f32_16x16x32_bf16 v[112:115], v[156:159], v[180:183], v[112:115]
	v_mfma_f32_16x16x32_bf16 v[104:107], v[164:167], v[180:183], v[104:107]
	v_mfma_f32_16x16x32_bf16 v[100:103], v[156:159], v[188:191], v[100:103]
	v_mfma_f32_16x16x32_bf16 v[92:95], v[164:167], v[188:191], v[92:95]
	v_mfma_f32_16x16x32_bf16 v[84:87], v[156:159], v[196:199], v[84:87]
	v_mfma_f32_16x16x32_bf16 v[76:79], v[164:167], v[196:199], v[76:79]
	s_barrier
	s_add_i32 s24, 0, 0x1c000
	s_add_i32 s25, s51, s26
	v_add_u32_e32 v151, s24, v147
	v_lshl_add_u64 v[144:145], v[144:145], 0, s[8:9]
	s_mov_b32 m0, s25
	ds_read_b128 v[200:203], v151
	ds_read_b128 v[204:207], v151 offset:1024
	ds_read_b128 v[208:211], v151 offset:2048
	ds_read_b128 v[212:215], v151 offset:3072
	global_load_lds_dwordx4 v[144:145], off
	v_lshl_add_u64 v[144:145], v[216:217], 0, s[8:9]
	s_add_i32 m0, s25, 0x2000
	s_nop 0
	global_load_lds_dwordx4 v[144:145], off
	s_barrier
; __device__ __forceinline__ int lane_id_() { int l; asm volatile("v_mbcnt_lo_u32_b32 %0, -1, 0\n\tv_mbcnt_hi_u32_b32 %0, -1, %0" : "=v"(l)); return l; }
; #define PG8_STAGE(bufoff, gbase, voff) do { _Pragma("unroll") for (int _i = 0; _i < 2; ++_i) \
;         __builtin_amdgcn_global_load_lds((const unsigned*)((const char*)(gbase) + (voff)[_i]), (LAS unsigned*)(lds + (bufoff) + ldsw + _i * 8192), 16, 0, 0); } while (0)
; #define PG8_LDA(dst, b, h) do { _Pragma("unroll") for (int m = 0; m < 4; ++m) _Pragma("unroll") for (int k = 0; k < 2; ++k) dst[m][k] = *(const LAS bf16x8*)(lds + PG8_SA(b, h) + aoff + m * 2048 + k * 1024); } while (0)
; #define PG8_MMA(ai, bj, At, Bt) do { __builtin_amdgcn_s_setprio(1); _Pragma("unroll") for (int m = 0; m < 4; ++m) _Pragma("unroll") for (int n = 0; n < 2; ++n) _Pragma("unroll") for (int k = 0; k < 2; ++k) \
;         acc[ai][bj][m][n] = __builtin_amdgcn_mfma_f32_16x16x32_bf16(Bt[n][k], At[m][k], acc[ai][bj][m][n], 0, 0, 0); __builtin_amdgcn_s_setprio(0); } while (0)
; #define PG8_WAIT_V(n) asm volatile("s_waitcnt vmcnt(" #n ")" ::: "memory")
; #define PG8_WAIT_L(n) asm volatile("s_waitcnt lgkmcnt(" #n ")" ::: "memory")
; #define PG8_BAR __builtin_amdgcn_s_barrier()
; #define PG8_SCHED __builtin_amdgcn_sched_barrier(0)
; template <class Epi, bool KS0 = false>
; __device__ __forceinline__ void gemm_phase(const int WID, LAS unsigned char* lds, const Gemm g, const StaticOrder& S, const Epi& E) {
;     ...
;             PG8_BAR; PG8_WAIT_L(0); PG8_MMA(0, 1, At, B1); PG8_BAR;
;             PG8_LDA(At, 1, 1); PG8_STAGE(PG8_SA(1, 0), a3, voffA);
;             PG8_BAR; PG8_WAIT_L(0); PG8_MMA(1, 0, At, B0); PG8_BAR; PG8_SCHED;
;             PG8_STAGE(PG8_SB(1, 1), b3 + hstep, voffB);
;             PG8_WAIT_V(6); PG8_BAR; PG8_MMA(1, 1, At, B1); PG8_BAR;
;         }
;         { int fr2 = lane_id_(), fq2; fq2 = fr2 >> 4; fr2 &= 15; asm volatile("" : "+v"(fr2), "+v"(fq2)); E(acc, cur, wr, wc, fr2, fq2); }
;     __device__ __forceinline__ void operator()(f32x4 (&acc)[2][2][4][2], const Unit& u, int wr, int wc, int fr, int fq) const {
;     ...
;         if (frag && u.pn >= fmin) { base = O + ((size_t)(u.pm * frag + u.pn) << 16) + (size_t)((((wr * 4 + wc) * 16) * 64 + fq * 16 + fr) << 3); s_ai = 4096; s_m = 1024; s_bj = 512; }
	s_waitcnt lgkmcnt(0)
	v_mfma_f32_16x16x32_bf16 v[116:119], v[200:203], v[168:171], v[116:119]
	v_mfma_f32_16x16x32_bf16 v[108:111], v[208:211], v[168:171], v[108:111]
	v_mfma_f32_16x16x32_bf16 v[96:99], v[200:203], v[176:179], v[96:99]
	v_mfma_f32_16x16x32_bf16 v[88:91], v[208:211], v[176:179], v[88:91]
	v_mfma_f32_16x16x32_bf16 v[80:83], v[200:203], v[184:187], v[80:83]
	v_mfma_f32_16x16x32_bf16 v[72:75], v[208:211], v[184:187], v[72:75]
	v_mfma_f32_16x16x32_bf16 v[68:71], v[200:203], v[192:195], v[68:71]
	v_mfma_f32_16x16x32_bf16 v[64:67], v[208:211], v[192:195], v[64:67]
	v_mfma_f32_16x16x32_bf16 v[116:119], v[204:207], v[172:175], v[116:119]
	v_mfma_f32_16x16x32_bf16 v[108:111], v[212:215], v[172:175], v[108:111]
	v_mfma_f32_16x16x32_bf16 v[96:99], v[204:207], v[180:183], v[96:99]
	v_mfma_f32_16x16x32_bf16 v[88:91], v[212:215], v[180:183], v[88:91]
	v_mfma_f32_16x16x32_bf16 v[80:83], v[204:207], v[188:191], v[80:83]
	v_mfma_f32_16x16x32_bf16 v[72:75], v[212:215], v[188:191], v[72:75]
	v_mfma_f32_16x16x32_bf16 v[68:71], v[204:207], v[196:199], v[68:71]
	v_mfma_f32_16x16x32_bf16 v[64:67], v[212:215], v[196:199], v[64:67]
	s_mov_b32 m0, s40
	v_lshl_add_u64 v[144:145], v[218:219], 0, s[8:9]
	s_barrier
	ds_read_b128 v[168:171], v149 offset:49152
	ds_read_b128 v[172:175], v149 offset:50176
	ds_read_b128 v[176:179], v149 offset:51200
	ds_read_b128 v[180:183], v149 offset:52224
	ds_read_b128 v[184:187], v149 offset:53248
	ds_read_b128 v[188:191], v149 offset:54272
	ds_read_b128 v[192:195], v149 offset:55296
	ds_read_b128 v[196:199], v149 offset:56320
	global_load_lds_dwordx4 v[144:145], off
	v_lshl_add_u64 v[144:145], v[220:221], 0, s[8:9]
	s_mov_b32 m0, s41
	s_nop 0
	global_load_lds_dwordx4 v[144:145], off
	s_barrier
	s_waitcnt lgkmcnt(0)
	v_mfma_f32_16x16x32_bf16 v[60:63], v[152:155], v[168:171], v[60:63]
	v_mfma_f32_16x16x32_bf16 v[56:59], v[160:163], v[168:171], v[56:59]
	v_mfma_f32_16x16x32_bf16 v[52:55], v[152:155], v[176:179], v[52:55]
	v_mfma_f32_16x16x32_bf16 v[44:47], v[160:163], v[176:179], v[44:47]
	v_mfma_f32_16x16x32_bf16 v[36:39], v[152:155], v[184:187], v[36:39]
	v_mfma_f32_16x16x32_bf16 v[28:31], v[160:163], v[184:187], v[28:31]
	v_mfma_f32_16x16x32_bf16 v[20:23], v[152:155], v[192:195], v[20:23]
	v_mfma_f32_16x16x32_bf16 v[12:15], v[160:163], v[192:195], v[12:15]
	v_mfma_f32_16x16x32_bf16 v[60:63], v[156:159], v[172:175], v[60:63]
	v_mfma_f32_16x16x32_bf16 v[56:59], v[164:167], v[172:175], v[56:59]
	v_mfma_f32_16x16x32_bf16 v[52:55], v[156:159], v[180:183], v[52:55]
	v_mfma_f32_16x16x32_bf16 v[44:47], v[164:167], v[180:183], v[44:47]
	v_mfma_f32_16x16x32_bf16 v[36:39], v[156:159], v[188:191], v[36:39]
	v_mfma_f32_16x16x32_bf16 v[28:31], v[164:167], v[188:191], v[28:31]
	v_mfma_f32_16x16x32_bf16 v[20:23], v[156:159], v[196:199], v[20:23]
	v_mfma_f32_16x16x32_bf16 v[12:15], v[164:167], v[196:199], v[12:15]
	s_barrier
	s_add_u32 s22, s22, 0x80080
	s_addc_u32 s23, s23, 0
	s_add_i32 s24, s24, s26
	s_mov_b32 m0, s24
	s_nop 0
	global_load_lds_dwordx4 v132, s[22:23]
	s_add_i32 m0, s24, 0x2000
	s_nop 0
	global_load_lds_dwordx4 v128, s[22:23]
	s_waitcnt vmcnt(6)
	s_barrier
	v_mfma_f32_16x16x32_bf16 v[48:51], v[200:203], v[168:171], v[48:51]
	v_mfma_f32_16x16x32_bf16 v[40:43], v[208:211], v[168:171], v[40:43]
	v_mfma_f32_16x16x32_bf16 v[32:35], v[200:203], v[176:179], v[32:35]
	v_mfma_f32_16x16x32_bf16 v[24:27], v[208:211], v[176:179], v[24:27]
	v_mfma_f32_16x16x32_bf16 v[16:19], v[200:203], v[184:187], v[16:19]
	v_mfma_f32_16x16x32_bf16 v[8:11], v[208:211], v[184:187], v[8:11]
	v_mfma_f32_16x16x32_bf16 v[4:7], v[200:203], v[192:195], v[4:7]
	v_mfma_f32_16x16x32_bf16 v[0:3], v[208:211], v[192:195], v[0:3]
	v_mfma_f32_16x16x32_bf16 v[48:51], v[204:207], v[172:175], v[48:51]
	v_mfma_f32_16x16x32_bf16 v[40:43], v[212:215], v[172:175], v[40:43]
	v_mfma_f32_16x16x32_bf16 v[32:35], v[204:207], v[180:183], v[32:35]
	v_mfma_f32_16x16x32_bf16 v[24:27], v[212:215], v[180:183], v[24:27]
	v_mfma_f32_16x16x32_bf16 v[16:19], v[204:207], v[188:191], v[16:19]
	v_mfma_f32_16x16x32_bf16 v[8:11], v[212:215], v[188:191], v[8:11]
	v_mfma_f32_16x16x32_bf16 v[4:7], v[204:207], v[196:199], v[4:7]
	v_mfma_f32_16x16x32_bf16 v[0:3], v[212:215], v[196:199], v[0:3]
	s_add_i32 s50, s50, 2
	s_add_u32 s20, s20, 0x100
	s_addc_u32 s21, s21, 0
	s_add_u32 s48, s48, 0x100
	s_addc_u32 s49, s49, 0
	s_cmp_gt_u32 s50, 29
	s_barrier
	s_cbranch_scc0 .LBB0_86
	v_mbcnt_lo_u32_b32 v144, -1, 0
	v_mbcnt_hi_u32_b32 v144, -1, v144
	s_cmp_lt_i32 s45, 8
	v_ashrrev_i32_e32 v145, 4, v144
	v_and_b32_e32 v151, 15, v144
	s_mov_b64 s[20:21], -1
	s_cbranch_scc1 .LBB0_89
	v_add_u32_e32 v144, s55, v151
	v_lshlrev_b32_e32 v152, 7, v145
	v_lshl_add_u32 v144, v144, 3, v152
	s_mov_b64 s[20:21], 0

; #define PG8_STAGE(bufoff, gbase, voff) do { _Pragma("unroll") for (int _i = 0; _i < 2; ++_i) \
;         __builtin_amdgcn_global_load_lds((const unsigned*)((const char*)(gbase) + (voff)[_i]), (LAS unsigned*)(lds + (bufoff) + ldsw + _i * 8192), 16, 0, 0); } while (0)
; #define PG8_LDA(dst, b, h) do { _Pragma("unroll") for (int m = 0; m < 4; ++m) _Pragma("unroll") for (int k = 0; k < 2; ++k) dst[m][k] = *(const LAS bf16x8*)(lds + PG8_SA(b, h) + aoff + m * 2048 + k * 1024); } while (0)
; #define PG8_LDB(dst, b, h) do { _Pragma("unroll") for (int n = 0; n < 2; ++n) _Pragma("unroll") for (int k = 0; k < 2; ++k) dst[n][k] = *(const LAS bf16x8*)(lds + PG8_SB(b, h) + boff + n * 2048 + k * 1024); } while (0)
; #define PG8_MMA(ai, bj, At, Bt) do { __builtin_amdgcn_s_setprio(1); _Pragma("unroll") for (int m = 0; m < 4; ++m) _Pragma("unroll") for (int n = 0; n < 2; ++n) _Pragma("unroll") for (int k = 0; k < 2; ++k) \
;         acc[ai][bj][m][n] = __builtin_amdgcn_mfma_f32_16x16x32_bf16(Bt[n][k], At[m][k], acc[ai][bj][m][n], 0, 0, 0); __builtin_amdgcn_s_setprio(0); } while (0)
; #define PG8_WAIT_V(n) asm volatile("s_waitcnt vmcnt(" #n ")" ::: "memory")
; #define PG8_WAIT_L(n) asm volatile("s_waitcnt lgkmcnt(" #n ")" ::: "memory")
; #define PG8_BAR __builtin_amdgcn_s_barrier()
; #define PG8_SCHED __builtin_amdgcn_sched_barrier(0)
; template <class Epi, bool KS0 = false>
; __device__ __forceinline__ void gemm_phase(const int WID, LAS unsigned char* lds, const Gemm g, const StaticOrder& S, const Epi& E) {
;     ...
;             PG8_LDB(B0, 0, 0); PG8_SCHED; PG8_LDA(At, 0, 0); PG8_STAGE(PG8_SA(1, 1), a1 + hstep, voffA);
;             PG8_WAIT_L(8); PG8_BAR; PG8_WAIT_L(0); PG8_MMA(0, 0, At, B0); PG8_BAR; PG8_SCHED;
;             PG8_LDB(B1, 0, 1); PG8_STAGE(PG8_SB(0, 0), b2, voffB);
;             PG8_BAR; PG8_WAIT_L(0); PG8_MMA(0, 1, At, B1); PG8_BAR;
;             PG8_LDA(At, 0, 1); PG8_STAGE(PG8_SA(0, 0), a2, voffA);
;             PG8_BAR; PG8_WAIT_L(0); PG8_MMA(1, 0, At, B0); PG8_BAR; PG8_SCHED;
;             PG8_STAGE(PG8_SB(0, 1), b2 + hstep, voffB);
;             PG8_WAIT_V(6); PG8_BAR; PG8_MMA(1, 1, At, B1); PG8_BAR;
.LBB0_670:
	ds_read_b128 v[128:131], v206
	ds_read_b128 v[132:135], v206 offset:1024
	ds_read_b128 v[136:139], v206 offset:2048
	ds_read_b128 v[140:143], v206 offset:3072
	s_add_u32 s42, s20, 0xfff80080
	s_addc_u32 s43, s21, -1
	s_cmp_eq_u32 s53, 28
	s_cselect_b32 s45, s11, s43
	s_cselect_b32 s44, s19, s42
	s_cselect_b32 s43, s9, s52
	s_cselect_b32 s42, s50, s51
	v_lshl_add_u64 v[192:193], s[20:21], 0, v[184:185]
	s_add_i32 m0, s23, 0xc000
	ds_read_b128 v[144:147], v207
	ds_read_b128 v[148:151], v207 offset:1024
	ds_read_b128 v[152:155], v207 offset:2048
	ds_read_b128 v[156:159], v207 offset:3072
	ds_read_b128 v[160:163], v207 offset:4096
	ds_read_b128 v[164:167], v207 offset:5120
	ds_read_b128 v[168:171], v207 offset:6144
	ds_read_b128 v[172:175], v207 offset:7168
	global_load_lds_dwordx4 v[192:193], off
	s_add_i32 m0, s23, 0xe000
	s_nop 0
	global_load_lds_dwordx4 v186, s[20:21]
	s_waitcnt lgkmcnt(8)
	s_barrier
	s_waitcnt lgkmcnt(0)
	v_mfma_f32_16x16x32_bf16 v[124:127], v[128:131], v[144:147], v[124:127]
	v_mfma_f32_16x16x32_bf16 v[120:123], v[136:139], v[144:147], v[120:123]
	v_mfma_f32_16x16x32_bf16 v[108:111], v[128:131], v[152:155], v[108:111]
	v_mfma_f32_16x16x32_bf16 v[104:107], v[136:139], v[152:155], v[104:107]
	v_mfma_f32_16x16x32_bf16 v[92:95], v[128:131], v[160:163], v[92:95]
	v_mfma_f32_16x16x32_bf16 v[88:91], v[136:139], v[160:163], v[88:91]
	v_mfma_f32_16x16x32_bf16 v[76:79], v[128:131], v[168:171], v[76:79]
	v_mfma_f32_16x16x32_bf16 v[72:75], v[136:139], v[168:171], v[72:75]
	v_mfma_f32_16x16x32_bf16 v[124:127], v[132:135], v[148:151], v[124:127]
	v_mfma_f32_16x16x32_bf16 v[120:123], v[140:143], v[148:151], v[120:123]
	v_mfma_f32_16x16x32_bf16 v[108:111], v[132:135], v[156:159], v[108:111]
	v_mfma_f32_16x16x32_bf16 v[104:107], v[140:143], v[156:159], v[104:107]
	v_mfma_f32_16x16x32_bf16 v[92:95], v[132:135], v[164:167], v[92:95]
	v_mfma_f32_16x16x32_bf16 v[88:91], v[140:143], v[164:167], v[88:91]
	v_mfma_f32_16x16x32_bf16 v[76:79], v[132:135], v[172:175], v[76:79]
	v_mfma_f32_16x16x32_bf16 v[72:75], v[140:143], v[172:175], v[72:75]
	s_barrier
	s_add_i32 s54, s35, s26
	v_lshl_add_u64 v[214:215], s[42:43], 0, v[178:179]
	s_mov_b32 m0, s54
	ds_read_b128 v[192:195], v208
	ds_read_b128 v[196:199], v208 offset:1024
	ds_read_b128 v[200:203], v208 offset:2048
	ds_read_b128 v[210:213], v208 offset:3072
	global_load_lds_dwordx4 v[214:215], off
	v_lshl_add_u64 v[216:217], s[42:43], 0, v[182:183]
	s_add_i32 m0, s54, 0x2000
	s_nop 0
	global_load_lds_dwordx4 v[216:217], off
	s_barrier
	s_waitcnt lgkmcnt(0)
	v_mfma_f32_16x16x32_bf16 v[116:119], v[192:195], v[144:147], v[116:119]
	v_mfma_f32_16x16x32_bf16 v[112:115], v[200:203], v[144:147], v[112:115]
	v_mfma_f32_16x16x32_bf16 v[100:103], v[192:195], v[152:155], v[100:103]
	v_mfma_f32_16x16x32_bf16 v[96:99], v[200:203], v[152:155], v[96:99]
	v_mfma_f32_16x16x32_bf16 v[84:87], v[192:195], v[160:163], v[84:87]
	v_mfma_f32_16x16x32_bf16 v[80:83], v[200:203], v[160:163], v[80:83]
	v_mfma_f32_16x16x32_bf16 v[68:71], v[192:195], v[168:171], v[68:71]
	v_mfma_f32_16x16x32_bf16 v[64:67], v[200:203], v[168:171], v[64:67]
	v_mfma_f32_16x16x32_bf16 v[116:119], v[196:199], v[148:151], v[116:119]
	v_mfma_f32_16x16x32_bf16 v[112:115], v[210:213], v[148:151], v[112:115]
	v_mfma_f32_16x16x32_bf16 v[100:103], v[196:199], v[156:159], v[100:103]
	v_mfma_f32_16x16x32_bf16 v[96:99], v[210:213], v[156:159], v[96:99]
	v_mfma_f32_16x16x32_bf16 v[84:87], v[196:199], v[164:167], v[84:87]
	v_mfma_f32_16x16x32_bf16 v[80:83], v[210:213], v[164:167], v[80:83]
	v_mfma_f32_16x16x32_bf16 v[68:71], v[196:199], v[172:175], v[68:71]
	v_mfma_f32_16x16x32_bf16 v[64:67], v[210:213], v[172:175], v[64:67]
	s_mov_b32 m0, s23
	v_lshl_add_u64 v[218:219], s[44:45], 0, v[176:177]
	s_barrier
	ds_read_b128 v[144:147], v207 offset:16384
	ds_read_b128 v[148:151], v207 offset:17408
	ds_read_b128 v[152:155], v207 offset:18432
	ds_read_b128 v[156:159], v207 offset:19456
	ds_read_b128 v[160:163], v207 offset:20480
	ds_read_b128 v[164:167], v207 offset:21504
	ds_read_b128 v[168:171], v207 offset:22528
	ds_read_b128 v[172:175], v207 offset:23552
	global_load_lds_dwordx4 v[218:219], off
	v_lshl_add_u64 v[220:221], s[44:45], 0, v[180:181]
	s_mov_b32 m0, s24
	s_nop 0
	global_load_lds_dwordx4 v[220:221], off
	s_barrier
	s_waitcnt lgkmcnt(0)
	v_mfma_f32_16x16x32_bf16 v[60:63], v[128:131], v[144:147], v[60:63]
	v_mfma_f32_16x16x32_bf16 v[56:59], v[136:139], v[144:147], v[56:59]
	v_mfma_f32_16x16x32_bf16 v[44:47], v[128:131], v[152:155], v[44:47]
	v_mfma_f32_16x16x32_bf16 v[40:43], v[136:139], v[152:155], v[40:43]
	v_mfma_f32_16x16x32_bf16 v[28:31], v[128:131], v[160:163], v[28:31]
	v_mfma_f32_16x16x32_bf16 v[24:27], v[136:139], v[160:163], v[24:27]
	v_mfma_f32_16x16x32_bf16 v[12:15], v[128:131], v[168:171], v[12:15]
	v_mfma_f32_16x16x32_bf16 v[8:11], v[136:139], v[168:171], v[8:11]
	v_mfma_f32_16x16x32_bf16 v[60:63], v[132:135], v[148:151], v[60:63]
	v_mfma_f32_16x16x32_bf16 v[56:59], v[140:143], v[148:151], v[56:59]
	v_mfma_f32_16x16x32_bf16 v[44:47], v[132:135], v[156:159], v[44:47]
	v_mfma_f32_16x16x32_bf16 v[40:43], v[140:143], v[156:159], v[40:43]
	v_mfma_f32_16x16x32_bf16 v[28:31], v[132:135], v[164:167], v[28:31]
	v_mfma_f32_16x16x32_bf16 v[24:27], v[140:143], v[164:167], v[24:27]
	v_mfma_f32_16x16x32_bf16 v[12:15], v[132:135], v[172:175], v[12:15]
	v_mfma_f32_16x16x32_bf16 v[8:11], v[140:143], v[172:175], v[8:11]
	s_barrier
	s_add_u32 s54, s42, 0x80000
	s_addc_u32 s55, s43, 0
	s_add_i32 s58, s48, s26
	s_mov_b32 m0, s58
	s_nop 0
	global_load_lds_dwordx4 v178, s[54:55]
	s_add_i32 m0, s58, 0x2000
	s_nop 0
	global_load_lds_dwordx4 v182, s[54:55]
	s_waitcnt vmcnt(6)
	s_barrier
; #define PG8_STAGE(bufoff, gbase, voff) do { _Pragma("unroll") for (int _i = 0; _i < 2; ++_i) \
;         __builtin_amdgcn_global_load_lds((const unsigned*)((const char*)(gbase) + (voff)[_i]), (LAS unsigned*)(lds + (bufoff) + ldsw + _i * 8192), 16, 0, 0); } while (0)
; #define PG8_LDA(dst, b, h) do { _Pragma("unroll") for (int m = 0; m < 4; ++m) _Pragma("unroll") for (int k = 0; k < 2; ++k) dst[m][k] = *(const LAS bf16x8*)(lds + PG8_SA(b, h) + aoff + m * 2048 + k * 1024); } while (0)
; #define PG8_LDB(dst, b, h) do { _Pragma("unroll") for (int n = 0; n < 2; ++n) _Pragma("unroll") for (int k = 0; k < 2; ++k) dst[n][k] = *(const LAS bf16x8*)(lds + PG8_SB(b, h) + boff + n * 2048 + k * 1024); } while (0)
; #define PG8_MMA(ai, bj, At, Bt) do { __builtin_amdgcn_s_setprio(1); _Pragma("unroll") for (int m = 0; m < 4; ++m) _Pragma("unroll") for (int n = 0; n < 2; ++n) _Pragma("unroll") for (int k = 0; k < 2; ++k) \
;         acc[ai][bj][m][n] = __builtin_amdgcn_mfma_f32_16x16x32_bf16(Bt[n][k], At[m][k], acc[ai][bj][m][n], 0, 0, 0); __builtin_amdgcn_s_setprio(0); } while (0)
; #define PG8_WAIT_V(n) asm volatile("s_waitcnt vmcnt(" #n ")" ::: "memory")
; #define PG8_WAIT_L(n) asm volatile("s_waitcnt lgkmcnt(" #n ")" ::: "memory")
; #define PG8_BAR __builtin_amdgcn_s_barrier()
; #define PG8_SCHED __builtin_amdgcn_sched_barrier(0)
; template <class Epi, bool KS0 = false>
; __device__ __forceinline__ void gemm_phase(const int WID, LAS unsigned char* lds, const Gemm g, const StaticOrder& S, const Epi& E) {
;     ...
;             PG8_WAIT_V(6); PG8_BAR; PG8_MMA(1, 1, At, B1); PG8_BAR;
;             PG8_LDB(B0, 1, 0); PG8_SCHED; PG8_LDA(At, 1, 0); PG8_STAGE(PG8_SA(0, 1), a2 + hstep, voffA);
;             PG8_WAIT_L(8); PG8_BAR; PG8_WAIT_L(0); PG8_MMA(0, 0, At, B0); PG8_BAR; PG8_SCHED;
;             PG8_LDB(B1, 1, 1); PG8_STAGE(PG8_SB(1, 0), b3, voffB);
;             PG8_BAR; PG8_WAIT_L(0); PG8_MMA(0, 1, At, B1); PG8_BAR;
;             PG8_LDA(At, 1, 1); PG8_STAGE(PG8_SA(1, 0), a3, voffA);
	v_mfma_f32_16x16x32_bf16 v[52:55], v[192:195], v[144:147], v[52:55]
	v_mfma_f32_16x16x32_bf16 v[48:51], v[200:203], v[144:147], v[48:51]
	v_mfma_f32_16x16x32_bf16 v[36:39], v[192:195], v[152:155], v[36:39]
	v_mfma_f32_16x16x32_bf16 v[32:35], v[200:203], v[152:155], v[32:35]
	v_mfma_f32_16x16x32_bf16 v[20:23], v[192:195], v[160:163], v[20:23]
	v_mfma_f32_16x16x32_bf16 v[16:19], v[200:203], v[160:163], v[16:19]
	v_mfma_f32_16x16x32_bf16 v[4:7], v[192:195], v[168:171], v[4:7]
	v_mfma_f32_16x16x32_bf16 v[0:3], v[200:203], v[168:171], v[0:3]
	v_mfma_f32_16x16x32_bf16 v[52:55], v[196:199], v[148:151], v[52:55]
	v_mfma_f32_16x16x32_bf16 v[48:51], v[210:213], v[148:151], v[48:51]
	v_mfma_f32_16x16x32_bf16 v[36:39], v[196:199], v[156:159], v[36:39]
	v_mfma_f32_16x16x32_bf16 v[32:35], v[210:213], v[156:159], v[32:35]
	v_mfma_f32_16x16x32_bf16 v[20:23], v[196:199], v[164:167], v[20:23]
	v_mfma_f32_16x16x32_bf16 v[16:19], v[210:213], v[164:167], v[16:19]
	v_mfma_f32_16x16x32_bf16 v[4:7], v[196:199], v[172:175], v[4:7]
	v_mfma_f32_16x16x32_bf16 v[0:3], v[210:213], v[172:175], v[0:3]
	s_add_i32 s54, 0, 0x18000
	v_add_u32_e32 v140, s54, v205
	s_barrier
	ds_read_b128 v[128:131], v140
	ds_read_b128 v[132:135], v140 offset:1024
	ds_read_b128 v[136:139], v140 offset:2048
	ds_read_b128 v[140:143], v140 offset:3072
	s_add_u32 s44, s44, 0x80000
	s_addc_u32 s45, s45, 0
	s_mov_b32 m0, s25
	v_lshl_add_u64 v[192:193], s[44:45], 0, v[176:177]
	ds_read_b128 v[144:147], v207 offset:32768
	ds_read_b128 v[148:151], v207 offset:33792
	ds_read_b128 v[152:155], v207 offset:34816
	ds_read_b128 v[156:159], v207 offset:35840
	ds_read_b128 v[160:163], v207 offset:36864
	ds_read_b128 v[164:167], v207 offset:37888
	ds_read_b128 v[168:171], v207 offset:38912
	ds_read_b128 v[172:175], v207 offset:39936
	global_load_lds_dwordx4 v[192:193], off
	s_mov_b32 m0, s28
	s_nop 0
	global_load_lds_dwordx4 v180, s[44:45]
	s_waitcnt lgkmcnt(8)
	s_barrier
	s_waitcnt lgkmcnt(0)
	v_mfma_f32_16x16x32_bf16 v[124:127], v[128:131], v[144:147], v[124:127]
	v_mfma_f32_16x16x32_bf16 v[120:123], v[136:139], v[144:147], v[120:123]
	v_mfma_f32_16x16x32_bf16 v[108:111], v[128:131], v[152:155], v[108:111]
	v_mfma_f32_16x16x32_bf16 v[104:107], v[136:139], v[152:155], v[104:107]
	v_mfma_f32_16x16x32_bf16 v[92:95], v[128:131], v[160:163], v[92:95]
	v_mfma_f32_16x16x32_bf16 v[88:91], v[136:139], v[160:163], v[88:91]
	v_mfma_f32_16x16x32_bf16 v[76:79], v[128:131], v[168:171], v[76:79]
	v_mfma_f32_16x16x32_bf16 v[72:75], v[136:139], v[168:171], v[72:75]
	v_mfma_f32_16x16x32_bf16 v[124:127], v[132:135], v[148:151], v[124:127]
	v_mfma_f32_16x16x32_bf16 v[120:123], v[140:143], v[148:151], v[120:123]
	v_mfma_f32_16x16x32_bf16 v[108:111], v[132:135], v[156:159], v[108:111]
	v_mfma_f32_16x16x32_bf16 v[104:107], v[140:143], v[156:159], v[104:107]
	v_mfma_f32_16x16x32_bf16 v[92:95], v[132:135], v[164:167], v[92:95]
	v_mfma_f32_16x16x32_bf16 v[88:91], v[140:143], v[164:167], v[88:91]
	v_mfma_f32_16x16x32_bf16 v[76:79], v[132:135], v[172:175], v[76:79]
	v_mfma_f32_16x16x32_bf16 v[72:75], v[140:143], v[172:175], v[72:75]
	s_barrier
	s_add_i32 s44, 0, 0x1c000
	s_add_i32 s45, s54, s26
	v_add_u32_e32 v210, s44, v205
	v_lshl_add_u64 v[214:215], v[214:215], 0, s[0:1]
	s_mov_b32 m0, s45
	ds_read_b128 v[192:195], v210
	ds_read_b128 v[196:199], v210 offset:1024
	ds_read_b128 v[200:203], v210 offset:2048
	ds_read_b128 v[210:213], v210 offset:3072
	global_load_lds_dwordx4 v[214:215], off
	v_lshl_add_u64 v[214:215], v[216:217], 0, s[0:1]
	s_add_i32 m0, s45, 0x2000
	s_nop 0
	global_load_lds_dwordx4 v[214:215], off
	s_barrier
	s_waitcnt lgkmcnt(0)
	v_mfma_f32_16x16x32_bf16 v[116:119], v[192:195], v[144:147], v[116:119]
	v_mfma_f32_16x16x32_bf16 v[112:115], v[200:203], v[144:147], v[112:115]
	v_mfma_f32_16x16x32_bf16 v[100:103], v[192:195], v[152:155], v[100:103]
	v_mfma_f32_16x16x32_bf16 v[96:99], v[200:203], v[152:155], v[96:99]
	v_mfma_f32_16x16x32_bf16 v[84:87], v[192:195], v[160:163], v[84:87]
	v_mfma_f32_16x16x32_bf16 v[80:83], v[200:203], v[160:163], v[80:83]
	v_mfma_f32_16x16x32_bf16 v[68:71], v[192:195], v[168:171], v[68:71]
	v_mfma_f32_16x16x32_bf16 v[64:67], v[200:203], v[168:171], v[64:67]
	v_mfma_f32_16x16x32_bf16 v[116:119], v[196:199], v[148:151], v[116:119]
	v_mfma_f32_16x16x32_bf16 v[112:115], v[210:213], v[148:151], v[112:115]
	v_mfma_f32_16x16x32_bf16 v[100:103], v[196:199], v[156:159], v[100:103]
	v_mfma_f32_16x16x32_bf16 v[96:99], v[210:213], v[156:159], v[96:99]
	v_mfma_f32_16x16x32_bf16 v[84:87], v[196:199], v[164:167], v[84:87]
	v_mfma_f32_16x16x32_bf16 v[80:83], v[210:213], v[164:167], v[80:83]
	v_mfma_f32_16x16x32_bf16 v[68:71], v[196:199], v[172:175], v[68:71]
	v_mfma_f32_16x16x32_bf16 v[64:67], v[210:213], v[172:175], v[64:67]
	s_mov_b32 m0, s29
	v_lshl_add_u64 v[214:215], v[218:219], 0, s[0:1]
	s_barrier
	ds_read_b128 v[144:147], v207 offset:49152
	ds_read_b128 v[148:151], v207 offset:50176
	ds_read_b128 v[152:155], v207 offset:51200
	ds_read_b128 v[156:159], v207 offset:52224
	ds_read_b128 v[160:163], v207 offset:53248
	ds_read_b128 v[164:167], v207 offset:54272
	ds_read_b128 v[168:171], v207 offset:55296
	ds_read_b128 v[172:175], v207 offset:56320
	global_load_lds_dwordx4 v[214:215], off
	v_lshl_add_u64 v[214:215], v[220:221], 0, s[0:1]
	s_mov_b32 m0, s34
	s_nop 0
	global_load_lds_dwordx4 v[214:215], off
	s_barrier
; #define PG8_STAGE(bufoff, gbase, voff) do { _Pragma("unroll") for (int _i = 0; _i < 2; ++_i) \
;         __builtin_amdgcn_global_load_lds((const unsigned*)((const char*)(gbase) + (voff)[_i]), (LAS unsigned*)(lds + (bufoff) + ldsw + _i * 8192), 16, 0, 0); } while (0)
; #define PG8_MMA(ai, bj, At, Bt) do { __builtin_amdgcn_s_setprio(1); _Pragma("unroll") for (int m = 0; m < 4; ++m) _Pragma("unroll") for (int n = 0; n < 2; ++n) _Pragma("unroll") for (int k = 0; k < 2; ++k) \
;         acc[ai][bj][m][n] = __builtin_amdgcn_mfma_f32_16x16x32_bf16(Bt[n][k], At[m][k], acc[ai][bj][m][n], 0, 0, 0); __builtin_amdgcn_s_setprio(0); } while (0)
; #define PG8_WAIT_V(n) asm volatile("s_waitcnt vmcnt(" #n ")" ::: "memory")
; #define PG8_WAIT_L(n) asm volatile("s_waitcnt lgkmcnt(" #n ")" ::: "memory")
; #define PG8_BAR __builtin_amdgcn_s_barrier()
; #define PG8_SCHED __builtin_amdgcn_sched_barrier(0)
; template <class Epi, bool KS0 = false>
; __device__ __forceinline__ void gemm_phase(const int WID, LAS unsigned char* lds, const Gemm g, const StaticOrder& S, const Epi& E) {
;     ...
;             PG8_BAR; PG8_WAIT_L(0); PG8_MMA(1, 0, At, B0); PG8_BAR; PG8_SCHED;
;             PG8_STAGE(PG8_SB(1, 1), b3 + hstep, voffB);
;             PG8_WAIT_V(6); PG8_BAR; PG8_MMA(1, 1, At, B1); PG8_BAR;
;         }
	s_waitcnt lgkmcnt(0)
	v_mfma_f32_16x16x32_bf16 v[60:63], v[128:131], v[144:147], v[60:63]
	v_mfma_f32_16x16x32_bf16 v[56:59], v[136:139], v[144:147], v[56:59]
	v_mfma_f32_16x16x32_bf16 v[44:47], v[128:131], v[152:155], v[44:47]
	v_mfma_f32_16x16x32_bf16 v[40:43], v[136:139], v[152:155], v[40:43]
	v_mfma_f32_16x16x32_bf16 v[28:31], v[128:131], v[160:163], v[28:31]
	v_mfma_f32_16x16x32_bf16 v[24:27], v[136:139], v[160:163], v[24:27]
	v_mfma_f32_16x16x32_bf16 v[12:15], v[128:131], v[168:171], v[12:15]
	v_mfma_f32_16x16x32_bf16 v[8:11], v[136:139], v[168:171], v[8:11]
	v_mfma_f32_16x16x32_bf16 v[60:63], v[132:135], v[148:151], v[60:63]
	v_mfma_f32_16x16x32_bf16 v[56:59], v[140:143], v[148:151], v[56:59]
	v_mfma_f32_16x16x32_bf16 v[44:47], v[132:135], v[156:159], v[44:47]
	v_mfma_f32_16x16x32_bf16 v[40:43], v[140:143], v[156:159], v[40:43]
	v_mfma_f32_16x16x32_bf16 v[28:31], v[132:135], v[164:167], v[28:31]
	v_mfma_f32_16x16x32_bf16 v[24:27], v[140:143], v[164:167], v[24:27]
	v_mfma_f32_16x16x32_bf16 v[12:15], v[132:135], v[172:175], v[12:15]
	v_mfma_f32_16x16x32_bf16 v[8:11], v[140:143], v[172:175], v[8:11]
	s_barrier
	s_add_u32 s42, s42, 0x80080
	s_addc_u32 s43, s43, 0
	s_add_i32 s44, s44, s26
	s_mov_b32 m0, s44
	s_nop 0
	global_load_lds_dwordx4 v178, s[42:43]
	s_add_i32 m0, s44, 0x2000
	s_nop 0
	global_load_lds_dwordx4 v182, s[42:43]
	s_waitcnt vmcnt(6)
	s_barrier
	v_mfma_f32_16x16x32_bf16 v[52:55], v[192:195], v[144:147], v[52:55]
	v_mfma_f32_16x16x32_bf16 v[48:51], v[200:203], v[144:147], v[48:51]
	v_mfma_f32_16x16x32_bf16 v[36:39], v[192:195], v[152:155], v[36:39]
	v_mfma_f32_16x16x32_bf16 v[32:35], v[200:203], v[152:155], v[32:35]
	v_mfma_f32_16x16x32_bf16 v[20:23], v[192:195], v[160:163], v[20:23]
	v_mfma_f32_16x16x32_bf16 v[16:19], v[200:203], v[160:163], v[16:19]
	v_mfma_f32_16x16x32_bf16 v[4:7], v[192:195], v[168:171], v[4:7]
	v_mfma_f32_16x16x32_bf16 v[0:3], v[200:203], v[168:171], v[0:3]
	v_mfma_f32_16x16x32_bf16 v[52:55], v[196:199], v[148:151], v[52:55]
	v_mfma_f32_16x16x32_bf16 v[48:51], v[210:213], v[148:151], v[48:51]
	v_mfma_f32_16x16x32_bf16 v[36:39], v[196:199], v[156:159], v[36:39]
	v_mfma_f32_16x16x32_bf16 v[32:35], v[210:213], v[156:159], v[32:35]
	v_mfma_f32_16x16x32_bf16 v[20:23], v[196:199], v[164:167], v[20:23]
	v_mfma_f32_16x16x32_bf16 v[16:19], v[210:213], v[164:167], v[16:19]
	v_mfma_f32_16x16x32_bf16 v[4:7], v[196:199], v[172:175], v[4:7]
	v_mfma_f32_16x16x32_bf16 v[0:3], v[210:213], v[172:175], v[0:3]
	s_add_i32 s53, s53, 2
	s_add_u32 s20, s20, 0x100
	s_addc_u32 s21, s21, 0
	s_add_u32 s51, s51, 0x100
	s_addc_u32 s52, s52, 0
	s_cmp_gt_u32 s53, 29
	s_barrier
	s_cbranch_scc0 .LBB0_670
; __device__ __forceinline__ unsigned cvt_pk_bf16(float lo, float hi) { unsigned r; asm volatile("v_cvt_pk_bf16_f32 %0, %1, %2" : "=v"(r) : "v"(lo), "v"(hi)); return r; }
; __device__ __forceinline__ float bflo(unsigned w) { return __uint_as_float(w << 16); }
; __device__ __forceinline__ float bfhi(unsigned w) { return __uint_as_float(w & 0xffff0000u); }
;     __device__ __forceinline__ void operator()(f32x4 (&acc)[2][2][4][2], const Unit& u, int wr, int wc, int fr, int fq) const {
;         const int row0 = u.pm * BM + wr * 64 + fr, col0 = u.pn * BM + wc * 32 + 8 * fq;
; #pragma unroll
;         for (int ai = 0; ai < 2; ++ai) {
;             f32x4 r[4][2][2];
; #pragma unroll
;             for (int m = 0; m < 4; ++m)
; #pragma unroll
;                 for (int bj = 0; bj < 2; ++bj) { const size_t o = (size_t)(row0 + ai * HALF + m * 16) * DM + col0 + bj * HALF;
;                     if (RB) { const u32x4 w = *(const u32x4*)((const bf16_t*)res + o); r[m][bj][0] = (f32x4){bflo(w.x), bfhi(w.x), bflo(w.y), bfhi(w.y)}; r[m][bj][1] = (f32x4){bflo(w.z), bfhi(w.z), bflo(w.w), bfhi(w.w)}; }
;                     else { r[m][bj][0] = __builtin_nontemporal_load((const f32x4*)((const float*)res + o)); r[m][bj][1] = __builtin_nontemporal_load((const f32x4*)((const float*)res + o + 4)); } }
; #pragma unroll
;             for (int m = 0; m < 4; ++m) { const int row = row0 + ai * HALF + m * 16; const size_t off = (size_t)row * DM + col0; float s = 0.f;
; #pragma unroll
;                 for (int bj = 0; bj < 2; ++bj) { const f32x4 v0 = acc[ai][bj][m][0] + r[m][bj][0], v1 = acc[ai][bj][m][1] + r[m][bj][1];
;                     u32x4 w; w.x = cvt_pk_bf16(v0[0], v0[1]); w.y = cvt_pk_bf16(v0[2], v0[3]); w.z = cvt_pk_bf16(v1[0], v1[1]); w.w = cvt_pk_bf16(v1[2], v1[3]);
;                     *(u32x4*)(outb + off + bj * HALF) = w;
;                     s += ((v0[0] * v0[0] + v0[1] * v0[1]) + (v0[2] * v0[2] + v0[3] * v0[3])) + ((v1[0] * v1[0] + v1[1] * v1[1]) + (v1[2] * v1[2] + v1[3] * v1[3])); }
;                 s += __shfl_xor(s, 16); s += __shfl_xor(s, 32);
;                 if (fq == 0) ssq[(size_t)row * 32 + u.pn * 4 + wc] = s; }
;             asm volatile("" ::: "memory"); }
;     }
	v_mbcnt_lo_u32_b32 v128, -1, 0
	v_mbcnt_hi_u32_b32 v128, -1, v128
	s_lshl_b32 s9, s18, 8
	v_ashrrev_i32_e32 v210, 4, v128
	v_and_b32_e32 v128, 15, v128
	s_add_i32 s9, s9, s22
	v_readlane_b32 s11, v254, 19
	v_add_u32_e32 v194, s9, v128
	s_lshl_b32 s9, s2, 8
	s_or_b32 s9, s9, s11
	v_lshl_add_u32 v192, v210, 3, s9
	v_ashrrev_i32_e32 v193, 31, v192
	v_ashrrev_i32_e32 v195, 31, v194
	v_lshl_add_u64 v[196:197], v[192:193], 2, s[56:57]
	v_lshlrev_b64 v[128:129], 13, v[194:195]
	v_lshl_add_u64 v[128:129], v[196:197], 0, v[128:129]
	global_load_dwordx4 v[212:215], v[128:129], off nt
	global_load_dwordx4 v[216:219], v[128:129], off offset:16 nt
	global_load_dwordx4 v[220:223], v[128:129], off offset:512 nt
	global_load_dwordx4 v[224:227], v[128:129], off offset:528 nt
	v_add_u32_e32 v202, 16, v194
	v_add_u32_e32 v200, 32, v194
	v_add_u32_e32 v198, 48, v194
	v_ashrrev_i32_e32 v203, 31, v202
	v_ashrrev_i32_e32 v201, 31, v200
	v_ashrrev_i32_e32 v199, 31, v198
	v_lshlrev_b64 v[128:129], 13, v[202:203]
	v_lshlrev_b64 v[130:131], 13, v[200:201]
	v_lshlrev_b64 v[132:133], 13, v[198:199]
	v_lshl_add_u64 v[128:129], v[196:197], 0, v[128:129]
	v_lshl_add_u64 v[130:131], v[196:197], 0, v[130:131]
	v_lshl_add_u64 v[132:133], v[196:197], 0, v[132:133]
	global_load_dwordx4 v[168:171], v[128:129], off offset:16 nt
	global_load_dwordx4 v[172:175], v[128:129], off nt
	global_load_dwordx4 v[160:163], v[128:129], off offset:528 nt
	global_load_dwordx4 v[164:167], v[128:129], off offset:512 nt
	global_load_dwordx4 v[152:155], v[130:131], off offset:16 nt
	global_load_dwordx4 v[156:159], v[130:131], off nt
	global_load_dwordx4 v[144:147], v[130:131], off offset:528 nt
	global_load_dwordx4 v[148:151], v[130:131], off offset:512 nt
	global_load_dwordx4 v[136:139], v[132:133], off offset:16 nt
	global_load_dwordx4 v[140:143], v[132:133], off nt
	s_nop 0
	global_load_dwordx4 v[128:131], v[132:133], off offset:528 nt
	s_nop 0
	global_load_dwordx4 v[132:135], v[132:133], off offset:512 nt
	v_and_b32_e32 v228, 64, v209
	v_xor_b32_e32 v211, 16, v209
	v_add_u32_e32 v228, 64, v228
	v_xor_b32_e32 v229, 32, v209
	v_cmp_lt_i32_e32 vcc, v211, v228
	s_lshl_b32 s18, s2, 2
	s_ashr_i32 s19, s18, 31
	v_cndmask_b32_e32 v211, v209, v211, vcc
	v_cmp_lt_i32_e32 vcc, v229, v228
	s_waitcnt vmcnt(0)
	v_pk_add_f32 v[126:127], v[126:127], v[214:215]
	v_pk_add_f32 v[124:125], v[124:125], v[212:213]
	v_pk_add_f32 v[122:123], v[122:123], v[218:219]
	v_pk_add_f32 v[120:121], v[120:121], v[216:217]
	v_pk_add_f32 v[118:119], v[118:119], v[222:223]
	v_pk_add_f32 v[116:117], v[116:117], v[220:221]
	v_pk_add_f32 v[212:213], v[114:115], v[226:227]
	v_pk_add_f32 v[214:215], v[112:113], v[224:225]
	v_cndmask_b32_e32 v230, v209, v229, vcc
	v_cmp_eq_u32_e32 vcc, 0, v210
	v_lshlrev_b32_e32 v210, 2, v211
	v_cvt_pk_bf16_f32 v112, v124, v125
	v_cvt_pk_bf16_f32 v113, v126, v127
	v_mul_f32_e32 v114, v125, v125
	v_mul_f32_e32 v115, v127, v127
	v_mul_f32_e32 v125, v121, v121
	v_mul_f32_e32 v127, v123, v123
	v_mul_f32_e32 v211, v117, v117
	v_mul_f32_e32 v216, v119, v119
	v_mul_f32_e32 v217, v215, v215
	v_mul_f32_e32 v218, v213, v213
	v_fmac_f32_e32 v114, v124, v124
	v_fmac_f32_e32 v115, v126, v126
	v_fmac_f32_e32 v125, v120, v120
	v_fmac_f32_e32 v127, v122, v122
	v_fmac_f32_e32 v211, v116, v116
	v_fmac_f32_e32 v216, v118, v118
	v_fmac_f32_e32 v217, v214, v214
	v_fmac_f32_e32 v218, v212, v212
	v_add_f32_e32 v114, v114, v115
	v_add_f32_e32 v115, v125, v127
	v_add_f32_e32 v124, v211, v216
	v_add_f32_e32 v125, v217, v218
	v_add_f32_e32 v114, v114, v115
	v_add_f32_e32 v115, v124, v125
	v_add_f32_e32 v124, v114, v115
	ds_bpermute_b32 v125, v210, v124
	v_lshlrev_b64 v[228:229], 12, v[194:195]
	v_lshl_add_u64 v[228:229], s[6:7], 0, v[228:229]
	v_lshl_add_u64 v[228:229], v[192:193], 1, v[228:229]
	v_cvt_pk_bf16_f32 v114, v120, v121
	v_cvt_pk_bf16_f32 v115, v122, v123
	global_store_dwordx4 v[228:229], v[112:115], off
	v_lshlrev_b32_e32 v120, 2, v230
	s_waitcnt lgkmcnt(0)
	v_add_f32_e32 v112, v124, v125
	ds_bpermute_b32 v113, v120, v112
	v_cvt_pk_bf16_f32 v114, v116, v117
	v_cvt_pk_bf16_f32 v115, v118, v119
	v_cvt_pk_bf16_f32 v116, v214, v215
	v_cvt_pk_bf16_f32 v117, v212, v213
	global_store_dwordx4 v[228:229], v[114:117], off offset:256
	s_and_saveexec_b64 s[20:21], vcc
	s_cbranch_execz .LBB0_673
	v_lshlrev_b64 v[114:115], 7, v[194:195]
	v_lshl_add_u64 v[114:115], s[16:17], 0, v[114:115]
	v_lshl_add_u64 v[114:115], s[18:19], 2, v[114:115]
	s_lshl_b32 s2, s27, 2
	v_lshl_add_u64 v[114:115], v[114:115], 0, s[2:3]
	s_waitcnt lgkmcnt(0)
	v_add_f32_e32 v112, v112, v113
	global_store_dword v[114:115], v112, off

; #define PG8_STAGE(bufoff, gbase, voff) do { _Pragma("unroll") for (int _i = 0; _i < 2; ++_i) \
;         __builtin_amdgcn_global_load_lds((const unsigned*)((const char*)(gbase) + (voff)[_i]), (LAS unsigned*)(lds + (bufoff) + ldsw + _i * 8192), 16, 0, 0); } while (0)
; #define PG8_LDA(dst, b, h) do { _Pragma("unroll") for (int m = 0; m < 4; ++m) _Pragma("unroll") for (int k = 0; k < 2; ++k) dst[m][k] = *(const LAS bf16x8*)(lds + PG8_SA(b, h) + aoff + m * 2048 + k * 1024); } while (0)
; #define PG8_LDB(dst, b, h) do { _Pragma("unroll") for (int n = 0; n < 2; ++n) _Pragma("unroll") for (int k = 0; k < 2; ++k) dst[n][k] = *(const LAS bf16x8*)(lds + PG8_SB(b, h) + boff + n * 2048 + k * 1024); } while (0)
; #define PG8_MMA(ai, bj, At, Bt) do { __builtin_amdgcn_s_setprio(1); _Pragma("unroll") for (int m = 0; m < 4; ++m) _Pragma("unroll") for (int n = 0; n < 2; ++n) _Pragma("unroll") for (int k = 0; k < 2; ++k) \
;         acc[ai][bj][m][n] = __builtin_amdgcn_mfma_f32_16x16x32_bf16(Bt[n][k], At[m][k], acc[ai][bj][m][n], 0, 0, 0); __builtin_amdgcn_s_setprio(0); } while (0)
; #define PG8_BAR __builtin_amdgcn_s_barrier()
; template <class Epi, bool KS0 = false>
; __device__ __forceinline__ void gemm_phase(const int WID, LAS unsigned char* lds, const Gemm g, const StaticOrder& S, const Epi& E) {
;     ...
;         const char* nA = has_next ? (const char*)g.A + (size_t)nxt.pm * tstep : cA; const char* nB = has_next ? (const char*)g.Bt + (size_t)nxt.pn * tstep : cB;
;         for (int t = 0; t < nt; t += 2) {
;             const bool last = (t == nt - 2);
;             const char* a1 = cA + (size_t)(t + 1) * kstep;
;             const char* a2 = last ? nA : cA + (size_t)(t + 2) * kstep; const char* b2 = last ? nB : cB + (size_t)(t + 2) * kstep;
;             const char* a3 = a2 + kstep; const char* b3 = b2 + kstep;
;             PG8_LDB(B0, 0, 0); PG8_SCHED; PG8_LDA(At, 0, 0); PG8_STAGE(PG8_SA(1, 1), a1 + hstep, voffA);
;             PG8_WAIT_L(8); PG8_BAR; PG8_WAIT_L(0); PG8_MMA(0, 0, At, B0); PG8_BAR; PG8_SCHED;
;             PG8_LDB(B1, 0, 1); PG8_STAGE(PG8_SB(0, 0), b2, voffB);
;             PG8_BAR; PG8_WAIT_L(0); PG8_MMA(0, 1, At, B1); PG8_BAR;
;             PG8_LDA(At, 0, 1); PG8_STAGE(PG8_SA(0, 0), a2, voffA);
;             PG8_BAR; PG8_WAIT_L(0); PG8_MMA(1, 0, At, B0); PG8_BAR; PG8_SCHED;
;             PG8_STAGE(PG8_SB(0, 1), b2 + hstep, voffB);
.LBB0_703:
	s_add_u32 s43, s20, s42
	s_addc_u32 s53, s21, 0
	s_add_u32 s48, s43, 0x100
	s_addc_u32 s49, s53, 0
	s_and_b64 s[44:45], s[34:35], exec
	s_cselect_b32 s49, s11, s49
	s_cselect_b32 s48, s63, s48
	s_add_u32 s42, s18, s42
	s_addc_u32 s44, s19, 0
	s_add_u32 s42, s42, 0x100
	s_addc_u32 s44, s44, 0
	s_and_b64 s[34:35], s[34:35], exec
	s_cselect_b32 s51, s9, s44
	s_cselect_b32 s50, s64, s42
	s_add_u32 s52, s43, 0x10080
	s_addc_u32 s53, s53, 0
	s_add_i32 s75, s59, s26
	s_add_i32 m0, s29, 0xc000
	s_add_i32 s80, s29, 0xe000
	s_add_i32 s74, s75, 0x2000
	s_add_u32 s44, s50, 0x10000
	s_addc_u32 s45, s51, 0
	s_add_i32 s73, s60, s26
	ds_read_b128 v[146:149], v143
	ds_read_b128 v[150:153], v143 offset:1024
	ds_read_b128 v[154:157], v143 offset:2048
	ds_read_b128 v[158:161], v143 offset:3072
	s_add_i32 s71, s73, 0x2000
	s_add_i32 s70, 0, 0x18000
	s_add_u32 s42, s48, 0x10000
	s_addc_u32 s43, s49, 0
	s_add_i32 s69, s70, s26
	s_add_i32 s68, 0, 0x1c000
	s_add_i32 s67, s69, 0x2000
	s_add_u32 s34, s50, 0x10080
	s_addc_u32 s35, s51, 0
	s_add_i32 s66, s68, s26
	s_add_i32 s65, s66, 0x2000
	v_lshl_add_u64 v[140:141], s[52:53], 0, v[134:135]
	ds_read_b128 v[162:165], v144
	ds_read_b128 v[166:169], v144 offset:1024
	ds_read_b128 v[170:173], v144 offset:2048
	ds_read_b128 v[174:177], v144 offset:3072
	ds_read_b128 v[178:181], v144 offset:4096
	ds_read_b128 v[182:185], v144 offset:5120
	ds_read_b128 v[186:189], v144 offset:6144
	ds_read_b128 v[190:193], v144 offset:7168
	global_load_lds_dwordx4 v[140:141], off
	s_mov_b32 m0, s80
	s_nop 0
	global_load_lds_dwordx4 v130, s[52:53]
	s_waitcnt lgkmcnt(8)
	s_barrier
	s_waitcnt lgkmcnt(0)
	v_mfma_f32_16x16x32_bf16 v[124:127], v[146:149], v[162:165], v[124:127]
	v_mfma_f32_16x16x32_bf16 v[120:123], v[154:157], v[162:165], v[120:123]
	v_mfma_f32_16x16x32_bf16 v[112:115], v[146:149], v[170:173], v[112:115]
	v_mfma_f32_16x16x32_bf16 v[104:107], v[154:157], v[170:173], v[104:107]
	v_mfma_f32_16x16x32_bf16 v[100:103], v[146:149], v[178:181], v[100:103]
	v_mfma_f32_16x16x32_bf16 v[92:95], v[154:157], v[178:181], v[92:95]
	v_mfma_f32_16x16x32_bf16 v[84:87], v[146:149], v[186:189], v[84:87]
	v_mfma_f32_16x16x32_bf16 v[76:79], v[154:157], v[186:189], v[76:79]
	v_mfma_f32_16x16x32_bf16 v[124:127], v[150:153], v[166:169], v[124:127]
	v_mfma_f32_16x16x32_bf16 v[120:123], v[158:161], v[166:169], v[120:123]
	v_mfma_f32_16x16x32_bf16 v[112:115], v[150:153], v[174:177], v[112:115]
	v_mfma_f32_16x16x32_bf16 v[104:107], v[158:161], v[174:177], v[104:107]
	v_mfma_f32_16x16x32_bf16 v[100:103], v[150:153], v[182:185], v[100:103]
	v_mfma_f32_16x16x32_bf16 v[92:95], v[158:161], v[182:185], v[92:95]
	v_mfma_f32_16x16x32_bf16 v[84:87], v[150:153], v[190:193], v[84:87]
	v_mfma_f32_16x16x32_bf16 v[76:79], v[158:161], v[190:193], v[76:79]
	s_barrier
	s_mov_b32 m0, s75
	v_lshl_add_u64 v[140:141], s[50:51], 0, v[132:133]
	ds_read_b128 v[194:197], v145
	ds_read_b128 v[198:201], v145 offset:1024
	ds_read_b128 v[210:213], v145 offset:2048
	ds_read_b128 v[214:217], v145 offset:3072
	global_load_lds_dwordx4 v[140:141], off
	v_lshl_add_u64 v[202:203], s[50:51], 0, v[128:129]
	s_mov_b32 m0, s74
	s_nop 0
	global_load_lds_dwordx4 v[202:203], off
	s_barrier
	s_waitcnt lgkmcnt(0)
	v_mfma_f32_16x16x32_bf16 v[116:119], v[194:197], v[162:165], v[116:119]
	v_mfma_f32_16x16x32_bf16 v[108:111], v[210:213], v[162:165], v[108:111]
	v_mfma_f32_16x16x32_bf16 v[96:99], v[194:197], v[170:173], v[96:99]
	v_mfma_f32_16x16x32_bf16 v[88:91], v[210:213], v[170:173], v[88:91]
	v_mfma_f32_16x16x32_bf16 v[80:83], v[194:197], v[178:181], v[80:83]
	v_mfma_f32_16x16x32_bf16 v[72:75], v[210:213], v[178:181], v[72:75]
	v_mfma_f32_16x16x32_bf16 v[68:71], v[194:197], v[186:189], v[68:71]
	v_mfma_f32_16x16x32_bf16 v[64:67], v[210:213], v[186:189], v[64:67]
	v_mfma_f32_16x16x32_bf16 v[116:119], v[198:201], v[166:169], v[116:119]
	v_mfma_f32_16x16x32_bf16 v[108:111], v[214:217], v[166:169], v[108:111]
	v_mfma_f32_16x16x32_bf16 v[96:99], v[198:201], v[174:177], v[96:99]
	v_mfma_f32_16x16x32_bf16 v[88:91], v[214:217], v[174:177], v[88:91]
	v_mfma_f32_16x16x32_bf16 v[80:83], v[198:201], v[182:185], v[80:83]
	v_mfma_f32_16x16x32_bf16 v[72:75], v[214:217], v[182:185], v[72:75]
	v_mfma_f32_16x16x32_bf16 v[68:71], v[198:201], v[190:193], v[68:71]
	v_mfma_f32_16x16x32_bf16 v[64:67], v[214:217], v[190:193], v[64:67]
	s_mov_b32 m0, s29
	v_lshl_add_u64 v[206:207], s[48:49], 0, v[134:135]
	s_barrier
	ds_read_b128 v[162:165], v144 offset:16384
	ds_read_b128 v[166:169], v144 offset:17408
	ds_read_b128 v[170:173], v144 offset:18432
	ds_read_b128 v[174:177], v144 offset:19456
	ds_read_b128 v[178:181], v144 offset:20480
	ds_read_b128 v[182:185], v144 offset:21504
	ds_read_b128 v[186:189], v144 offset:22528
	ds_read_b128 v[190:193], v144 offset:23552
	global_load_lds_dwordx4 v[206:207], off
	v_lshl_add_u64 v[218:219], s[48:49], 0, v[130:131]
	s_mov_b32 m0, s54
	s_nop 0
	global_load_lds_dwordx4 v[218:219], off
	s_barrier
	s_waitcnt lgkmcnt(0)
	v_mfma_f32_16x16x32_bf16 v[60:63], v[146:149], v[162:165], v[60:63]
	v_mfma_f32_16x16x32_bf16 v[56:59], v[154:157], v[162:165], v[56:59]
	v_mfma_f32_16x16x32_bf16 v[52:55], v[146:149], v[170:173], v[52:55]
	v_mfma_f32_16x16x32_bf16 v[44:47], v[154:157], v[170:173], v[44:47]
	v_mfma_f32_16x16x32_bf16 v[36:39], v[146:149], v[178:181], v[36:39]
	v_mfma_f32_16x16x32_bf16 v[28:31], v[154:157], v[178:181], v[28:31]
	v_mfma_f32_16x16x32_bf16 v[20:23], v[146:149], v[186:189], v[20:23]
	v_mfma_f32_16x16x32_bf16 v[12:15], v[154:157], v[186:189], v[12:15]
	v_mfma_f32_16x16x32_bf16 v[60:63], v[150:153], v[166:169], v[60:63]
	v_mfma_f32_16x16x32_bf16 v[56:59], v[158:161], v[166:169], v[56:59]
	v_mfma_f32_16x16x32_bf16 v[52:55], v[150:153], v[174:177], v[52:55]
	v_mfma_f32_16x16x32_bf16 v[44:47], v[158:161], v[174:177], v[44:47]
	v_mfma_f32_16x16x32_bf16 v[36:39], v[150:153], v[182:185], v[36:39]
	v_mfma_f32_16x16x32_bf16 v[28:31], v[158:161], v[182:185], v[28:31]
	v_mfma_f32_16x16x32_bf16 v[20:23], v[150:153], v[190:193], v[20:23]
	v_mfma_f32_16x16x32_bf16 v[12:15], v[158:161], v[190:193], v[12:15]
	s_barrier
; #define PG8_STAGE(bufoff, gbase, voff) do { _Pragma("unroll") for (int _i = 0; _i < 2; ++_i) \
;         __builtin_amdgcn_global_load_lds((const unsigned*)((const char*)(gbase) + (voff)[_i]), (LAS unsigned*)(lds + (bufoff) + ldsw + _i * 8192), 16, 0, 0); } while (0)
; #define PG8_LDA(dst, b, h) do { _Pragma("unroll") for (int m = 0; m < 4; ++m) _Pragma("unroll") for (int k = 0; k < 2; ++k) dst[m][k] = *(const LAS bf16x8*)(lds + PG8_SA(b, h) + aoff + m * 2048 + k * 1024); } while (0)
; #define PG8_LDB(dst, b, h) do { _Pragma("unroll") for (int n = 0; n < 2; ++n) _Pragma("unroll") for (int k = 0; k < 2; ++k) dst[n][k] = *(const LAS bf16x8*)(lds + PG8_SB(b, h) + boff + n * 2048 + k * 1024); } while (0)
; #define PG8_MMA(ai, bj, At, Bt) do { __builtin_amdgcn_s_setprio(1); _Pragma("unroll") for (int m = 0; m < 4; ++m) _Pragma("unroll") for (int n = 0; n < 2; ++n) _Pragma("unroll") for (int k = 0; k < 2; ++k) \
;         acc[ai][bj][m][n] = __builtin_amdgcn_mfma_f32_16x16x32_bf16(Bt[n][k], At[m][k], acc[ai][bj][m][n], 0, 0, 0); __builtin_amdgcn_s_setprio(0); } while (0)
; #define PG8_WAIT_V(n) asm volatile("s_waitcnt vmcnt(" #n ")" ::: "memory")
; #define PG8_WAIT_L(n) asm volatile("s_waitcnt lgkmcnt(" #n ")" ::: "memory")
; #define PG8_BAR __builtin_amdgcn_s_barrier()
; #define PG8_SCHED __builtin_amdgcn_sched_barrier(0)
; template <class Epi, bool KS0 = false>
; __device__ __forceinline__ void gemm_phase(const int WID, LAS unsigned char* lds, const Gemm g, const StaticOrder& S, const Epi& E) {
;     ...
;             PG8_STAGE(PG8_SB(0, 1), b2 + hstep, voffB);
;             PG8_WAIT_V(6); PG8_BAR; PG8_MMA(1, 1, At, B1); PG8_BAR;
;             PG8_LDB(B0, 1, 0); PG8_SCHED; PG8_LDA(At, 1, 0); PG8_STAGE(PG8_SA(0, 1), a2 + hstep, voffA);
;             PG8_WAIT_L(8); PG8_BAR; PG8_WAIT_L(0); PG8_MMA(0, 0, At, B0); PG8_BAR; PG8_SCHED;
;             PG8_LDB(B1, 1, 1); PG8_STAGE(PG8_SB(1, 0), b3, voffB);
	s_mov_b32 m0, s73
	global_load_lds_dwordx4 v132, s[44:45]
	s_mov_b32 m0, s71
	s_nop 0
	global_load_lds_dwordx4 v128, s[44:45]
	s_waitcnt vmcnt(6)
	s_barrier
	v_mfma_f32_16x16x32_bf16 v[48:51], v[194:197], v[162:165], v[48:51]
	v_mfma_f32_16x16x32_bf16 v[40:43], v[210:213], v[162:165], v[40:43]
	v_mfma_f32_16x16x32_bf16 v[32:35], v[194:197], v[170:173], v[32:35]
	v_mfma_f32_16x16x32_bf16 v[24:27], v[210:213], v[170:173], v[24:27]
	v_mfma_f32_16x16x32_bf16 v[16:19], v[194:197], v[178:181], v[16:19]
	v_mfma_f32_16x16x32_bf16 v[8:11], v[210:213], v[178:181], v[8:11]
	v_mfma_f32_16x16x32_bf16 v[4:7], v[194:197], v[186:189], v[4:7]
	v_mfma_f32_16x16x32_bf16 v[0:3], v[210:213], v[186:189], v[0:3]
	v_mfma_f32_16x16x32_bf16 v[48:51], v[198:201], v[166:169], v[48:51]
	v_mfma_f32_16x16x32_bf16 v[40:43], v[214:217], v[166:169], v[40:43]
	v_mfma_f32_16x16x32_bf16 v[32:35], v[198:201], v[174:177], v[32:35]
	v_mfma_f32_16x16x32_bf16 v[24:27], v[214:217], v[174:177], v[24:27]
	v_mfma_f32_16x16x32_bf16 v[16:19], v[198:201], v[182:185], v[16:19]
	v_mfma_f32_16x16x32_bf16 v[8:11], v[214:217], v[182:185], v[8:11]
	v_mfma_f32_16x16x32_bf16 v[4:7], v[198:201], v[190:193], v[4:7]
	v_mfma_f32_16x16x32_bf16 v[0:3], v[214:217], v[190:193], v[0:3]
	v_add_u32_e32 v158, s70, v142
	s_barrier
	ds_read_b128 v[146:149], v158
	ds_read_b128 v[150:153], v158 offset:1024
	ds_read_b128 v[154:157], v158 offset:2048
	ds_read_b128 v[158:161], v158 offset:3072
	s_mov_b32 m0, s55
	v_lshl_add_u64 v[194:195], s[42:43], 0, v[134:135]
	ds_read_b128 v[162:165], v144 offset:32768
	ds_read_b128 v[166:169], v144 offset:33792
	ds_read_b128 v[170:173], v144 offset:34816
	ds_read_b128 v[174:177], v144 offset:35840
	ds_read_b128 v[178:181], v144 offset:36864
	ds_read_b128 v[182:185], v144 offset:37888
	ds_read_b128 v[186:189], v144 offset:38912
	ds_read_b128 v[190:193], v144 offset:39936
	global_load_lds_dwordx4 v[194:195], off
	s_mov_b32 m0, s56
	s_nop 0
	global_load_lds_dwordx4 v130, s[42:43]
	s_waitcnt lgkmcnt(8)
	s_barrier
	s_waitcnt lgkmcnt(0)
	v_mfma_f32_16x16x32_bf16 v[124:127], v[146:149], v[162:165], v[124:127]
	v_mfma_f32_16x16x32_bf16 v[120:123], v[154:157], v[162:165], v[120:123]
	v_mfma_f32_16x16x32_bf16 v[112:115], v[146:149], v[170:173], v[112:115]
	v_mfma_f32_16x16x32_bf16 v[104:107], v[154:157], v[170:173], v[104:107]
	v_mfma_f32_16x16x32_bf16 v[100:103], v[146:149], v[178:181], v[100:103]
	v_mfma_f32_16x16x32_bf16 v[92:95], v[154:157], v[178:181], v[92:95]
	v_mfma_f32_16x16x32_bf16 v[84:87], v[146:149], v[186:189], v[84:87]
	v_mfma_f32_16x16x32_bf16 v[76:79], v[154:157], v[186:189], v[76:79]
	v_mfma_f32_16x16x32_bf16 v[124:127], v[150:153], v[166:169], v[124:127]
	v_mfma_f32_16x16x32_bf16 v[120:123], v[158:161], v[166:169], v[120:123]
	v_mfma_f32_16x16x32_bf16 v[112:115], v[150:153], v[174:177], v[112:115]
	v_mfma_f32_16x16x32_bf16 v[104:107], v[158:161], v[174:177], v[104:107]
	v_mfma_f32_16x16x32_bf16 v[100:103], v[150:153], v[182:185], v[100:103]
	v_mfma_f32_16x16x32_bf16 v[92:95], v[158:161], v[182:185], v[92:95]
	v_mfma_f32_16x16x32_bf16 v[84:87], v[150:153], v[190:193], v[84:87]
	v_mfma_f32_16x16x32_bf16 v[76:79], v[158:161], v[190:193], v[76:79]
	s_barrier
	s_mov_b32 m0, s69
	v_add_u32_e32 v205, s68, v142
	v_lshl_add_u64 v[140:141], v[140:141], 0, s[2:3]
	ds_read_b128 v[194:197], v205
	ds_read_b128 v[198:201], v205 offset:1024
	ds_read_b128 v[210:213], v205 offset:2048
	ds_read_b128 v[214:217], v205 offset:3072
	global_load_lds_dwordx4 v[140:141], off
	v_lshl_add_u64 v[140:141], v[202:203], 0, s[2:3]
	s_mov_b32 m0, s67
	s_nop 0
	global_load_lds_dwordx4 v[140:141], off
	s_barrier
; __device__ __forceinline__ int lane_id_() { int l; asm volatile("v_mbcnt_lo_u32_b32 %0, -1, 0\n\tv_mbcnt_hi_u32_b32 %0, -1, %0" : "=v"(l)); return l; }
; #define PG8_STAGE(bufoff, gbase, voff) do { _Pragma("unroll") for (int _i = 0; _i < 2; ++_i) \
;         __builtin_amdgcn_global_load_lds((const unsigned*)((const char*)(gbase) + (voff)[_i]), (LAS unsigned*)(lds + (bufoff) + ldsw + _i * 8192), 16, 0, 0); } while (0)
; #define PG8_LDA(dst, b, h) do { _Pragma("unroll") for (int m = 0; m < 4; ++m) _Pragma("unroll") for (int k = 0; k < 2; ++k) dst[m][k] = *(const LAS bf16x8*)(lds + PG8_SA(b, h) + aoff + m * 2048 + k * 1024); } while (0)
; #define PG8_MMA(ai, bj, At, Bt) do { __builtin_amdgcn_s_setprio(1); _Pragma("unroll") for (int m = 0; m < 4; ++m) _Pragma("unroll") for (int n = 0; n < 2; ++n) _Pragma("unroll") for (int k = 0; k < 2; ++k) \
;         acc[ai][bj][m][n] = __builtin_amdgcn_mfma_f32_16x16x32_bf16(Bt[n][k], At[m][k], acc[ai][bj][m][n], 0, 0, 0); __builtin_amdgcn_s_setprio(0); } while (0)
; #define PG8_WAIT_V(n) asm volatile("s_waitcnt vmcnt(" #n ")" ::: "memory")
; #define PG8_WAIT_L(n) asm volatile("s_waitcnt lgkmcnt(" #n ")" ::: "memory")
; #define PG8_BAR __builtin_amdgcn_s_barrier()
; #define PG8_SCHED __builtin_amdgcn_sched_barrier(0)
; template <class Epi, bool KS0 = false>
; __device__ __forceinline__ void gemm_phase(const int WID, LAS unsigned char* lds, const Gemm g, const StaticOrder& S, const Epi& E) {
;     ...
;             PG8_BAR; PG8_WAIT_L(0); PG8_MMA(0, 1, At, B1); PG8_BAR;
;             PG8_LDA(At, 1, 1); PG8_STAGE(PG8_SA(1, 0), a3, voffA);
;             PG8_BAR; PG8_WAIT_L(0); PG8_MMA(1, 0, At, B0); PG8_BAR; PG8_SCHED;
;             PG8_STAGE(PG8_SB(1, 1), b3 + hstep, voffB);
;             PG8_WAIT_V(6); PG8_BAR; PG8_MMA(1, 1, At, B1); PG8_BAR;
;         }
;         { int fr2 = lane_id_(), fq2; fq2 = fr2 >> 4; fr2 &= 15; asm volatile("" : "+v"(fr2), "+v"(fq2)); E(acc, cur, wr, wc, fr2, fq2); }
;     __device__ __forceinline__ void operator()(f32x4 (&acc)[2][2][4][2], const Unit& u, int wr, int wc, int fr, int fq) const {
;     ...
;         if (frag && u.pn >= fmin) { base = O + ((size_t)(u.pm * frag + u.pn) << 16) + (size_t)((((wr * 4 + wc) * 16) * 64 + fq * 16 + fr) << 3); s_ai = 4096; s_m = 1024; s_bj = 512; }
	s_waitcnt lgkmcnt(0)
	v_mfma_f32_16x16x32_bf16 v[116:119], v[194:197], v[162:165], v[116:119]
	v_mfma_f32_16x16x32_bf16 v[108:111], v[210:213], v[162:165], v[108:111]
	v_mfma_f32_16x16x32_bf16 v[96:99], v[194:197], v[170:173], v[96:99]
	v_mfma_f32_16x16x32_bf16 v[88:91], v[210:213], v[170:173], v[88:91]
	v_mfma_f32_16x16x32_bf16 v[80:83], v[194:197], v[178:181], v[80:83]
	v_mfma_f32_16x16x32_bf16 v[72:75], v[210:213], v[178:181], v[72:75]
	v_mfma_f32_16x16x32_bf16 v[68:71], v[194:197], v[186:189], v[68:71]
	v_mfma_f32_16x16x32_bf16 v[64:67], v[210:213], v[186:189], v[64:67]
	v_mfma_f32_16x16x32_bf16 v[116:119], v[198:201], v[166:169], v[116:119]
	v_mfma_f32_16x16x32_bf16 v[108:111], v[214:217], v[166:169], v[108:111]
	v_mfma_f32_16x16x32_bf16 v[96:99], v[198:201], v[174:177], v[96:99]
	v_mfma_f32_16x16x32_bf16 v[88:91], v[214:217], v[174:177], v[88:91]
	v_mfma_f32_16x16x32_bf16 v[80:83], v[198:201], v[182:185], v[80:83]
	v_mfma_f32_16x16x32_bf16 v[72:75], v[214:217], v[182:185], v[72:75]
	v_mfma_f32_16x16x32_bf16 v[68:71], v[198:201], v[190:193], v[68:71]
	v_mfma_f32_16x16x32_bf16 v[64:67], v[214:217], v[190:193], v[64:67]
	s_mov_b32 m0, s57
	v_lshl_add_u64 v[140:141], v[206:207], 0, s[2:3]
	s_barrier
	ds_read_b128 v[162:165], v144 offset:49152
	ds_read_b128 v[166:169], v144 offset:50176
	ds_read_b128 v[170:173], v144 offset:51200
	ds_read_b128 v[174:177], v144 offset:52224
	ds_read_b128 v[178:181], v144 offset:53248
	ds_read_b128 v[182:185], v144 offset:54272
	ds_read_b128 v[186:189], v144 offset:55296
	ds_read_b128 v[190:193], v144 offset:56320
	global_load_lds_dwordx4 v[140:141], off
	v_lshl_add_u64 v[140:141], v[218:219], 0, s[2:3]
	s_mov_b32 m0, s58
	s_nop 0
	global_load_lds_dwordx4 v[140:141], off
	s_barrier
	s_waitcnt lgkmcnt(0)
	v_mfma_f32_16x16x32_bf16 v[60:63], v[146:149], v[162:165], v[60:63]
	v_mfma_f32_16x16x32_bf16 v[56:59], v[154:157], v[162:165], v[56:59]
	v_mfma_f32_16x16x32_bf16 v[52:55], v[146:149], v[170:173], v[52:55]
	v_mfma_f32_16x16x32_bf16 v[44:47], v[154:157], v[170:173], v[44:47]
	v_mfma_f32_16x16x32_bf16 v[36:39], v[146:149], v[178:181], v[36:39]
	v_mfma_f32_16x16x32_bf16 v[28:31], v[154:157], v[178:181], v[28:31]
	v_mfma_f32_16x16x32_bf16 v[20:23], v[146:149], v[186:189], v[20:23]
	v_mfma_f32_16x16x32_bf16 v[12:15], v[154:157], v[186:189], v[12:15]
	v_mfma_f32_16x16x32_bf16 v[60:63], v[150:153], v[166:169], v[60:63]
	v_mfma_f32_16x16x32_bf16 v[56:59], v[158:161], v[166:169], v[56:59]
	v_mfma_f32_16x16x32_bf16 v[52:55], v[150:153], v[174:177], v[52:55]
	v_mfma_f32_16x16x32_bf16 v[44:47], v[158:161], v[174:177], v[44:47]
	v_mfma_f32_16x16x32_bf16 v[36:39], v[150:153], v[182:185], v[36:39]
	v_mfma_f32_16x16x32_bf16 v[28:31], v[158:161], v[182:185], v[28:31]
	v_mfma_f32_16x16x32_bf16 v[20:23], v[150:153], v[190:193], v[20:23]
	v_mfma_f32_16x16x32_bf16 v[12:15], v[158:161], v[190:193], v[12:15]
	s_barrier
	s_mov_b32 m0, s66
	global_load_lds_dwordx4 v132, s[34:35]
	s_mov_b32 m0, s65
	s_nop 0
	global_load_lds_dwordx4 v128, s[34:35]
	s_waitcnt vmcnt(6)
	s_barrier
	v_mfma_f32_16x16x32_bf16 v[48:51], v[194:197], v[162:165], v[48:51]
	v_mfma_f32_16x16x32_bf16 v[40:43], v[210:213], v[162:165], v[40:43]
	v_mfma_f32_16x16x32_bf16 v[32:35], v[194:197], v[170:173], v[32:35]
	v_mfma_f32_16x16x32_bf16 v[24:27], v[210:213], v[170:173], v[24:27]
	v_mfma_f32_16x16x32_bf16 v[16:19], v[194:197], v[178:181], v[16:19]
	v_mfma_f32_16x16x32_bf16 v[8:11], v[210:213], v[178:181], v[8:11]
	v_mfma_f32_16x16x32_bf16 v[4:7], v[194:197], v[186:189], v[4:7]
	v_mfma_f32_16x16x32_bf16 v[0:3], v[210:213], v[186:189], v[0:3]
	v_mfma_f32_16x16x32_bf16 v[48:51], v[198:201], v[166:169], v[48:51]
	v_mfma_f32_16x16x32_bf16 v[40:43], v[214:217], v[166:169], v[40:43]
	v_mfma_f32_16x16x32_bf16 v[32:35], v[198:201], v[174:177], v[32:35]
	v_mfma_f32_16x16x32_bf16 v[24:27], v[214:217], v[174:177], v[24:27]
	v_mfma_f32_16x16x32_bf16 v[16:19], v[198:201], v[182:185], v[16:19]
	v_mfma_f32_16x16x32_bf16 v[8:11], v[214:217], v[182:185], v[8:11]
	v_mfma_f32_16x16x32_bf16 v[4:7], v[198:201], v[190:193], v[4:7]
	v_mfma_f32_16x16x32_bf16 v[0:3], v[214:217], v[190:193], v[0:3]
	s_movk_i32 s42, 0x100
	s_andn2_b64 vcc, exec, s[30:31]
	s_mov_b64 s[34:35], -1
	s_mov_b64 s[30:31], 0
	s_barrier
	s_cbranch_vccz .LBB0_703
	v_mbcnt_lo_u32_b32 v140, -1, 0
	v_mbcnt_hi_u32_b32 v140, -1, v140
	s_cmp_lt_i32 s62, 0
	v_ashrrev_i32_e32 v141, 4, v140
	v_and_b32_e32 v146, 15, v140
	s_mov_b64 s[18:19], -1
	s_cbranch_scc1 .LBB0_706
	v_readlane_b32 s9, v251, 37
	v_lshlrev_b32_e32 v147, 7, v141
	s_mov_b64 s[18:19], 0
	v_add_u32_e32 v140, s9, v146
	v_lshl_add_u32 v140, v140, 3, v147

; #define PG8_STAGE(bufoff, gbase, voff) do { _Pragma("unroll") for (int _i = 0; _i < 2; ++_i) \
;         __builtin_amdgcn_global_load_lds((const unsigned*)((const char*)(gbase) + (voff)[_i]), (LAS unsigned*)(lds + (bufoff) + ldsw + _i * 8192), 16, 0, 0); } while (0)
; #define PG8_LDA(dst, b, h) do { _Pragma("unroll") for (int m = 0; m < 4; ++m) _Pragma("unroll") for (int k = 0; k < 2; ++k) dst[m][k] = *(const LAS bf16x8*)(lds + PG8_SA(b, h) + aoff + m * 2048 + k * 1024); } while (0)
; #define PG8_LDB(dst, b, h) do { _Pragma("unroll") for (int n = 0; n < 2; ++n) _Pragma("unroll") for (int k = 0; k < 2; ++k) dst[n][k] = *(const LAS bf16x8*)(lds + PG8_SB(b, h) + boff + n * 2048 + k * 1024); } while (0)
; #define PG8_MMA(ai, bj, At, Bt) do { __builtin_amdgcn_s_setprio(1); _Pragma("unroll") for (int m = 0; m < 4; ++m) _Pragma("unroll") for (int n = 0; n < 2; ++n) _Pragma("unroll") for (int k = 0; k < 2; ++k) \
;         acc[ai][bj][m][n] = __builtin_amdgcn_mfma_f32_16x16x32_bf16(Bt[n][k], At[m][k], acc[ai][bj][m][n], 0, 0, 0); __builtin_amdgcn_s_setprio(0); } while (0)
; #define PG8_WAIT_V(n) asm volatile("s_waitcnt vmcnt(" #n ")" ::: "memory")
; #define PG8_WAIT_L(n) asm volatile("s_waitcnt lgkmcnt(" #n ")" ::: "memory")
; #define PG8_BAR __builtin_amdgcn_s_barrier()
; #define PG8_SCHED __builtin_amdgcn_sched_barrier(0)
; template <class Epi, bool KS0 = false>
; __device__ __forceinline__ void gemm_phase(const int WID, LAS unsigned char* lds, const Gemm g, const StaticOrder& S, const Epi& E) {
;     ...
;             PG8_LDB(B0, 0, 0); PG8_SCHED; PG8_LDA(At, 0, 0); PG8_STAGE(PG8_SA(1, 1), a1 + hstep, voffA);
;             PG8_WAIT_L(8); PG8_BAR; PG8_WAIT_L(0); PG8_MMA(0, 0, At, B0); PG8_BAR; PG8_SCHED;
;             PG8_LDB(B1, 0, 1); PG8_STAGE(PG8_SB(0, 0), b2, voffB);
;             PG8_BAR; PG8_WAIT_L(0); PG8_MMA(0, 1, At, B1); PG8_BAR;
;             PG8_LDA(At, 0, 1); PG8_STAGE(PG8_SA(0, 0), a2, voffA);
;             PG8_BAR; PG8_WAIT_L(0); PG8_MMA(1, 0, At, B0); PG8_BAR; PG8_SCHED;
;             PG8_STAGE(PG8_SB(0, 1), b2 + hstep, voffB);
;             PG8_WAIT_V(6); PG8_BAR; PG8_MMA(1, 1, At, B1); PG8_BAR;
.LBB0_777:
	ds_read_b128 v[108:111], v175
	ds_read_b128 v[132:135], v175 offset:1024
	ds_read_b128 v[136:139], v175 offset:2048
	ds_read_b128 v[152:155], v175 offset:3072
	s_add_u32 s12, s2, 0xfff80080
	s_addc_u32 s13, s3, -1
	s_cmp_eq_u32 s53, 28
	s_cselect_b32 s15, s28, s13
	s_cselect_b32 s14, s29, s12
	s_cselect_b32 s13, s42, s45
	s_cselect_b32 s12, s43, s44
	v_lshl_add_u64 v[196:197], s[2:3], 0, v[144:145]
	s_add_i32 m0, s9, 0xc000
	ds_read_b128 v[156:159], v176
	ds_read_b128 v[160:163], v176 offset:1024
	ds_read_b128 v[164:167], v176 offset:2048
	ds_read_b128 v[168:171], v176 offset:3072
	ds_read_b128 v[180:183], v176 offset:4096
	ds_read_b128 v[184:187], v176 offset:5120
	ds_read_b128 v[188:191], v176 offset:6144
	ds_read_b128 v[192:195], v176 offset:7168
	global_load_lds_dwordx4 v[196:197], off
	s_add_i32 m0, s9, 0xe000
	s_nop 0
	global_load_lds_dwordx4 v146, s[2:3]
	s_waitcnt lgkmcnt(8)
	s_barrier
	s_waitcnt lgkmcnt(0)
	v_mfma_f32_16x16x32_bf16 v[128:131], v[108:111], v[156:159], v[128:131]
	v_mfma_f32_16x16x32_bf16 v[124:127], v[136:139], v[156:159], v[124:127]
	v_mfma_f32_16x16x32_bf16 v[116:119], v[108:111], v[164:167], v[116:119]
	v_mfma_f32_16x16x32_bf16 v[112:115], v[136:139], v[164:167], v[112:115]
	v_mfma_f32_16x16x32_bf16 v[104:107], v[108:111], v[180:183], v[104:107]
	v_mfma_f32_16x16x32_bf16 v[96:99], v[136:139], v[180:183], v[96:99]
	v_mfma_f32_16x16x32_bf16 v[88:91], v[108:111], v[188:191], v[88:91]
	v_mfma_f32_16x16x32_bf16 v[24:27], v[136:139], v[188:191], v[24:27]
	v_mfma_f32_16x16x32_bf16 v[128:131], v[132:135], v[160:163], v[128:131]
	v_mfma_f32_16x16x32_bf16 v[124:127], v[152:155], v[160:163], v[124:127]
	v_mfma_f32_16x16x32_bf16 v[116:119], v[132:135], v[168:171], v[116:119]
	v_mfma_f32_16x16x32_bf16 v[112:115], v[152:155], v[168:171], v[112:115]
	v_mfma_f32_16x16x32_bf16 v[104:107], v[132:135], v[184:187], v[104:107]
	v_mfma_f32_16x16x32_bf16 v[96:99], v[152:155], v[184:187], v[96:99]
	v_mfma_f32_16x16x32_bf16 v[88:91], v[132:135], v[192:195], v[88:91]
	v_mfma_f32_16x16x32_bf16 v[24:27], v[152:155], v[192:195], v[24:27]
	s_barrier
	s_add_i32 s55, s63, s26
	v_lshl_add_u64 v[214:215], s[12:13], 0, v[140:141]
	s_mov_b32 m0, s55
	ds_read_b128 v[196:199], v177
	ds_read_b128 v[200:203], v177 offset:1024
	ds_read_b128 v[204:207], v177 offset:2048
	ds_read_b128 v[210:213], v177 offset:3072
	global_load_lds_dwordx4 v[214:215], off
	v_lshl_add_u64 v[216:217], s[12:13], 0, v[142:143]
	s_add_i32 m0, s55, 0x2000
	s_nop 0
	global_load_lds_dwordx4 v[216:217], off
	s_barrier
	s_waitcnt lgkmcnt(0)
	v_mfma_f32_16x16x32_bf16 v[12:15], v[196:199], v[156:159], v[12:15]
	v_mfma_f32_16x16x32_bf16 v[120:123], v[204:207], v[156:159], v[120:123]
	v_mfma_f32_16x16x32_bf16 v[100:103], v[196:199], v[164:167], v[100:103]
	v_mfma_f32_16x16x32_bf16 v[92:95], v[204:207], v[164:167], v[92:95]
	v_mfma_f32_16x16x32_bf16 v[84:87], v[196:199], v[180:183], v[84:87]
	v_mfma_f32_16x16x32_bf16 v[80:83], v[204:207], v[180:183], v[80:83]
	v_mfma_f32_16x16x32_bf16 v[28:31], v[196:199], v[188:191], v[28:31]
	v_mfma_f32_16x16x32_bf16 v[20:23], v[204:207], v[188:191], v[20:23]
	v_mfma_f32_16x16x32_bf16 v[12:15], v[200:203], v[160:163], v[12:15]
	v_mfma_f32_16x16x32_bf16 v[120:123], v[210:213], v[160:163], v[120:123]
	v_mfma_f32_16x16x32_bf16 v[100:103], v[200:203], v[168:171], v[100:103]
	v_mfma_f32_16x16x32_bf16 v[92:95], v[210:213], v[168:171], v[92:95]
	v_mfma_f32_16x16x32_bf16 v[84:87], v[200:203], v[184:187], v[84:87]
	v_mfma_f32_16x16x32_bf16 v[80:83], v[210:213], v[184:187], v[80:83]
	v_mfma_f32_16x16x32_bf16 v[28:31], v[200:203], v[192:195], v[28:31]
	v_mfma_f32_16x16x32_bf16 v[20:23], v[210:213], v[192:195], v[20:23]
	s_mov_b32 m0, s9
	v_lshl_add_u64 v[218:219], s[14:15], 0, v[140:141]
	s_barrier
	ds_read_b128 v[156:159], v176 offset:16384
	ds_read_b128 v[160:163], v176 offset:17408
	ds_read_b128 v[164:167], v176 offset:18432
	ds_read_b128 v[168:171], v176 offset:19456
	ds_read_b128 v[180:183], v176 offset:20480
	ds_read_b128 v[184:187], v176 offset:21504
	ds_read_b128 v[188:191], v176 offset:22528
	ds_read_b128 v[192:195], v176 offset:23552
	global_load_lds_dwordx4 v[218:219], off
	v_lshl_add_u64 v[220:221], s[14:15], 0, v[142:143]
	s_mov_b32 m0, s11
	s_nop 0
	global_load_lds_dwordx4 v[220:221], off
	s_barrier
	s_waitcnt lgkmcnt(0)
	v_mfma_f32_16x16x32_bf16 v[76:79], v[108:111], v[156:159], v[76:79]
	v_mfma_f32_16x16x32_bf16 v[72:75], v[136:139], v[156:159], v[72:75]
	v_mfma_f32_16x16x32_bf16 v[68:71], v[108:111], v[164:167], v[68:71]
	v_mfma_f32_16x16x32_bf16 v[64:67], v[136:139], v[164:167], v[64:67]
	v_mfma_f32_16x16x32_bf16 v[52:55], v[108:111], v[180:183], v[52:55]
	v_mfma_f32_16x16x32_bf16 v[48:51], v[136:139], v[180:183], v[48:51]
	v_mfma_f32_16x16x32_bf16 v[16:19], v[108:111], v[188:191], v[16:19]
	v_mfma_f32_16x16x32_bf16 v[8:11], v[136:139], v[188:191], v[8:11]
	v_mfma_f32_16x16x32_bf16 v[76:79], v[132:135], v[160:163], v[76:79]
	v_mfma_f32_16x16x32_bf16 v[72:75], v[152:155], v[160:163], v[72:75]
	v_mfma_f32_16x16x32_bf16 v[68:71], v[132:135], v[168:171], v[68:71]
	v_mfma_f32_16x16x32_bf16 v[64:67], v[152:155], v[168:171], v[64:67]
	v_mfma_f32_16x16x32_bf16 v[52:55], v[132:135], v[184:187], v[52:55]
	v_mfma_f32_16x16x32_bf16 v[48:51], v[152:155], v[184:187], v[48:51]
	v_mfma_f32_16x16x32_bf16 v[16:19], v[132:135], v[192:195], v[16:19]
	v_mfma_f32_16x16x32_bf16 v[8:11], v[152:155], v[192:195], v[8:11]
	s_barrier
	s_add_u32 s70, s12, 0x80000
	s_addc_u32 s71, s13, 0
	s_add_i32 s55, s64, s26
	s_mov_b32 m0, s55
	s_nop 0
	global_load_lds_dwordx4 v140, s[70:71]
	s_add_i32 m0, s55, 0x2000
	s_nop 0
	global_load_lds_dwordx4 v142, s[70:71]
	s_waitcnt vmcnt(6)
	s_barrier
; #define PG8_STAGE(bufoff, gbase, voff) do { _Pragma("unroll") for (int _i = 0; _i < 2; ++_i) \
;         __builtin_amdgcn_global_load_lds((const unsigned*)((const char*)(gbase) + (voff)[_i]), (LAS unsigned*)(lds + (bufoff) + ldsw + _i * 8192), 16, 0, 0); } while (0)
; #define PG8_LDA(dst, b, h) do { _Pragma("unroll") for (int m = 0; m < 4; ++m) _Pragma("unroll") for (int k = 0; k < 2; ++k) dst[m][k] = *(const LAS bf16x8*)(lds + PG8_SA(b, h) + aoff + m * 2048 + k * 1024); } while (0)
; #define PG8_LDB(dst, b, h) do { _Pragma("unroll") for (int n = 0; n < 2; ++n) _Pragma("unroll") for (int k = 0; k < 2; ++k) dst[n][k] = *(const LAS bf16x8*)(lds + PG8_SB(b, h) + boff + n * 2048 + k * 1024); } while (0)
; #define PG8_MMA(ai, bj, At, Bt) do { __builtin_amdgcn_s_setprio(1); _Pragma("unroll") for (int m = 0; m < 4; ++m) _Pragma("unroll") for (int n = 0; n < 2; ++n) _Pragma("unroll") for (int k = 0; k < 2; ++k) \
;         acc[ai][bj][m][n] = __builtin_amdgcn_mfma_f32_16x16x32_bf16(Bt[n][k], At[m][k], acc[ai][bj][m][n], 0, 0, 0); __builtin_amdgcn_s_setprio(0); } while (0)
; #define PG8_WAIT_V(n) asm volatile("s_waitcnt vmcnt(" #n ")" ::: "memory")
; #define PG8_WAIT_L(n) asm volatile("s_waitcnt lgkmcnt(" #n ")" ::: "memory")
; #define PG8_BAR __builtin_amdgcn_s_barrier()
; #define PG8_SCHED __builtin_amdgcn_sched_barrier(0)
; template <class Epi, bool KS0 = false>
; __device__ __forceinline__ void gemm_phase(const int WID, LAS unsigned char* lds, const Gemm g, const StaticOrder& S, const Epi& E) {
;     ...
;             PG8_WAIT_V(6); PG8_BAR; PG8_MMA(1, 1, At, B1); PG8_BAR;
;             PG8_LDB(B0, 1, 0); PG8_SCHED; PG8_LDA(At, 1, 0); PG8_STAGE(PG8_SA(0, 1), a2 + hstep, voffA);
;             PG8_WAIT_L(8); PG8_BAR; PG8_WAIT_L(0); PG8_MMA(0, 0, At, B0); PG8_BAR; PG8_SCHED;
;             PG8_LDB(B1, 1, 1); PG8_STAGE(PG8_SB(1, 0), b3, voffB);
;             PG8_BAR; PG8_WAIT_L(0); PG8_MMA(0, 1, At, B1); PG8_BAR;
;             PG8_LDA(At, 1, 1); PG8_STAGE(PG8_SA(1, 0), a3, voffA);
	v_mfma_f32_16x16x32_bf16 v[60:63], v[196:199], v[156:159], v[60:63]
	v_mfma_f32_16x16x32_bf16 v[56:59], v[204:207], v[156:159], v[56:59]
	v_mfma_f32_16x16x32_bf16 v[44:47], v[196:199], v[164:167], v[44:47]
	v_mfma_f32_16x16x32_bf16 v[40:43], v[204:207], v[164:167], v[40:43]
	v_mfma_f32_16x16x32_bf16 v[36:39], v[196:199], v[180:183], v[36:39]
	v_mfma_f32_16x16x32_bf16 v[32:35], v[204:207], v[180:183], v[32:35]
	v_mfma_f32_16x16x32_bf16 v[4:7], v[196:199], v[188:191], v[4:7]
	v_mfma_f32_16x16x32_bf16 v[0:3], v[204:207], v[188:191], v[0:3]
	v_mfma_f32_16x16x32_bf16 v[60:63], v[200:203], v[160:163], v[60:63]
	v_mfma_f32_16x16x32_bf16 v[56:59], v[210:213], v[160:163], v[56:59]
	v_mfma_f32_16x16x32_bf16 v[44:47], v[200:203], v[168:171], v[44:47]
	v_mfma_f32_16x16x32_bf16 v[40:43], v[210:213], v[168:171], v[40:43]
	v_mfma_f32_16x16x32_bf16 v[36:39], v[200:203], v[184:187], v[36:39]
	v_mfma_f32_16x16x32_bf16 v[32:35], v[210:213], v[184:187], v[32:35]
	v_mfma_f32_16x16x32_bf16 v[4:7], v[200:203], v[192:195], v[4:7]
	v_mfma_f32_16x16x32_bf16 v[0:3], v[210:213], v[192:195], v[0:3]
	s_add_i32 s55, 0, 0x18000
	v_add_u32_e32 v152, s55, v174
	s_barrier
	ds_read_b128 v[108:111], v152
	ds_read_b128 v[132:135], v152 offset:1024
	ds_read_b128 v[136:139], v152 offset:2048
	ds_read_b128 v[152:155], v152 offset:3072
	s_add_u32 s14, s14, 0x80000
	s_addc_u32 s15, s15, 0
	s_mov_b32 m0, s18
	v_lshl_add_u64 v[196:197], s[14:15], 0, v[140:141]
	ds_read_b128 v[156:159], v176 offset:32768
	ds_read_b128 v[160:163], v176 offset:33792
	ds_read_b128 v[164:167], v176 offset:34816
	ds_read_b128 v[168:171], v176 offset:35840
	ds_read_b128 v[180:183], v176 offset:36864
	ds_read_b128 v[184:187], v176 offset:37888
	ds_read_b128 v[188:191], v176 offset:38912
	ds_read_b128 v[192:195], v176 offset:39936
	global_load_lds_dwordx4 v[196:197], off
	s_mov_b32 m0, s19
	s_nop 0
	global_load_lds_dwordx4 v142, s[14:15]
	s_waitcnt lgkmcnt(8)
	s_barrier
	s_waitcnt lgkmcnt(0)
	v_mfma_f32_16x16x32_bf16 v[128:131], v[108:111], v[156:159], v[128:131]
	v_mfma_f32_16x16x32_bf16 v[124:127], v[136:139], v[156:159], v[124:127]
	v_mfma_f32_16x16x32_bf16 v[116:119], v[108:111], v[164:167], v[116:119]
	v_mfma_f32_16x16x32_bf16 v[112:115], v[136:139], v[164:167], v[112:115]
	v_mfma_f32_16x16x32_bf16 v[104:107], v[108:111], v[180:183], v[104:107]
	v_mfma_f32_16x16x32_bf16 v[96:99], v[136:139], v[180:183], v[96:99]
	v_mfma_f32_16x16x32_bf16 v[88:91], v[108:111], v[188:191], v[88:91]
	v_mfma_f32_16x16x32_bf16 v[24:27], v[136:139], v[188:191], v[24:27]
	v_mfma_f32_16x16x32_bf16 v[128:131], v[132:135], v[160:163], v[128:131]
	v_mfma_f32_16x16x32_bf16 v[124:127], v[152:155], v[160:163], v[124:127]
	v_mfma_f32_16x16x32_bf16 v[116:119], v[132:135], v[168:171], v[116:119]
	v_mfma_f32_16x16x32_bf16 v[112:115], v[152:155], v[168:171], v[112:115]
	v_mfma_f32_16x16x32_bf16 v[104:107], v[132:135], v[184:187], v[104:107]
	v_mfma_f32_16x16x32_bf16 v[96:99], v[152:155], v[184:187], v[96:99]
	v_mfma_f32_16x16x32_bf16 v[88:91], v[132:135], v[192:195], v[88:91]
	v_mfma_f32_16x16x32_bf16 v[24:27], v[152:155], v[192:195], v[24:27]
	s_barrier
	s_add_i32 s14, 0, 0x1c000
	s_add_i32 s15, s55, s26
	v_add_u32_e32 v179, s14, v174
	v_lshl_add_u64 v[214:215], v[214:215], 0, s[50:51]
	s_mov_b32 m0, s15
	ds_read_b128 v[196:199], v179
	ds_read_b128 v[200:203], v179 offset:1024
	ds_read_b128 v[204:207], v179 offset:2048
	ds_read_b128 v[210:213], v179 offset:3072
	global_load_lds_dwordx4 v[214:215], off
	v_lshl_add_u64 v[214:215], v[216:217], 0, s[50:51]
	s_add_i32 m0, s15, 0x2000
	s_nop 0
	global_load_lds_dwordx4 v[214:215], off
	s_barrier
	s_waitcnt lgkmcnt(0)
	v_mfma_f32_16x16x32_bf16 v[12:15], v[196:199], v[156:159], v[12:15]
	v_mfma_f32_16x16x32_bf16 v[120:123], v[204:207], v[156:159], v[120:123]
	v_mfma_f32_16x16x32_bf16 v[100:103], v[196:199], v[164:167], v[100:103]
	v_mfma_f32_16x16x32_bf16 v[92:95], v[204:207], v[164:167], v[92:95]
	v_mfma_f32_16x16x32_bf16 v[84:87], v[196:199], v[180:183], v[84:87]
	v_mfma_f32_16x16x32_bf16 v[80:83], v[204:207], v[180:183], v[80:83]
	v_mfma_f32_16x16x32_bf16 v[28:31], v[196:199], v[188:191], v[28:31]
	v_mfma_f32_16x16x32_bf16 v[20:23], v[204:207], v[188:191], v[20:23]
	v_mfma_f32_16x16x32_bf16 v[12:15], v[200:203], v[160:163], v[12:15]
	v_mfma_f32_16x16x32_bf16 v[120:123], v[210:213], v[160:163], v[120:123]
	v_mfma_f32_16x16x32_bf16 v[100:103], v[200:203], v[168:171], v[100:103]
	v_mfma_f32_16x16x32_bf16 v[92:95], v[210:213], v[168:171], v[92:95]
	v_mfma_f32_16x16x32_bf16 v[84:87], v[200:203], v[184:187], v[84:87]
	v_mfma_f32_16x16x32_bf16 v[80:83], v[210:213], v[184:187], v[80:83]
	v_mfma_f32_16x16x32_bf16 v[28:31], v[200:203], v[192:195], v[28:31]
	v_mfma_f32_16x16x32_bf16 v[20:23], v[210:213], v[192:195], v[20:23]
	s_mov_b32 m0, s61
	v_lshl_add_u64 v[214:215], v[218:219], 0, s[50:51]
	s_barrier
	ds_read_b128 v[156:159], v176 offset:49152
	ds_read_b128 v[160:163], v176 offset:50176
	ds_read_b128 v[164:167], v176 offset:51200
	ds_read_b128 v[168:171], v176 offset:52224
	ds_read_b128 v[180:183], v176 offset:53248
	ds_read_b128 v[184:187], v176 offset:54272
	ds_read_b128 v[188:191], v176 offset:55296
	ds_read_b128 v[192:195], v176 offset:56320
	global_load_lds_dwordx4 v[214:215], off
	v_lshl_add_u64 v[214:215], v[220:221], 0, s[50:51]
	s_mov_b32 m0, s62
	s_nop 0
	global_load_lds_dwordx4 v[214:215], off
	s_barrier
; #define LAS __attribute__((address_space(3)))
; #define PG8_STAGE(bufoff, gbase, voff) do { _Pragma("unroll") for (int _i = 0; _i < 2; ++_i) \
;         __builtin_amdgcn_global_load_lds((const unsigned*)((const char*)(gbase) + (voff)[_i]), (LAS unsigned*)(lds + (bufoff) + ldsw + _i * 8192), 16, 0, 0); } while (0)
; #define PG8_MMA(ai, bj, At, Bt) do { __builtin_amdgcn_s_setprio(1); _Pragma("unroll") for (int m = 0; m < 4; ++m) _Pragma("unroll") for (int n = 0; n < 2; ++n) _Pragma("unroll") for (int k = 0; k < 2; ++k) \
;         acc[ai][bj][m][n] = __builtin_amdgcn_mfma_f32_16x16x32_bf16(Bt[n][k], At[m][k], acc[ai][bj][m][n], 0, 0, 0); __builtin_amdgcn_s_setprio(0); } while (0)
; #define PG8_WAIT_V(n) asm volatile("s_waitcnt vmcnt(" #n ")" ::: "memory")
; #define PG8_WAIT_L(n) asm volatile("s_waitcnt lgkmcnt(" #n ")" ::: "memory")
; #define PG8_BAR __builtin_amdgcn_s_barrier()
; #define PG8_SCHED __builtin_amdgcn_sched_barrier(0)
; template <class Epi, bool KS0 = false>
; __device__ __forceinline__ void gemm_phase(const int WID, LAS unsigned char* lds, const Gemm g, const StaticOrder& S, const Epi& E) {
;     ...
;             PG8_BAR; PG8_WAIT_L(0); PG8_MMA(1, 0, At, B0); PG8_BAR; PG8_SCHED;
;             PG8_STAGE(PG8_SB(1, 1), b3 + hstep, voffB);
;             PG8_WAIT_V(6); PG8_BAR; PG8_MMA(1, 1, At, B1); PG8_BAR;
;         }
;     __device__ __forceinline__ void operator()(f32x4 (&acc)[2][2][4][2], const Unit& u, int wr, int wc, int fr, int fq) const {
;         const int rowt = u.pm * BM + wr * 64 + fr, cl0 = wc * 32 + 4 * fq, wv = wr * 4 + wc, ln = fq * 16 + fr;
;         float cwr[4];
; #pragma unroll
;         for (int i = 0; i < 4; ++i) { const float* srcp = (i < 3) ? (cw + (size_t)i * FF2) : cb; cwr[i] = srcp[(ln >> 5) * FF + u.pn * HALF + wc * 32 + (ln & 31)]; }
;         {
;             LAS float* myr = rsl + wv * 128; LAS int* mypm = (LAS int*)(rsl + 1024) + wv;
;             if (__builtin_amdgcn_readfirstlane(*mypm) != u.pm) {
; #pragma unroll
;                 for (int ai = 0; ai < 2; ++ai)
; #pragma unroll
;                     for (int m = 0; m < 4; ++m) { const float r_ = row_rstd(ssq_in, rowt + ai * HALF + m * 16, fq); if (fq == 0) myr[(ai * 4 + m) * 16 + fr] = r_; }
;                 if (fq == 0 && fr == 0) *mypm = u.pm;
;                 asm volatile("s_waitcnt lgkmcnt(0)" ::: "memory");
	s_waitcnt lgkmcnt(0)
	v_mfma_f32_16x16x32_bf16 v[76:79], v[108:111], v[156:159], v[76:79]
	v_mfma_f32_16x16x32_bf16 v[72:75], v[136:139], v[156:159], v[72:75]
	v_mfma_f32_16x16x32_bf16 v[68:71], v[108:111], v[164:167], v[68:71]
	v_mfma_f32_16x16x32_bf16 v[64:67], v[136:139], v[164:167], v[64:67]
	v_mfma_f32_16x16x32_bf16 v[52:55], v[108:111], v[180:183], v[52:55]
	v_mfma_f32_16x16x32_bf16 v[48:51], v[136:139], v[180:183], v[48:51]
	v_mfma_f32_16x16x32_bf16 v[16:19], v[108:111], v[188:191], v[16:19]
	v_mfma_f32_16x16x32_bf16 v[8:11], v[136:139], v[188:191], v[8:11]
	v_mfma_f32_16x16x32_bf16 v[76:79], v[132:135], v[160:163], v[76:79]
	v_mfma_f32_16x16x32_bf16 v[72:75], v[152:155], v[160:163], v[72:75]
	v_mfma_f32_16x16x32_bf16 v[68:71], v[132:135], v[168:171], v[68:71]
	v_mfma_f32_16x16x32_bf16 v[64:67], v[152:155], v[168:171], v[64:67]
	v_mfma_f32_16x16x32_bf16 v[52:55], v[132:135], v[184:187], v[52:55]
	v_mfma_f32_16x16x32_bf16 v[48:51], v[152:155], v[184:187], v[48:51]
	v_mfma_f32_16x16x32_bf16 v[16:19], v[132:135], v[192:195], v[16:19]
	v_mfma_f32_16x16x32_bf16 v[8:11], v[152:155], v[192:195], v[8:11]
	s_barrier
	s_add_u32 s12, s12, 0x80080
	s_addc_u32 s13, s13, 0
	s_add_i32 s14, s14, s26
	s_mov_b32 m0, s14
	s_nop 0
	global_load_lds_dwordx4 v140, s[12:13]
	s_add_i32 m0, s14, 0x2000
	s_nop 0
	global_load_lds_dwordx4 v142, s[12:13]
	s_waitcnt vmcnt(6)
	s_barrier
	v_mfma_f32_16x16x32_bf16 v[60:63], v[196:199], v[156:159], v[60:63]
	v_mfma_f32_16x16x32_bf16 v[56:59], v[204:207], v[156:159], v[56:59]
	v_mfma_f32_16x16x32_bf16 v[44:47], v[196:199], v[164:167], v[44:47]
	v_mfma_f32_16x16x32_bf16 v[40:43], v[204:207], v[164:167], v[40:43]
	v_mfma_f32_16x16x32_bf16 v[36:39], v[196:199], v[180:183], v[36:39]
	v_mfma_f32_16x16x32_bf16 v[32:35], v[204:207], v[180:183], v[32:35]
	v_mfma_f32_16x16x32_bf16 v[4:7], v[196:199], v[188:191], v[4:7]
	v_mfma_f32_16x16x32_bf16 v[0:3], v[204:207], v[188:191], v[0:3]
	v_mfma_f32_16x16x32_bf16 v[60:63], v[200:203], v[160:163], v[60:63]
	v_mfma_f32_16x16x32_bf16 v[56:59], v[210:213], v[160:163], v[56:59]
	v_mfma_f32_16x16x32_bf16 v[44:47], v[200:203], v[168:171], v[44:47]
	v_mfma_f32_16x16x32_bf16 v[40:43], v[210:213], v[168:171], v[40:43]
	v_mfma_f32_16x16x32_bf16 v[36:39], v[200:203], v[184:187], v[36:39]
	v_mfma_f32_16x16x32_bf16 v[32:35], v[210:213], v[184:187], v[32:35]
	v_mfma_f32_16x16x32_bf16 v[4:7], v[200:203], v[192:195], v[4:7]
	v_mfma_f32_16x16x32_bf16 v[0:3], v[210:213], v[192:195], v[0:3]
	s_add_i32 s53, s53, 2
	s_add_u32 s2, s2, 0x100
	s_addc_u32 s3, s3, 0
	s_add_u32 s44, s44, 0x100
	s_addc_u32 s45, s45, 0
	s_cmp_gt_u32 s53, 29
	s_barrier
	s_cbranch_scc0 .LBB0_777
	v_mbcnt_lo_u32_b32 v108, -1, 0
	v_mbcnt_hi_u32_b32 v108, -1, v108
	s_movk_i32 s3, 0x1600
	v_ashrrev_i32_e32 v132, 4, v108
	v_and_b32_e32 v179, 15, v108
	s_lshl_b32 s12, s8, 7
	v_lshl_add_u32 v164, v132, 4, v179
	v_lshrrev_b32_e32 v108, 5, v164
	v_mul_lo_u32 v108, v108, s3
	v_add_u32_e32 v108, s12, v108
	v_and_b32_e32 v109, 31, v164
	v_readlane_b32 s3, v254, 19
	s_lshl_b32 s2, s10, 8
	s_add_i32 s2, s2, s22
	v_or3_b32 v108, v108, v109, s3
	v_ashrrev_i32_e32 v109, 31, v108
	v_lshlrev_b64 v[108:109], 2, v[108:109]
	v_lshl_add_u64 v[110:111], s[76:77], 0, v[108:109]
	global_load_dword v165, v[110:111], off
	v_lshl_add_u64 v[110:111], s[34:35], 0, v[108:109]
	global_load_dword v166, v[110:111], off
	v_lshl_add_u64 v[110:111], s[48:49], 0, v[108:109]
	v_lshl_add_u64 v[108:109], s[78:79], 0, v[108:109]
	global_load_dword v167, v[110:111], off
	global_load_dword v168, v[108:109], off
	v_mov_b32_e32 v108, s25
	ds_read_b32 v108, v108
	v_add_u32_e32 v152, s2, v179
	v_lshl_add_u32 v155, v179, 2, s21
	s_waitcnt lgkmcnt(0)
	v_readfirstlane_b32 s2, v108
	s_cmp_eq_u32 s2, s10
	s_cbranch_scc1 .LBB0_798
	v_lshlrev_b32_e32 v108, 3, v132
	v_ashrrev_i32_e32 v109, 31, v108
	v_ashrrev_i32_e32 v153, 31, v152
	v_lshl_add_u64 v[108:109], v[108:109], 2, s[16:17]
	v_lshlrev_b64 v[110:111], 7, v[152:153]
	v_lshl_add_u64 v[110:111], v[108:109], 0, v[110:111]
	global_load_dwordx4 v[134:137], v[110:111], off
	global_load_dwordx4 v[156:159], v[110:111], off offset:16
	v_and_b32_e32 v138, 64, v209
	v_xor_b32_e32 v133, 16, v209
	v_add_u32_e32 v138, 64, v138
	v_cmp_lt_i32_e32 vcc, v133, v138
	v_cmp_eq_u32_e64 s[42:43], 0, v132
	s_waitcnt vmcnt(0)
	v_add_f32_e32 v134, v134, v135
	v_add_f32_e32 v135, v136, v137
	v_add_f32_e32 v136, v156, v157
	v_add_f32_e32 v137, v158, v159
	v_cndmask_b32_e32 v133, v209, v133, vcc
	v_add_f32_e32 v134, v134, v135
	v_add_f32_e32 v135, v136, v137
	v_lshlrev_b32_e32 v133, 2, v133
	v_add_f32_e32 v135, v134, v135
	ds_bpermute_b32 v136, v133, v135
	v_xor_b32_e32 v134, 32, v209
	v_cmp_lt_i32_e32 vcc, v134, v138
	s_waitcnt lgkmcnt(0)
	v_add_f32_e32 v135, v135, v136
	v_cndmask_b32_e32 v134, v209, v134, vcc
	v_lshlrev_b32_e32 v134, 2, v134
	ds_bpermute_b32 v136, v134, v135
	s_and_saveexec_b64 s[2:3], s[42:43]
	s_cbranch_execz .LBB0_781
	s_waitcnt lgkmcnt(0)
	v_add_f32_e32 v135, v135, v136
	v_fmamk_f32 v135, v135, 0x3a000000, v178
	v_mul_f32_e32 v136, 0x4b800000, v135
	v_cmp_gt_f32_e32 vcc, s65, v135
	s_nop 1
	v_cndmask_b32_e32 v135, v135, v136, vcc
	v_rsq_f32_e32 v135, v135
	s_nop 0
	v_mul_f32_e32 v136, 0x45800000, v135
	v_cndmask_b32_e32 v135, v135, v136, vcc
	ds_write_b32 v155, v135

; #define PG8_STAGE(bufoff, gbase, voff) do { _Pragma("unroll") for (int _i = 0; _i < 2; ++_i) \
;         __builtin_amdgcn_global_load_lds((const unsigned*)((const char*)(gbase) + (voff)[_i]), (LAS unsigned*)(lds + (bufoff) + ldsw + _i * 8192), 16, 0, 0); } while (0)
; #define PG8_LDA(dst, b, h) do { _Pragma("unroll") for (int m = 0; m < 4; ++m) _Pragma("unroll") for (int k = 0; k < 2; ++k) dst[m][k] = *(const LAS bf16x8*)(lds + PG8_SA(b, h) + aoff + m * 2048 + k * 1024); } while (0)
; #define PG8_LDB(dst, b, h) do { _Pragma("unroll") for (int n = 0; n < 2; ++n) _Pragma("unroll") for (int k = 0; k < 2; ++k) dst[n][k] = *(const LAS bf16x8*)(lds + PG8_SB(b, h) + boff + n * 2048 + k * 1024); } while (0)
; #define PG8_MMA(ai, bj, At, Bt) do { __builtin_amdgcn_s_setprio(1); _Pragma("unroll") for (int m = 0; m < 4; ++m) _Pragma("unroll") for (int n = 0; n < 2; ++n) _Pragma("unroll") for (int k = 0; k < 2; ++k) \
;         acc[ai][bj][m][n] = __builtin_amdgcn_mfma_f32_16x16x32_bf16(Bt[n][k], At[m][k], acc[ai][bj][m][n], 0, 0, 0); __builtin_amdgcn_s_setprio(0); } while (0)
; #define PG8_WAIT_V(n) asm volatile("s_waitcnt vmcnt(" #n ")" ::: "memory")
; #define PG8_WAIT_L(n) asm volatile("s_waitcnt lgkmcnt(" #n ")" ::: "memory")
; #define PG8_BAR __builtin_amdgcn_s_barrier()
; #define PG8_SCHED __builtin_amdgcn_sched_barrier(0)
; template <class Epi, bool KS0 = false>
; __device__ __forceinline__ void gemm_phase(const int WID, LAS unsigned char* lds, const Gemm g, const StaticOrder& S, const Epi& E) {
;     ...
;             PG8_LDB(B0, 0, 0); PG8_SCHED; PG8_LDA(At, 0, 0); PG8_STAGE(PG8_SA(1, 1), a1 + hstep, voffA);
;             PG8_WAIT_L(8); PG8_BAR; PG8_WAIT_L(0); PG8_MMA(0, 0, At, B0); PG8_BAR; PG8_SCHED;
;             PG8_LDB(B1, 0, 1); PG8_STAGE(PG8_SB(0, 0), b2, voffB);
;             PG8_BAR; PG8_WAIT_L(0); PG8_MMA(0, 1, At, B1); PG8_BAR;
;             PG8_LDA(At, 0, 1); PG8_STAGE(PG8_SA(0, 0), a2, voffA);
;             PG8_BAR; PG8_WAIT_L(0); PG8_MMA(1, 0, At, B0); PG8_BAR; PG8_SCHED;
;             PG8_STAGE(PG8_SB(0, 1), b2 + hstep, voffB);
;             PG8_WAIT_V(6); PG8_BAR; PG8_MMA(1, 1, At, B1); PG8_BAR;
.LBB0_914:
	ds_read_b128 v[128:131], v187
	ds_read_b128 v[132:135], v187 offset:1024
	ds_read_b128 v[136:139], v187 offset:2048
	ds_read_b128 v[140:143], v187 offset:3072
	s_add_u32 s18, s2, 0x100
	s_addc_u32 s19, s3, 0
	s_cmpk_eq_i32 s42, 0x54
	s_cselect_b32 s29, s13, s19
	s_cselect_b32 s28, s12, s18
	s_cselect_b32 s21, s15, s41
	s_cselect_b32 s20, s14, s40
	v_lshl_add_u64 v[184:185], s[2:3], 0, v[160:161]
	s_add_i32 m0, s25, 0xc000
	ds_read_b128 v[144:147], v188
	ds_read_b128 v[148:151], v188 offset:1024
	ds_read_b128 v[168:171], v188 offset:2048
	ds_read_b128 v[172:175], v188 offset:3072
	ds_read_b128 v[176:179], v188 offset:4096
	ds_read_b128 v[180:183], v188 offset:5120
	ds_read_b128 v[190:193], v188 offset:6144
	ds_read_b128 v[194:197], v188 offset:7168
	global_load_lds_dwordx4 v[184:185], off
	s_add_i32 m0, s25, 0xe000
	s_nop 0
	global_load_lds_dwordx4 v162, s[2:3]
	s_waitcnt lgkmcnt(8)
	s_barrier
	s_waitcnt lgkmcnt(0)
	v_mfma_f32_16x16x32_bf16 v[124:127], v[128:131], v[144:147], v[124:127]
	v_mfma_f32_16x16x32_bf16 v[120:123], v[136:139], v[144:147], v[120:123]
	v_mfma_f32_16x16x32_bf16 v[108:111], v[128:131], v[168:171], v[108:111]
	v_mfma_f32_16x16x32_bf16 v[104:107], v[136:139], v[168:171], v[104:107]
	v_mfma_f32_16x16x32_bf16 v[92:95], v[128:131], v[176:179], v[92:95]
	v_mfma_f32_16x16x32_bf16 v[88:91], v[136:139], v[176:179], v[88:91]
	v_mfma_f32_16x16x32_bf16 v[76:79], v[128:131], v[190:193], v[76:79]
	v_mfma_f32_16x16x32_bf16 v[72:75], v[136:139], v[190:193], v[72:75]
	v_mfma_f32_16x16x32_bf16 v[124:127], v[132:135], v[148:151], v[124:127]
	v_mfma_f32_16x16x32_bf16 v[120:123], v[140:143], v[148:151], v[120:123]
	v_mfma_f32_16x16x32_bf16 v[108:111], v[132:135], v[172:175], v[108:111]
	v_mfma_f32_16x16x32_bf16 v[104:107], v[140:143], v[172:175], v[104:107]
	v_mfma_f32_16x16x32_bf16 v[92:95], v[132:135], v[180:183], v[92:95]
	v_mfma_f32_16x16x32_bf16 v[88:91], v[140:143], v[180:183], v[88:91]
	v_mfma_f32_16x16x32_bf16 v[76:79], v[132:135], v[194:197], v[76:79]
	v_mfma_f32_16x16x32_bf16 v[72:75], v[140:143], v[194:197], v[72:75]
	s_barrier
	s_add_i32 s2, s47, s26
	v_lshl_add_u64 v[184:185], s[20:21], 0, v[154:155]
	s_mov_b32 m0, s2
	ds_read_b128 v[198:201], v189
	ds_read_b128 v[202:205], v189 offset:1024
	ds_read_b128 v[210:213], v189 offset:2048
	ds_read_b128 v[214:217], v189 offset:3072
	global_load_lds_dwordx4 v[184:185], off
	v_lshl_add_u64 v[206:207], s[20:21], 0, v[158:159]
	s_add_i32 m0, s2, 0x2000
	s_nop 0
	global_load_lds_dwordx4 v[206:207], off
	s_barrier
	s_waitcnt lgkmcnt(0)
	v_mfma_f32_16x16x32_bf16 v[116:119], v[198:201], v[144:147], v[116:119]
	v_mfma_f32_16x16x32_bf16 v[112:115], v[210:213], v[144:147], v[112:115]
	v_mfma_f32_16x16x32_bf16 v[100:103], v[198:201], v[168:171], v[100:103]
	v_mfma_f32_16x16x32_bf16 v[96:99], v[210:213], v[168:171], v[96:99]
	v_mfma_f32_16x16x32_bf16 v[84:87], v[198:201], v[176:179], v[84:87]
	v_mfma_f32_16x16x32_bf16 v[80:83], v[210:213], v[176:179], v[80:83]
	v_mfma_f32_16x16x32_bf16 v[68:71], v[198:201], v[190:193], v[68:71]
	v_mfma_f32_16x16x32_bf16 v[64:67], v[210:213], v[190:193], v[64:67]
	v_mfma_f32_16x16x32_bf16 v[116:119], v[202:205], v[148:151], v[116:119]
	v_mfma_f32_16x16x32_bf16 v[112:115], v[214:217], v[148:151], v[112:115]
	v_mfma_f32_16x16x32_bf16 v[100:103], v[202:205], v[172:175], v[100:103]
	v_mfma_f32_16x16x32_bf16 v[96:99], v[214:217], v[172:175], v[96:99]
	v_mfma_f32_16x16x32_bf16 v[84:87], v[202:205], v[180:183], v[84:87]
	v_mfma_f32_16x16x32_bf16 v[80:83], v[214:217], v[180:183], v[80:83]
	v_mfma_f32_16x16x32_bf16 v[68:71], v[202:205], v[194:197], v[68:71]
	v_mfma_f32_16x16x32_bf16 v[64:67], v[214:217], v[194:197], v[64:67]
	s_mov_b32 m0, s25
	v_lshl_add_u64 v[218:219], s[28:29], 0, v[152:153]
	s_barrier
	ds_read_b128 v[144:147], v188 offset:16384
	ds_read_b128 v[148:151], v188 offset:17408
	ds_read_b128 v[168:171], v188 offset:18432
	ds_read_b128 v[172:175], v188 offset:19456
	ds_read_b128 v[176:179], v188 offset:20480
	ds_read_b128 v[180:183], v188 offset:21504
	ds_read_b128 v[190:193], v188 offset:22528
	ds_read_b128 v[194:197], v188 offset:23552
	global_load_lds_dwordx4 v[218:219], off
	v_lshl_add_u64 v[220:221], s[28:29], 0, v[156:157]
	s_mov_b32 m0, s30
	s_nop 0
	global_load_lds_dwordx4 v[220:221], off
	s_barrier
	s_waitcnt lgkmcnt(0)
	v_mfma_f32_16x16x32_bf16 v[60:63], v[128:131], v[144:147], v[60:63]
	v_mfma_f32_16x16x32_bf16 v[56:59], v[136:139], v[144:147], v[56:59]
	v_mfma_f32_16x16x32_bf16 v[44:47], v[128:131], v[168:171], v[44:47]
	v_mfma_f32_16x16x32_bf16 v[40:43], v[136:139], v[168:171], v[40:43]
	v_mfma_f32_16x16x32_bf16 v[28:31], v[128:131], v[176:179], v[28:31]
	v_mfma_f32_16x16x32_bf16 v[24:27], v[136:139], v[176:179], v[24:27]
	v_mfma_f32_16x16x32_bf16 v[12:15], v[128:131], v[190:193], v[12:15]
	v_mfma_f32_16x16x32_bf16 v[8:11], v[136:139], v[190:193], v[8:11]
	v_mfma_f32_16x16x32_bf16 v[60:63], v[132:135], v[148:151], v[60:63]
	v_mfma_f32_16x16x32_bf16 v[56:59], v[140:143], v[148:151], v[56:59]
	v_mfma_f32_16x16x32_bf16 v[44:47], v[132:135], v[172:175], v[44:47]
	v_mfma_f32_16x16x32_bf16 v[40:43], v[140:143], v[172:175], v[40:43]
	v_mfma_f32_16x16x32_bf16 v[28:31], v[132:135], v[180:183], v[28:31]
	v_mfma_f32_16x16x32_bf16 v[24:27], v[140:143], v[180:183], v[24:27]
	v_mfma_f32_16x16x32_bf16 v[12:15], v[132:135], v[194:197], v[12:15]
	v_mfma_f32_16x16x32_bf16 v[8:11], v[140:143], v[194:197], v[8:11]
	s_barrier
	s_add_u32 s2, s20, 0x160000
	s_addc_u32 s3, s21, 0
	s_add_i32 s43, s48, s26
	s_mov_b32 m0, s43
	s_nop 0
	global_load_lds_dwordx4 v154, s[2:3]
	s_add_i32 m0, s43, 0x2000
	s_nop 0
	global_load_lds_dwordx4 v158, s[2:3]
	s_waitcnt vmcnt(6)
	s_barrier
; #define PG8_STAGE(bufoff, gbase, voff) do { _Pragma("unroll") for (int _i = 0; _i < 2; ++_i) \
;         __builtin_amdgcn_global_load_lds((const unsigned*)((const char*)(gbase) + (voff)[_i]), (LAS unsigned*)(lds + (bufoff) + ldsw + _i * 8192), 16, 0, 0); } while (0)
; #define PG8_LDA(dst, b, h) do { _Pragma("unroll") for (int m = 0; m < 4; ++m) _Pragma("unroll") for (int k = 0; k < 2; ++k) dst[m][k] = *(const LAS bf16x8*)(lds + PG8_SA(b, h) + aoff + m * 2048 + k * 1024); } while (0)
; #define PG8_LDB(dst, b, h) do { _Pragma("unroll") for (int n = 0; n < 2; ++n) _Pragma("unroll") for (int k = 0; k < 2; ++k) dst[n][k] = *(const LAS bf16x8*)(lds + PG8_SB(b, h) + boff + n * 2048 + k * 1024); } while (0)
; #define PG8_MMA(ai, bj, At, Bt) do { __builtin_amdgcn_s_setprio(1); _Pragma("unroll") for (int m = 0; m < 4; ++m) _Pragma("unroll") for (int n = 0; n < 2; ++n) _Pragma("unroll") for (int k = 0; k < 2; ++k) \
;         acc[ai][bj][m][n] = __builtin_amdgcn_mfma_f32_16x16x32_bf16(Bt[n][k], At[m][k], acc[ai][bj][m][n], 0, 0, 0); __builtin_amdgcn_s_setprio(0); } while (0)
; #define PG8_WAIT_V(n) asm volatile("s_waitcnt vmcnt(" #n ")" ::: "memory")
; #define PG8_WAIT_L(n) asm volatile("s_waitcnt lgkmcnt(" #n ")" ::: "memory")
; #define PG8_BAR __builtin_amdgcn_s_barrier()
; #define PG8_SCHED __builtin_amdgcn_sched_barrier(0)
; template <class Epi, bool KS0 = false>
; __device__ __forceinline__ void gemm_phase(const int WID, LAS unsigned char* lds, const Gemm g, const StaticOrder& S, const Epi& E) {
;     ...
;             PG8_WAIT_V(6); PG8_BAR; PG8_MMA(1, 1, At, B1); PG8_BAR;
;             PG8_LDB(B0, 1, 0); PG8_SCHED; PG8_LDA(At, 1, 0); PG8_STAGE(PG8_SA(0, 1), a2 + hstep, voffA);
;             PG8_WAIT_L(8); PG8_BAR; PG8_WAIT_L(0); PG8_MMA(0, 0, At, B0); PG8_BAR; PG8_SCHED;
;             PG8_LDB(B1, 1, 1); PG8_STAGE(PG8_SB(1, 0), b3, voffB);
;             PG8_BAR; PG8_WAIT_L(0); PG8_MMA(0, 1, At, B1); PG8_BAR;
;             PG8_LDA(At, 1, 1); PG8_STAGE(PG8_SA(1, 0), a3, voffA);
	v_mfma_f32_16x16x32_bf16 v[52:55], v[198:201], v[144:147], v[52:55]
	v_mfma_f32_16x16x32_bf16 v[48:51], v[210:213], v[144:147], v[48:51]
	v_mfma_f32_16x16x32_bf16 v[36:39], v[198:201], v[168:171], v[36:39]
	v_mfma_f32_16x16x32_bf16 v[32:35], v[210:213], v[168:171], v[32:35]
	v_mfma_f32_16x16x32_bf16 v[20:23], v[198:201], v[176:179], v[20:23]
	v_mfma_f32_16x16x32_bf16 v[16:19], v[210:213], v[176:179], v[16:19]
	v_mfma_f32_16x16x32_bf16 v[4:7], v[198:201], v[190:193], v[4:7]
	v_mfma_f32_16x16x32_bf16 v[0:3], v[210:213], v[190:193], v[0:3]
	v_mfma_f32_16x16x32_bf16 v[52:55], v[202:205], v[148:151], v[52:55]
	v_mfma_f32_16x16x32_bf16 v[48:51], v[214:217], v[148:151], v[48:51]
	v_mfma_f32_16x16x32_bf16 v[36:39], v[202:205], v[172:175], v[36:39]
	v_mfma_f32_16x16x32_bf16 v[32:35], v[214:217], v[172:175], v[32:35]
	v_mfma_f32_16x16x32_bf16 v[20:23], v[202:205], v[180:183], v[20:23]
	v_mfma_f32_16x16x32_bf16 v[16:19], v[214:217], v[180:183], v[16:19]
	v_mfma_f32_16x16x32_bf16 v[4:7], v[202:205], v[194:197], v[4:7]
	v_mfma_f32_16x16x32_bf16 v[0:3], v[214:217], v[194:197], v[0:3]
	s_add_i32 s43, 0, 0x18000
	v_add_u32_e32 v140, s43, v186
	s_barrier
	ds_read_b128 v[128:131], v140
	ds_read_b128 v[132:135], v140 offset:1024
	ds_read_b128 v[136:139], v140 offset:2048
	ds_read_b128 v[140:143], v140 offset:3072
	s_add_u32 s2, s28, 0x160000
	s_addc_u32 s3, s29, 0
	s_mov_b32 m0, s31
	v_lshl_add_u64 v[198:199], s[2:3], 0, v[152:153]
	ds_read_b128 v[144:147], v188 offset:32768
	ds_read_b128 v[148:151], v188 offset:33792
	ds_read_b128 v[168:171], v188 offset:34816
	ds_read_b128 v[172:175], v188 offset:35840
	ds_read_b128 v[176:179], v188 offset:36864
	ds_read_b128 v[180:183], v188 offset:37888
	ds_read_b128 v[190:193], v188 offset:38912
	ds_read_b128 v[194:197], v188 offset:39936
	global_load_lds_dwordx4 v[198:199], off
	s_mov_b32 m0, s44
	s_nop 0
	global_load_lds_dwordx4 v156, s[2:3]
	s_waitcnt lgkmcnt(8)
	s_barrier
	s_waitcnt lgkmcnt(0)
	v_mfma_f32_16x16x32_bf16 v[124:127], v[128:131], v[144:147], v[124:127]
	v_mfma_f32_16x16x32_bf16 v[120:123], v[136:139], v[144:147], v[120:123]
	v_mfma_f32_16x16x32_bf16 v[108:111], v[128:131], v[168:171], v[108:111]
	v_mfma_f32_16x16x32_bf16 v[104:107], v[136:139], v[168:171], v[104:107]
	v_mfma_f32_16x16x32_bf16 v[92:95], v[128:131], v[176:179], v[92:95]
	v_mfma_f32_16x16x32_bf16 v[88:91], v[136:139], v[176:179], v[88:91]
	v_mfma_f32_16x16x32_bf16 v[76:79], v[128:131], v[190:193], v[76:79]
	v_mfma_f32_16x16x32_bf16 v[72:75], v[136:139], v[190:193], v[72:75]
	v_mfma_f32_16x16x32_bf16 v[124:127], v[132:135], v[148:151], v[124:127]
	v_mfma_f32_16x16x32_bf16 v[120:123], v[140:143], v[148:151], v[120:123]
	v_mfma_f32_16x16x32_bf16 v[108:111], v[132:135], v[172:175], v[108:111]
	v_mfma_f32_16x16x32_bf16 v[104:107], v[140:143], v[172:175], v[104:107]
	v_mfma_f32_16x16x32_bf16 v[92:95], v[132:135], v[180:183], v[92:95]
	v_mfma_f32_16x16x32_bf16 v[88:91], v[140:143], v[180:183], v[88:91]
	v_mfma_f32_16x16x32_bf16 v[76:79], v[132:135], v[194:197], v[76:79]
	v_mfma_f32_16x16x32_bf16 v[72:75], v[140:143], v[194:197], v[72:75]
	s_barrier
	s_add_i32 s28, 0, 0x1c000
	s_add_i32 s2, s43, s26
	v_add_u32_e32 v208, s28, v186
	v_lshl_add_u64 v[184:185], v[184:185], 0, s[10:11]
	s_mov_b32 m0, s2
	ds_read_b128 v[198:201], v208
	ds_read_b128 v[202:205], v208 offset:1024
	ds_read_b128 v[210:213], v208 offset:2048
	ds_read_b128 v[214:217], v208 offset:3072
	global_load_lds_dwordx4 v[184:185], off
	v_lshl_add_u64 v[184:185], v[206:207], 0, s[10:11]
	s_add_i32 m0, s2, 0x2000
	s_nop 0
	global_load_lds_dwordx4 v[184:185], off
	s_barrier
	s_waitcnt lgkmcnt(0)
	v_mfma_f32_16x16x32_bf16 v[116:119], v[198:201], v[144:147], v[116:119]
	v_mfma_f32_16x16x32_bf16 v[112:115], v[210:213], v[144:147], v[112:115]
	v_mfma_f32_16x16x32_bf16 v[100:103], v[198:201], v[168:171], v[100:103]
	v_mfma_f32_16x16x32_bf16 v[96:99], v[210:213], v[168:171], v[96:99]
	v_mfma_f32_16x16x32_bf16 v[84:87], v[198:201], v[176:179], v[84:87]
	v_mfma_f32_16x16x32_bf16 v[80:83], v[210:213], v[176:179], v[80:83]
	v_mfma_f32_16x16x32_bf16 v[68:71], v[198:201], v[190:193], v[68:71]
	v_mfma_f32_16x16x32_bf16 v[64:67], v[210:213], v[190:193], v[64:67]
	v_mfma_f32_16x16x32_bf16 v[116:119], v[202:205], v[148:151], v[116:119]
	v_mfma_f32_16x16x32_bf16 v[112:115], v[214:217], v[148:151], v[112:115]
	v_mfma_f32_16x16x32_bf16 v[100:103], v[202:205], v[172:175], v[100:103]
	v_mfma_f32_16x16x32_bf16 v[96:99], v[214:217], v[172:175], v[96:99]
	v_mfma_f32_16x16x32_bf16 v[84:87], v[202:205], v[180:183], v[84:87]
	v_mfma_f32_16x16x32_bf16 v[80:83], v[214:217], v[180:183], v[80:83]
	v_mfma_f32_16x16x32_bf16 v[68:71], v[202:205], v[194:197], v[68:71]
	v_mfma_f32_16x16x32_bf16 v[64:67], v[214:217], v[194:197], v[64:67]
	s_mov_b32 m0, s45
	v_lshl_add_u64 v[184:185], v[218:219], 0, s[10:11]
	s_barrier
	ds_read_b128 v[144:147], v188 offset:49152
	ds_read_b128 v[148:151], v188 offset:50176
	ds_read_b128 v[168:171], v188 offset:51200
	ds_read_b128 v[172:175], v188 offset:52224
	ds_read_b128 v[176:179], v188 offset:53248
	ds_read_b128 v[180:183], v188 offset:54272
	ds_read_b128 v[190:193], v188 offset:55296
	ds_read_b128 v[194:197], v188 offset:56320
	global_load_lds_dwordx4 v[184:185], off
	v_lshl_add_u64 v[184:185], v[220:221], 0, s[10:11]
	s_mov_b32 m0, s46
	s_nop 0
	global_load_lds_dwordx4 v[184:185], off
	s_barrier
; #define PG8_STAGE(bufoff, gbase, voff) do { _Pragma("unroll") for (int _i = 0; _i < 2; ++_i) \
;         __builtin_amdgcn_global_load_lds((const unsigned*)((const char*)(gbase) + (voff)[_i]), (LAS unsigned*)(lds + (bufoff) + ldsw + _i * 8192), 16, 0, 0); } while (0)
; #define PG8_MMA(ai, bj, At, Bt) do { __builtin_amdgcn_s_setprio(1); _Pragma("unroll") for (int m = 0; m < 4; ++m) _Pragma("unroll") for (int n = 0; n < 2; ++n) _Pragma("unroll") for (int k = 0; k < 2; ++k) \
;         acc[ai][bj][m][n] = __builtin_amdgcn_mfma_f32_16x16x32_bf16(Bt[n][k], At[m][k], acc[ai][bj][m][n], 0, 0, 0); __builtin_amdgcn_s_setprio(0); } while (0)
; #define PG8_WAIT_V(n) asm volatile("s_waitcnt vmcnt(" #n ")" ::: "memory")
; #define PG8_WAIT_L(n) asm volatile("s_waitcnt lgkmcnt(" #n ")" ::: "memory")
; #define PG8_BAR __builtin_amdgcn_s_barrier()
; #define PG8_SCHED __builtin_amdgcn_sched_barrier(0)
; template <class Epi, bool KS0 = false>
; __device__ __forceinline__ void gemm_phase(const int WID, LAS unsigned char* lds, const Gemm g, const StaticOrder& S, const Epi& E) {
;     ...
;             PG8_BAR; PG8_WAIT_L(0); PG8_MMA(1, 0, At, B0); PG8_BAR; PG8_SCHED;
;             PG8_STAGE(PG8_SB(1, 1), b3 + hstep, voffB);
;             PG8_WAIT_V(6); PG8_BAR; PG8_MMA(1, 1, At, B1); PG8_BAR;
;         }
	s_waitcnt lgkmcnt(0)
	v_mfma_f32_16x16x32_bf16 v[60:63], v[128:131], v[144:147], v[60:63]
	v_mfma_f32_16x16x32_bf16 v[56:59], v[136:139], v[144:147], v[56:59]
	v_mfma_f32_16x16x32_bf16 v[44:47], v[128:131], v[168:171], v[44:47]
	v_mfma_f32_16x16x32_bf16 v[40:43], v[136:139], v[168:171], v[40:43]
	v_mfma_f32_16x16x32_bf16 v[28:31], v[128:131], v[176:179], v[28:31]
	v_mfma_f32_16x16x32_bf16 v[24:27], v[136:139], v[176:179], v[24:27]
	v_mfma_f32_16x16x32_bf16 v[12:15], v[128:131], v[190:193], v[12:15]
	v_mfma_f32_16x16x32_bf16 v[8:11], v[136:139], v[190:193], v[8:11]
	v_mfma_f32_16x16x32_bf16 v[60:63], v[132:135], v[148:151], v[60:63]
	v_mfma_f32_16x16x32_bf16 v[56:59], v[140:143], v[148:151], v[56:59]
	v_mfma_f32_16x16x32_bf16 v[44:47], v[132:135], v[172:175], v[44:47]
	v_mfma_f32_16x16x32_bf16 v[40:43], v[140:143], v[172:175], v[40:43]
	v_mfma_f32_16x16x32_bf16 v[28:31], v[132:135], v[180:183], v[28:31]
	v_mfma_f32_16x16x32_bf16 v[24:27], v[140:143], v[180:183], v[24:27]
	v_mfma_f32_16x16x32_bf16 v[12:15], v[132:135], v[194:197], v[12:15]
	v_mfma_f32_16x16x32_bf16 v[8:11], v[140:143], v[194:197], v[8:11]
	s_barrier
	s_add_u32 s2, s20, 0x160080
	s_addc_u32 s3, s21, 0
	s_add_i32 s20, s28, s26
	s_mov_b32 m0, s20
	s_nop 0
	global_load_lds_dwordx4 v154, s[2:3]
	s_add_i32 m0, s20, 0x2000
	s_nop 0
	global_load_lds_dwordx4 v158, s[2:3]
	s_waitcnt vmcnt(6)
	s_barrier
	v_mfma_f32_16x16x32_bf16 v[52:55], v[198:201], v[144:147], v[52:55]
	v_mfma_f32_16x16x32_bf16 v[48:51], v[210:213], v[144:147], v[48:51]
	v_mfma_f32_16x16x32_bf16 v[36:39], v[198:201], v[168:171], v[36:39]
	v_mfma_f32_16x16x32_bf16 v[32:35], v[210:213], v[168:171], v[32:35]
	v_mfma_f32_16x16x32_bf16 v[20:23], v[198:201], v[176:179], v[20:23]
	v_mfma_f32_16x16x32_bf16 v[16:19], v[210:213], v[176:179], v[16:19]
	v_mfma_f32_16x16x32_bf16 v[4:7], v[198:201], v[190:193], v[4:7]
	v_mfma_f32_16x16x32_bf16 v[0:3], v[210:213], v[190:193], v[0:3]
	v_mfma_f32_16x16x32_bf16 v[52:55], v[202:205], v[148:151], v[52:55]
	v_mfma_f32_16x16x32_bf16 v[48:51], v[214:217], v[148:151], v[48:51]
	v_mfma_f32_16x16x32_bf16 v[36:39], v[202:205], v[172:175], v[36:39]
	v_mfma_f32_16x16x32_bf16 v[32:35], v[214:217], v[172:175], v[32:35]
	v_mfma_f32_16x16x32_bf16 v[20:23], v[202:205], v[180:183], v[20:23]
	v_mfma_f32_16x16x32_bf16 v[16:19], v[214:217], v[180:183], v[16:19]
	v_mfma_f32_16x16x32_bf16 v[4:7], v[202:205], v[194:197], v[4:7]
	v_mfma_f32_16x16x32_bf16 v[0:3], v[214:217], v[194:197], v[0:3]
	s_add_i32 s42, s42, 2
	s_add_u32 s40, s40, 0x100
	s_addc_u32 s41, s41, 0
	s_cmpk_gt_u32 s42, 0x55
	s_mov_b64 s[2:3], s[18:19]
	s_barrier
	s_cbranch_scc0 .LBB0_914
; __device__ __forceinline__ unsigned cvt_pk_bf16(float lo, float hi) { unsigned r; asm volatile("v_cvt_pk_bf16_f32 %0, %1, %2" : "=v"(r) : "v"(lo), "v"(hi)); return r; }
; __device__ __forceinline__ float bflo(unsigned w) { return __uint_as_float(w << 16); }
; __device__ __forceinline__ float bfhi(unsigned w) { return __uint_as_float(w & 0xffff0000u); }
;     __device__ __forceinline__ void operator()(f32x4 (&acc)[2][2][4][2], const Unit& u, int wr, int wc, int fr, int fq) const {
;         const int row0 = u.pm * BM + wr * 64 + fr, col0 = u.pn * BM + wc * 32 + 8 * fq;
; #pragma unroll
;         for (int ai = 0; ai < 2; ++ai) {
;             f32x4 r[4][2][2];
; #pragma unroll
;             for (int m = 0; m < 4; ++m)
; #pragma unroll
;                 for (int bj = 0; bj < 2; ++bj) { const size_t o = (size_t)(row0 + ai * HALF + m * 16) * DM + col0 + bj * HALF;
;                     if (RB) { const u32x4 w = *(const u32x4*)((const bf16_t*)res + o); r[m][bj][0] = (f32x4){bflo(w.x), bfhi(w.x), bflo(w.y), bfhi(w.y)}; r[m][bj][1] = (f32x4){bflo(w.z), bfhi(w.z), bflo(w.w), bfhi(w.w)}; }
;                     else { r[m][bj][0] = __builtin_nontemporal_load((const f32x4*)((const float*)res + o)); r[m][bj][1] = __builtin_nontemporal_load((const f32x4*)((const float*)res + o + 4)); } }
; #pragma unroll
;             for (int m = 0; m < 4; ++m) { const int row = row0 + ai * HALF + m * 16; const size_t off = (size_t)row * DM + col0; float s = 0.f;
; #pragma unroll
;                 for (int bj = 0; bj < 2; ++bj) { const f32x4 v0 = acc[ai][bj][m][0] + r[m][bj][0], v1 = acc[ai][bj][m][1] + r[m][bj][1];
;                     u32x4 w; w.x = cvt_pk_bf16(v0[0], v0[1]); w.y = cvt_pk_bf16(v0[2], v0[3]); w.z = cvt_pk_bf16(v1[0], v1[1]); w.w = cvt_pk_bf16(v1[2], v1[3]);
;                     *(u32x4*)(outb + off + bj * HALF) = w;
;                     s += ((v0[0] * v0[0] + v0[1] * v0[1]) + (v0[2] * v0[2] + v0[3] * v0[3])) + ((v1[0] * v1[0] + v1[1] * v1[1]) + (v1[2] * v1[2] + v1[3] * v1[3])); }
;                 s += __shfl_xor(s, 16); s += __shfl_xor(s, 32);
;                 if (fq == 0) ssq[(size_t)row * 32 + u.pn * 4 + wc] = s; }
;             asm volatile("" ::: "memory"); }
;     }
	v_mbcnt_lo_u32_b32 v128, -1, 0
	v_mbcnt_hi_u32_b32 v128, -1, v128
	s_lshl_b32 s2, s52, 8
	v_ashrrev_i32_e32 v129, 4, v128
	v_and_b32_e32 v128, 15, v128
	s_add_i32 s2, s2, s22
	v_readlane_b32 s3, v254, 19
	v_add_u32_e32 v172, s2, v128
	s_lshl_b32 s2, s8, 8
	s_or_b32 s2, s2, s3
	v_lshl_add_u32 v168, v129, 3, s2
	v_ashrrev_i32_e32 v169, 31, v168
	v_lshlrev_b64 v[190:191], 1, v[168:169]
	v_ashrrev_i32_e32 v173, 31, v172
	v_lshl_add_u64 v[170:171], s[6:7], 0, v[190:191]
	v_lshlrev_b64 v[192:193], 12, v[172:173]
	v_lshl_add_u64 v[132:133], v[170:171], 0, v[192:193]
	v_cmp_eq_u32_e32 vcc, 0, v129
	global_load_dwordx4 v[128:131], v[132:133], off
	v_add_u32_e32 v182, 16, v172
	v_ashrrev_i32_e32 v183, 31, v182
	v_add_u32_e32 v178, 32, v172
	v_lshlrev_b64 v[184:185], 12, v[182:183]
	v_ashrrev_i32_e32 v179, 31, v178
	v_add_u32_e32 v174, 48, v172
	v_lshlrev_b64 v[180:181], 12, v[178:179]
	v_ashrrev_i32_e32 v175, 31, v174
	v_lshlrev_b64 v[176:177], 12, v[174:175]
	v_lshl_add_u64 v[192:193], s[6:7], 0, v[192:193]
	v_lshl_add_u64 v[190:191], v[192:193], 0, v[190:191]
	s_lshl_b32 s18, s8, 2
	s_ashr_i32 s19, s18, 31
	s_waitcnt vmcnt(0)
	v_lshlrev_b32_e32 v194, 16, v128
	v_and_b32_e32 v195, 0xffff0000, v128
	v_lshlrev_b32_e32 v196, 16, v129
	v_and_b32_e32 v197, 0xffff0000, v129
	v_lshlrev_b32_e32 v198, 16, v130
	v_and_b32_e32 v199, 0xffff0000, v130
	v_lshlrev_b32_e32 v200, 16, v131
	v_and_b32_e32 v201, 0xffff0000, v131
	global_load_dwordx4 v[128:131], v[132:133], off offset:256
	v_pk_add_f32 v[126:127], v[126:127], v[196:197]
	v_pk_add_f32 v[124:125], v[124:125], v[194:195]
	v_pk_add_f32 v[196:197], v[120:121], v[198:199]
	v_pk_add_f32 v[194:195], v[122:123], v[200:201]
	s_waitcnt vmcnt(0)
	v_lshlrev_b32_e32 v202, 16, v128
	v_and_b32_e32 v203, 0xffff0000, v128
	v_lshlrev_b32_e32 v204, 16, v129
	v_and_b32_e32 v205, 0xffff0000, v129
	v_lshl_add_u64 v[128:129], v[170:171], 0, v[184:185]
	global_load_dwordx4 v[148:151], v[128:129], off
	global_load_dwordx4 v[144:147], v[128:129], off offset:256
	v_lshl_add_u64 v[128:129], v[170:171], 0, v[180:181]
	global_load_dwordx4 v[140:143], v[128:129], off
	global_load_dwordx4 v[136:139], v[128:129], off offset:256
	v_lshl_add_u64 v[128:129], v[170:171], 0, v[176:177]
	v_lshlrev_b32_e32 v206, 16, v130
	v_and_b32_e32 v207, 0xffff0000, v130
	v_lshlrev_b32_e32 v210, 16, v131
	v_and_b32_e32 v211, 0xffff0000, v131
	global_load_dwordx4 v[132:135], v[128:129], off
	s_nop 0
	global_load_dwordx4 v[128:131], v[128:129], off offset:256
	v_cvt_pk_bf16_f32 v120, v124, v125
	v_cvt_pk_bf16_f32 v121, v126, v127
	v_cvt_pk_bf16_f32 v122, v196, v197
	v_cvt_pk_bf16_f32 v123, v194, v195
	global_store_dwordx4 v[190:191], v[120:123], off
	v_pk_add_f32 v[118:119], v[118:119], v[204:205]
	v_pk_add_f32 v[116:117], v[116:117], v[202:203]
	v_mul_f32_e32 v120, v125, v125
	v_mul_f32_e32 v121, v127, v127
	v_fmac_f32_e32 v120, v124, v124
	v_fmac_f32_e32 v121, v126, v126
	v_add_f32_e32 v120, v120, v121
	v_mul_f32_e32 v121, v197, v197
	v_mul_f32_e32 v122, v195, v195
	v_fmac_f32_e32 v121, v196, v196
	v_fmac_f32_e32 v122, v194, v194
	v_add_f32_e32 v121, v121, v122
	v_pk_add_f32 v[122:123], v[112:113], v[206:207]
	v_cvt_pk_bf16_f32 v112, v116, v117
	v_cvt_pk_bf16_f32 v113, v118, v119
	v_add_f32_e32 v124, v120, v121
	v_pk_add_f32 v[120:121], v[114:115], v[210:211]
	v_cvt_pk_bf16_f32 v114, v122, v123
	s_nop 0
	v_cvt_pk_bf16_f32 v115, v120, v121
	global_store_dwordx4 v[190:191], v[112:115], off offset:256
	s_nop 1
	v_mul_f32_e32 v112, v117, v117
	v_mul_f32_e32 v113, v119, v119
	v_fmac_f32_e32 v112, v116, v116
	v_fmac_f32_e32 v113, v118, v118
	v_add_f32_e32 v112, v112, v113
	v_mul_f32_e32 v113, v123, v123
	v_mul_f32_e32 v114, v121, v121
	v_fmac_f32_e32 v113, v122, v122
	v_fmac_f32_e32 v114, v120, v120
	v_add_f32_e32 v113, v113, v114
	v_add_f32_e32 v112, v112, v113
	v_and_b32_e32 v114, 64, v209
	v_add_f32_e32 v113, v124, v112
	v_xor_b32_e32 v112, 16, v209
	v_add_u32_e32 v115, 64, v114
	v_cmp_lt_i32_e64 s[2:3], v112, v115
	s_nop 1
	v_cndmask_b32_e64 v112, v209, v112, s[2:3]
	v_lshlrev_b32_e32 v112, 2, v112
	ds_bpermute_b32 v114, v112, v113
	s_waitcnt lgkmcnt(0)
	v_add_f32_e32 v114, v113, v114
	v_xor_b32_e32 v113, 32, v209
	v_cmp_lt_i32_e64 s[2:3], v113, v115
	s_nop 1
	v_cndmask_b32_e64 v113, v209, v113, s[2:3]
	v_lshlrev_b32_e32 v113, 2, v113
	ds_bpermute_b32 v115, v113, v114
	s_and_saveexec_b64 s[2:3], vcc
	s_cbranch_execz .LBB0_917
	v_lshlrev_b64 v[116:117], 7, v[172:173]
	v_lshl_add_u64 v[116:117], s[16:17], 0, v[116:117]
	v_lshl_add_u64 v[116:117], s[18:19], 2, v[116:117]
	s_lshl_b32 s8, s27, 2
	v_lshl_add_u64 v[116:117], v[116:117], 0, s[8:9]
	s_waitcnt lgkmcnt(0)
	v_add_f32_e32 v114, v114, v115
	global_store_dword v[116:117], v114, off

; #define PG8_STAGE(bufoff, gbase, voff) do { _Pragma("unroll") for (int _i = 0; _i < 2; ++_i) \
;         __builtin_amdgcn_global_load_lds((const unsigned*)((const char*)(gbase) + (voff)[_i]), (LAS unsigned*)(lds + (bufoff) + ldsw + _i * 8192), 16, 0, 0); } while (0)
; #define PG8_LDA(dst, b, h) do { _Pragma("unroll") for (int m = 0; m < 4; ++m) _Pragma("unroll") for (int k = 0; k < 2; ++k) dst[m][k] = *(const LAS bf16x8*)(lds + PG8_SA(b, h) + aoff + m * 2048 + k * 1024); } while (0)
; #define PG8_LDB(dst, b, h) do { _Pragma("unroll") for (int n = 0; n < 2; ++n) _Pragma("unroll") for (int k = 0; k < 2; ++k) dst[n][k] = *(const LAS bf16x8*)(lds + PG8_SB(b, h) + boff + n * 2048 + k * 1024); } while (0)
; #define PG8_MMA(ai, bj, At, Bt) do { __builtin_amdgcn_s_setprio(1); _Pragma("unroll") for (int m = 0; m < 4; ++m) _Pragma("unroll") for (int n = 0; n < 2; ++n) _Pragma("unroll") for (int k = 0; k < 2; ++k) \
;         acc[ai][bj][m][n] = __builtin_amdgcn_mfma_f32_16x16x32_bf16(Bt[n][k], At[m][k], acc[ai][bj][m][n], 0, 0, 0); __builtin_amdgcn_s_setprio(0); } while (0)
; #define PG8_WAIT_V(n) asm volatile("s_waitcnt vmcnt(" #n ")" ::: "memory")
; #define PG8_WAIT_L(n) asm volatile("s_waitcnt lgkmcnt(" #n ")" ::: "memory")
; #define PG8_BAR __builtin_amdgcn_s_barrier()
; #define PG8_SCHED __builtin_amdgcn_sched_barrier(0)
; template <class Epi, bool KS0 = false>
; __device__ __forceinline__ void gemm_phase(const int WID, LAS unsigned char* lds, const Gemm g, const StaticOrder& S, const Epi& E) {
;     ...
;             PG8_LDB(B0, 0, 0); PG8_SCHED; PG8_LDA(At, 0, 0); PG8_STAGE(PG8_SA(1, 1), a1 + hstep, voffA);
;             PG8_WAIT_L(8); PG8_BAR; PG8_WAIT_L(0); PG8_MMA(0, 0, At, B0); PG8_BAR; PG8_SCHED;
;             PG8_LDB(B1, 0, 1); PG8_STAGE(PG8_SB(0, 0), b2, voffB);
;             PG8_BAR; PG8_WAIT_L(0); PG8_MMA(0, 1, At, B1); PG8_BAR;
;             PG8_LDA(At, 0, 1); PG8_STAGE(PG8_SA(0, 0), a2, voffA);
;             PG8_BAR; PG8_WAIT_L(0); PG8_MMA(1, 0, At, B0); PG8_BAR; PG8_SCHED;
;             PG8_STAGE(PG8_SB(0, 1), b2 + hstep, voffB);
;             PG8_WAIT_V(6); PG8_BAR; PG8_MMA(1, 1, At, B1); PG8_BAR;
.LBB0_1006:
	ds_read_b128 v[104:107], v246
	ds_read_b128 v[108:111], v246 offset:1024
	ds_read_b128 v[112:115], v246 offset:2048
	ds_read_b128 v[120:123], v246 offset:3072
	s_add_u32 s10, s8, 0xfff80080
	s_addc_u32 s11, s9, -1
	s_cmp_eq_u32 s43, 28
	s_cselect_b32 s13, s3, s11
	s_cselect_b32 s12, s14, s10
	s_cselect_b32 s11, s15, s41
	s_cselect_b32 s10, s36, s37
	v_lshl_add_u64 v[176:177], s[8:9], 0, v[200:201]
	s_add_i32 m0, s18, 0xc000
	ds_read_b128 v[136:139], v247
	ds_read_b128 v[144:147], v247 offset:1024
	ds_read_b128 v[148:151], v247 offset:2048
	ds_read_b128 v[156:159], v247 offset:3072
	ds_read_b128 v[160:163], v247 offset:4096
	ds_read_b128 v[164:167], v247 offset:5120
	ds_read_b128 v[168:171], v247 offset:6144
	ds_read_b128 v[172:175], v247 offset:7168
	global_load_lds_dwordx4 v[176:177], off
	s_add_i32 m0, s18, 0xe000
	s_nop 0
	global_load_lds_dwordx4 v202, s[8:9]
	s_waitcnt lgkmcnt(8)
	s_barrier
	s_waitcnt lgkmcnt(0)
	v_mfma_f32_16x16x32_bf16 v[152:155], v[104:107], v[136:139], v[152:155]
	v_mfma_f32_16x16x32_bf16 v[140:143], v[112:115], v[136:139], v[140:143]
	v_mfma_f32_16x16x32_bf16 v[124:127], v[104:107], v[148:151], v[124:127]
	v_mfma_f32_16x16x32_bf16 v[116:119], v[112:115], v[148:151], v[116:119]
	v_mfma_f32_16x16x32_bf16 v[92:95], v[104:107], v[160:163], v[92:95]
	v_mfma_f32_16x16x32_bf16 v[88:91], v[112:115], v[160:163], v[88:91]
	v_mfma_f32_16x16x32_bf16 v[76:79], v[104:107], v[168:171], v[76:79]
	v_mfma_f32_16x16x32_bf16 v[72:75], v[112:115], v[168:171], v[72:75]
	v_mfma_f32_16x16x32_bf16 v[152:155], v[108:111], v[144:147], v[152:155]
	v_mfma_f32_16x16x32_bf16 v[140:143], v[120:123], v[144:147], v[140:143]
	v_mfma_f32_16x16x32_bf16 v[124:127], v[108:111], v[156:159], v[124:127]
	v_mfma_f32_16x16x32_bf16 v[116:119], v[120:123], v[156:159], v[116:119]
	v_mfma_f32_16x16x32_bf16 v[92:95], v[108:111], v[164:167], v[92:95]
	v_mfma_f32_16x16x32_bf16 v[88:91], v[120:123], v[164:167], v[88:91]
	v_mfma_f32_16x16x32_bf16 v[76:79], v[108:111], v[172:175], v[76:79]
	v_mfma_f32_16x16x32_bf16 v[72:75], v[120:123], v[172:175], v[72:75]
	s_barrier
	s_add_i32 s48, s50, s26
	v_lshl_add_u64 v[210:211], s[10:11], 0, v[194:195]
	s_mov_b32 m0, s48
	ds_read_b128 v[176:179], v248
	ds_read_b128 v[180:183], v248 offset:1024
	ds_read_b128 v[184:187], v248 offset:2048
	ds_read_b128 v[188:191], v248 offset:3072
	global_load_lds_dwordx4 v[210:211], off
	v_lshl_add_u64 v[212:213], s[10:11], 0, v[198:199]
	s_add_i32 m0, s48, 0x2000
	s_nop 0
	global_load_lds_dwordx4 v[212:213], off
	s_barrier
	s_waitcnt lgkmcnt(0)
	v_mfma_f32_16x16x32_bf16 v[132:135], v[176:179], v[136:139], v[132:135]
	v_mfma_f32_16x16x32_bf16 v[128:131], v[184:187], v[136:139], v[128:131]
	v_mfma_f32_16x16x32_bf16 v[100:103], v[176:179], v[148:151], v[100:103]
	v_mfma_f32_16x16x32_bf16 v[96:99], v[184:187], v[148:151], v[96:99]
	v_mfma_f32_16x16x32_bf16 v[84:87], v[176:179], v[160:163], v[84:87]
	v_mfma_f32_16x16x32_bf16 v[80:83], v[184:187], v[160:163], v[80:83]
	v_mfma_f32_16x16x32_bf16 v[68:71], v[176:179], v[168:171], v[68:71]
	v_mfma_f32_16x16x32_bf16 v[64:67], v[184:187], v[168:171], v[64:67]
	v_mfma_f32_16x16x32_bf16 v[132:135], v[180:183], v[144:147], v[132:135]
	v_mfma_f32_16x16x32_bf16 v[128:131], v[188:191], v[144:147], v[128:131]
	v_mfma_f32_16x16x32_bf16 v[100:103], v[180:183], v[156:159], v[100:103]
	v_mfma_f32_16x16x32_bf16 v[96:99], v[188:191], v[156:159], v[96:99]
	v_mfma_f32_16x16x32_bf16 v[84:87], v[180:183], v[164:167], v[84:87]
	v_mfma_f32_16x16x32_bf16 v[80:83], v[188:191], v[164:167], v[80:83]
	v_mfma_f32_16x16x32_bf16 v[68:71], v[180:183], v[172:175], v[68:71]
	v_mfma_f32_16x16x32_bf16 v[64:67], v[188:191], v[172:175], v[64:67]
	s_mov_b32 m0, s18
	v_lshl_add_u64 v[214:215], s[12:13], 0, v[192:193]
	s_barrier
	ds_read_b128 v[136:139], v247 offset:16384
	ds_read_b128 v[144:147], v247 offset:17408
	ds_read_b128 v[148:151], v247 offset:18432
	ds_read_b128 v[156:159], v247 offset:19456
	ds_read_b128 v[160:163], v247 offset:20480
	ds_read_b128 v[164:167], v247 offset:21504
	ds_read_b128 v[168:171], v247 offset:22528
	ds_read_b128 v[172:175], v247 offset:23552
	global_load_lds_dwordx4 v[214:215], off
	v_lshl_add_u64 v[216:217], s[12:13], 0, v[196:197]
	s_mov_b32 m0, s19
	s_nop 0
	global_load_lds_dwordx4 v[216:217], off
	s_barrier
	s_waitcnt lgkmcnt(0)
	v_mfma_f32_16x16x32_bf16 v[60:63], v[104:107], v[136:139], v[60:63]
	v_mfma_f32_16x16x32_bf16 v[56:59], v[112:115], v[136:139], v[56:59]
	v_mfma_f32_16x16x32_bf16 v[44:47], v[104:107], v[148:151], v[44:47]
	v_mfma_f32_16x16x32_bf16 v[40:43], v[112:115], v[148:151], v[40:43]
	v_mfma_f32_16x16x32_bf16 v[28:31], v[104:107], v[160:163], v[28:31]
	v_mfma_f32_16x16x32_bf16 v[24:27], v[112:115], v[160:163], v[24:27]
	v_mfma_f32_16x16x32_bf16 v[12:15], v[104:107], v[168:171], v[12:15]
	v_mfma_f32_16x16x32_bf16 v[8:11], v[112:115], v[168:171], v[8:11]
	v_mfma_f32_16x16x32_bf16 v[60:63], v[108:111], v[144:147], v[60:63]
	v_mfma_f32_16x16x32_bf16 v[56:59], v[120:123], v[144:147], v[56:59]
	v_mfma_f32_16x16x32_bf16 v[44:47], v[108:111], v[156:159], v[44:47]
	v_mfma_f32_16x16x32_bf16 v[40:43], v[120:123], v[156:159], v[40:43]
	v_mfma_f32_16x16x32_bf16 v[28:31], v[108:111], v[164:167], v[28:31]
	v_mfma_f32_16x16x32_bf16 v[24:27], v[120:123], v[164:167], v[24:27]
	v_mfma_f32_16x16x32_bf16 v[12:15], v[108:111], v[172:175], v[12:15]
	v_mfma_f32_16x16x32_bf16 v[8:11], v[120:123], v[172:175], v[8:11]
	s_barrier
	s_add_u32 s48, s10, 0x80000
	s_addc_u32 s49, s11, 0
	s_add_i32 s54, s51, s26
	s_mov_b32 m0, s54
	s_nop 0
	global_load_lds_dwordx4 v194, s[48:49]
	s_add_i32 m0, s54, 0x2000
	s_nop 0
	global_load_lds_dwordx4 v198, s[48:49]
	s_waitcnt vmcnt(6)
	s_barrier
; #define PG8_STAGE(bufoff, gbase, voff) do { _Pragma("unroll") for (int _i = 0; _i < 2; ++_i) \
;         __builtin_amdgcn_global_load_lds((const unsigned*)((const char*)(gbase) + (voff)[_i]), (LAS unsigned*)(lds + (bufoff) + ldsw + _i * 8192), 16, 0, 0); } while (0)
; #define PG8_LDA(dst, b, h) do { _Pragma("unroll") for (int m = 0; m < 4; ++m) _Pragma("unroll") for (int k = 0; k < 2; ++k) dst[m][k] = *(const LAS bf16x8*)(lds + PG8_SA(b, h) + aoff + m * 2048 + k * 1024); } while (0)
; #define PG8_LDB(dst, b, h) do { _Pragma("unroll") for (int n = 0; n < 2; ++n) _Pragma("unroll") for (int k = 0; k < 2; ++k) dst[n][k] = *(const LAS bf16x8*)(lds + PG8_SB(b, h) + boff + n * 2048 + k * 1024); } while (0)
; #define PG8_MMA(ai, bj, At, Bt) do { __builtin_amdgcn_s_setprio(1); _Pragma("unroll") for (int m = 0; m < 4; ++m) _Pragma("unroll") for (int n = 0; n < 2; ++n) _Pragma("unroll") for (int k = 0; k < 2; ++k) \
;         acc[ai][bj][m][n] = __builtin_amdgcn_mfma_f32_16x16x32_bf16(Bt[n][k], At[m][k], acc[ai][bj][m][n], 0, 0, 0); __builtin_amdgcn_s_setprio(0); } while (0)
; #define PG8_WAIT_V(n) asm volatile("s_waitcnt vmcnt(" #n ")" ::: "memory")
; #define PG8_WAIT_L(n) asm volatile("s_waitcnt lgkmcnt(" #n ")" ::: "memory")
; #define PG8_BAR __builtin_amdgcn_s_barrier()
; #define PG8_SCHED __builtin_amdgcn_sched_barrier(0)
; template <class Epi, bool KS0 = false>
; __device__ __forceinline__ void gemm_phase(const int WID, LAS unsigned char* lds, const Gemm g, const StaticOrder& S, const Epi& E) {
;     ...
;             PG8_WAIT_V(6); PG8_BAR; PG8_MMA(1, 1, At, B1); PG8_BAR;
;             PG8_LDB(B0, 1, 0); PG8_SCHED; PG8_LDA(At, 1, 0); PG8_STAGE(PG8_SA(0, 1), a2 + hstep, voffA);
;             PG8_WAIT_L(8); PG8_BAR; PG8_WAIT_L(0); PG8_MMA(0, 0, At, B0); PG8_BAR; PG8_SCHED;
;             PG8_LDB(B1, 1, 1); PG8_STAGE(PG8_SB(1, 0), b3, voffB);
;             PG8_BAR; PG8_WAIT_L(0); PG8_MMA(0, 1, At, B1); PG8_BAR;
;             PG8_LDA(At, 1, 1); PG8_STAGE(PG8_SA(1, 0), a3, voffA);
;             PG8_BAR; PG8_WAIT_L(0); PG8_MMA(1, 0, At, B0); PG8_BAR; PG8_SCHED;
;             PG8_STAGE(PG8_SB(1, 1), b3 + hstep, voffB);
	v_mfma_f32_16x16x32_bf16 v[52:55], v[176:179], v[136:139], v[52:55]
	v_mfma_f32_16x16x32_bf16 v[48:51], v[184:187], v[136:139], v[48:51]
	v_mfma_f32_16x16x32_bf16 v[36:39], v[176:179], v[148:151], v[36:39]
	v_mfma_f32_16x16x32_bf16 v[32:35], v[184:187], v[148:151], v[32:35]
	v_mfma_f32_16x16x32_bf16 v[20:23], v[176:179], v[160:163], v[20:23]
	v_mfma_f32_16x16x32_bf16 v[16:19], v[184:187], v[160:163], v[16:19]
	v_mfma_f32_16x16x32_bf16 v[4:7], v[176:179], v[168:171], v[4:7]
	v_mfma_f32_16x16x32_bf16 v[0:3], v[184:187], v[168:171], v[0:3]
	v_mfma_f32_16x16x32_bf16 v[52:55], v[180:183], v[144:147], v[52:55]
	v_mfma_f32_16x16x32_bf16 v[48:51], v[188:191], v[144:147], v[48:51]
	v_mfma_f32_16x16x32_bf16 v[36:39], v[180:183], v[156:159], v[36:39]
	v_mfma_f32_16x16x32_bf16 v[32:35], v[188:191], v[156:159], v[32:35]
	v_mfma_f32_16x16x32_bf16 v[20:23], v[180:183], v[164:167], v[20:23]
	v_mfma_f32_16x16x32_bf16 v[16:19], v[188:191], v[164:167], v[16:19]
	v_mfma_f32_16x16x32_bf16 v[4:7], v[180:183], v[172:175], v[4:7]
	v_mfma_f32_16x16x32_bf16 v[0:3], v[188:191], v[172:175], v[0:3]
	s_add_i32 s48, 0, 0x18000
	v_add_u32_e32 v120, s48, v245
	s_barrier
	ds_read_b128 v[104:107], v120
	ds_read_b128 v[108:111], v120 offset:1024
	ds_read_b128 v[112:115], v120 offset:2048
	ds_read_b128 v[120:123], v120 offset:3072
	s_add_u32 s12, s12, 0x80000
	s_addc_u32 s13, s13, 0
	s_mov_b32 m0, s20
	v_lshl_add_u64 v[176:177], s[12:13], 0, v[192:193]
	ds_read_b128 v[136:139], v247 offset:32768
	ds_read_b128 v[144:147], v247 offset:33792
	ds_read_b128 v[148:151], v247 offset:34816
	ds_read_b128 v[156:159], v247 offset:35840
	ds_read_b128 v[160:163], v247 offset:36864
	ds_read_b128 v[164:167], v247 offset:37888
	ds_read_b128 v[168:171], v247 offset:38912
	ds_read_b128 v[172:175], v247 offset:39936
	global_load_lds_dwordx4 v[176:177], off
	s_mov_b32 m0, s21
	s_nop 0
	global_load_lds_dwordx4 v196, s[12:13]
	s_waitcnt lgkmcnt(8)
	s_barrier
	s_waitcnt lgkmcnt(0)
	v_mfma_f32_16x16x32_bf16 v[152:155], v[104:107], v[136:139], v[152:155]
	v_mfma_f32_16x16x32_bf16 v[140:143], v[112:115], v[136:139], v[140:143]
	v_mfma_f32_16x16x32_bf16 v[124:127], v[104:107], v[148:151], v[124:127]
	v_mfma_f32_16x16x32_bf16 v[116:119], v[112:115], v[148:151], v[116:119]
	v_mfma_f32_16x16x32_bf16 v[92:95], v[104:107], v[160:163], v[92:95]
	v_mfma_f32_16x16x32_bf16 v[88:91], v[112:115], v[160:163], v[88:91]
	v_mfma_f32_16x16x32_bf16 v[76:79], v[104:107], v[168:171], v[76:79]
	v_mfma_f32_16x16x32_bf16 v[72:75], v[112:115], v[168:171], v[72:75]
	v_mfma_f32_16x16x32_bf16 v[152:155], v[108:111], v[144:147], v[152:155]
	v_mfma_f32_16x16x32_bf16 v[140:143], v[120:123], v[144:147], v[140:143]
	v_mfma_f32_16x16x32_bf16 v[124:127], v[108:111], v[156:159], v[124:127]
	v_mfma_f32_16x16x32_bf16 v[116:119], v[120:123], v[156:159], v[116:119]
	v_mfma_f32_16x16x32_bf16 v[92:95], v[108:111], v[164:167], v[92:95]
	v_mfma_f32_16x16x32_bf16 v[88:91], v[120:123], v[164:167], v[88:91]
	v_mfma_f32_16x16x32_bf16 v[76:79], v[108:111], v[172:175], v[76:79]
	v_mfma_f32_16x16x32_bf16 v[72:75], v[120:123], v[172:175], v[72:75]
	s_barrier
	s_add_i32 s12, 0, 0x1c000
	s_add_i32 s13, s48, s26
	v_add_u32_e32 v188, s12, v245
	v_lshl_add_u64 v[210:211], v[210:211], 0, s[30:31]
	s_mov_b32 m0, s13
	ds_read_b128 v[176:179], v188
	ds_read_b128 v[180:183], v188 offset:1024
	ds_read_b128 v[184:187], v188 offset:2048
	ds_read_b128 v[188:191], v188 offset:3072
	global_load_lds_dwordx4 v[210:211], off
	v_lshl_add_u64 v[210:211], v[212:213], 0, s[30:31]
	s_add_i32 m0, s13, 0x2000
	s_nop 0
	global_load_lds_dwordx4 v[210:211], off
	s_barrier
	s_waitcnt lgkmcnt(0)
	v_mfma_f32_16x16x32_bf16 v[132:135], v[176:179], v[136:139], v[132:135]
	v_mfma_f32_16x16x32_bf16 v[128:131], v[184:187], v[136:139], v[128:131]
	v_mfma_f32_16x16x32_bf16 v[100:103], v[176:179], v[148:151], v[100:103]
	v_mfma_f32_16x16x32_bf16 v[96:99], v[184:187], v[148:151], v[96:99]
	v_mfma_f32_16x16x32_bf16 v[84:87], v[176:179], v[160:163], v[84:87]
	v_mfma_f32_16x16x32_bf16 v[80:83], v[184:187], v[160:163], v[80:83]
	v_mfma_f32_16x16x32_bf16 v[68:71], v[176:179], v[168:171], v[68:71]
	v_mfma_f32_16x16x32_bf16 v[64:67], v[184:187], v[168:171], v[64:67]
	v_mfma_f32_16x16x32_bf16 v[132:135], v[180:183], v[144:147], v[132:135]
	v_mfma_f32_16x16x32_bf16 v[128:131], v[188:191], v[144:147], v[128:131]
	v_mfma_f32_16x16x32_bf16 v[100:103], v[180:183], v[156:159], v[100:103]
	v_mfma_f32_16x16x32_bf16 v[96:99], v[188:191], v[156:159], v[96:99]
	v_mfma_f32_16x16x32_bf16 v[84:87], v[180:183], v[164:167], v[84:87]
	v_mfma_f32_16x16x32_bf16 v[80:83], v[188:191], v[164:167], v[80:83]
	v_mfma_f32_16x16x32_bf16 v[68:71], v[180:183], v[172:175], v[68:71]
	v_mfma_f32_16x16x32_bf16 v[64:67], v[188:191], v[172:175], v[64:67]
	s_mov_b32 m0, s25
	v_lshl_add_u64 v[210:211], v[214:215], 0, s[30:31]
	s_barrier
	ds_read_b128 v[136:139], v247 offset:49152
	ds_read_b128 v[144:147], v247 offset:50176
	ds_read_b128 v[148:151], v247 offset:51200
	ds_read_b128 v[156:159], v247 offset:52224
	ds_read_b128 v[160:163], v247 offset:53248
	ds_read_b128 v[164:167], v247 offset:54272
	ds_read_b128 v[168:171], v247 offset:55296
	ds_read_b128 v[172:175], v247 offset:56320
	global_load_lds_dwordx4 v[210:211], off
	v_lshl_add_u64 v[210:211], v[216:217], 0, s[30:31]
	s_mov_b32 m0, s39
	s_nop 0
	global_load_lds_dwordx4 v[210:211], off
	s_barrier
; #define PG8_STAGE(bufoff, gbase, voff) do { _Pragma("unroll") for (int _i = 0; _i < 2; ++_i) \
;         __builtin_amdgcn_global_load_lds((const unsigned*)((const char*)(gbase) + (voff)[_i]), (LAS unsigned*)(lds + (bufoff) + ldsw + _i * 8192), 16, 0, 0); } while (0)
; #define PG8_MMA(ai, bj, At, Bt) do { __builtin_amdgcn_s_setprio(1); _Pragma("unroll") for (int m = 0; m < 4; ++m) _Pragma("unroll") for (int n = 0; n < 2; ++n) _Pragma("unroll") for (int k = 0; k < 2; ++k) \
;         acc[ai][bj][m][n] = __builtin_amdgcn_mfma_f32_16x16x32_bf16(Bt[n][k], At[m][k], acc[ai][bj][m][n], 0, 0, 0); __builtin_amdgcn_s_setprio(0); } while (0)
; #define PG8_WAIT_V(n) asm volatile("s_waitcnt vmcnt(" #n ")" ::: "memory")
; #define PG8_WAIT_L(n) asm volatile("s_waitcnt lgkmcnt(" #n ")" ::: "memory")
; #define PG8_BAR __builtin_amdgcn_s_barrier()
; #define PG8_SCHED __builtin_amdgcn_sched_barrier(0)
; template <class Epi, bool KS0 = false>
; __device__ __forceinline__ void gemm_phase(const int WID, LAS unsigned char* lds, const Gemm g, const StaticOrder& S, const Epi& E) {
;     ...
;             PG8_BAR; PG8_WAIT_L(0); PG8_MMA(1, 0, At, B0); PG8_BAR; PG8_SCHED;
;             PG8_STAGE(PG8_SB(1, 1), b3 + hstep, voffB);
;             PG8_WAIT_V(6); PG8_BAR; PG8_MMA(1, 1, At, B1); PG8_BAR;
;     __device__ __forceinline__ void operator()(f32x4 (&acc)[2][2][4][2], const Unit& u, int wr, int wc, int fr, int fq) const {
;         const int row0 = u.pm * BM + wr * 64 + fr, col0 = u.pn * BM + wc * 32 + 8 * fq;
;         const bf16_t* ppf = pp + ((size_t)(u.pm * (DM / 256) + u.pn) << 16) + (size_t)((((wr * 4 + wc) * 16) * 64 + fq * 16 + fr) << 3);
; #pragma unroll
;         for (int ai = 0; ai < 2; ++ai) {
;             u32x4 hw[4][2], pw[4][2]; float rstd[4];
; #pragma unroll
;             for (int m = 0; m < 4; ++m) { const int row = row0 + ai * HALF + m * 16;
; #pragma unroll
;                 for (int bj = 0; bj < 2; ++bj) { const size_t o = (size_t)row * DM + col0 + bj * HALF; hw[m][bj] = *(const u32x4*)(hb + o); pw[m][bj] = *(const u32x4*)(ppf + (((ai * 4 + m) * 2 + bj) << 9)); }
;                 rstd[m] = row_rstd(ssq_in, row, fq); }
	s_waitcnt lgkmcnt(0)
	v_mfma_f32_16x16x32_bf16 v[60:63], v[104:107], v[136:139], v[60:63]
	v_mfma_f32_16x16x32_bf16 v[56:59], v[112:115], v[136:139], v[56:59]
	v_mfma_f32_16x16x32_bf16 v[44:47], v[104:107], v[148:151], v[44:47]
	v_mfma_f32_16x16x32_bf16 v[40:43], v[112:115], v[148:151], v[40:43]
	v_mfma_f32_16x16x32_bf16 v[28:31], v[104:107], v[160:163], v[28:31]
	v_mfma_f32_16x16x32_bf16 v[24:27], v[112:115], v[160:163], v[24:27]
	v_mfma_f32_16x16x32_bf16 v[12:15], v[104:107], v[168:171], v[12:15]
	v_mfma_f32_16x16x32_bf16 v[8:11], v[112:115], v[168:171], v[8:11]
	v_mfma_f32_16x16x32_bf16 v[60:63], v[108:111], v[144:147], v[60:63]
	v_mfma_f32_16x16x32_bf16 v[56:59], v[120:123], v[144:147], v[56:59]
	v_mfma_f32_16x16x32_bf16 v[44:47], v[108:111], v[156:159], v[44:47]
	v_mfma_f32_16x16x32_bf16 v[40:43], v[120:123], v[156:159], v[40:43]
	v_mfma_f32_16x16x32_bf16 v[28:31], v[108:111], v[164:167], v[28:31]
	v_mfma_f32_16x16x32_bf16 v[24:27], v[120:123], v[164:167], v[24:27]
	v_mfma_f32_16x16x32_bf16 v[12:15], v[108:111], v[172:175], v[12:15]
	v_mfma_f32_16x16x32_bf16 v[8:11], v[120:123], v[172:175], v[8:11]
	s_barrier
	s_add_u32 s10, s10, 0x80080
	s_addc_u32 s11, s11, 0
	s_add_i32 s12, s12, s26
	s_mov_b32 m0, s12
	s_nop 0
	global_load_lds_dwordx4 v194, s[10:11]
	s_add_i32 m0, s12, 0x2000
	s_nop 0
	global_load_lds_dwordx4 v198, s[10:11]
	s_waitcnt vmcnt(6)
	s_barrier
	v_mfma_f32_16x16x32_bf16 v[52:55], v[176:179], v[136:139], v[52:55]
	v_mfma_f32_16x16x32_bf16 v[48:51], v[184:187], v[136:139], v[48:51]
	v_mfma_f32_16x16x32_bf16 v[36:39], v[176:179], v[148:151], v[36:39]
	v_mfma_f32_16x16x32_bf16 v[32:35], v[184:187], v[148:151], v[32:35]
	v_mfma_f32_16x16x32_bf16 v[20:23], v[176:179], v[160:163], v[20:23]
	v_mfma_f32_16x16x32_bf16 v[16:19], v[184:187], v[160:163], v[16:19]
	v_mfma_f32_16x16x32_bf16 v[4:7], v[176:179], v[168:171], v[4:7]
	v_mfma_f32_16x16x32_bf16 v[0:3], v[184:187], v[168:171], v[0:3]
	v_mfma_f32_16x16x32_bf16 v[52:55], v[180:183], v[144:147], v[52:55]
	v_mfma_f32_16x16x32_bf16 v[48:51], v[188:191], v[144:147], v[48:51]
	v_mfma_f32_16x16x32_bf16 v[36:39], v[180:183], v[156:159], v[36:39]
	v_mfma_f32_16x16x32_bf16 v[32:35], v[188:191], v[156:159], v[32:35]
	v_mfma_f32_16x16x32_bf16 v[20:23], v[180:183], v[164:167], v[20:23]
	v_mfma_f32_16x16x32_bf16 v[16:19], v[188:191], v[164:167], v[16:19]
	v_mfma_f32_16x16x32_bf16 v[4:7], v[180:183], v[172:175], v[4:7]
	v_mfma_f32_16x16x32_bf16 v[0:3], v[188:191], v[172:175], v[0:3]
	s_add_i32 s43, s43, 2
	s_add_u32 s8, s8, 0x100
	s_addc_u32 s9, s9, 0
	s_add_u32 s37, s37, 0x100
	s_addc_u32 s41, s41, 0
	s_cmp_gt_u32 s43, 29
	s_barrier
	s_cbranch_scc0 .LBB0_1006
	s_lshl_b32 s3, s4, 8
	v_mbcnt_lo_u32_b32 v104, -1, 0
	v_mbcnt_hi_u32_b32 v104, -1, v104
	s_add_i32 s3, s3, s22
	v_ashrrev_i32_e32 v108, 4, v104
	v_and_b32_e32 v109, 15, v104
	v_readlane_b32 s8, v254, 19
	v_add_u32_e32 v212, s3, v109
	v_lshlrev_b32_e32 v104, 3, v108
	v_ashrrev_i32_e32 v105, 31, v104
	v_ashrrev_i32_e32 v213, 31, v212
	v_add_u32_e32 v160, 16, v212
	v_lshl_add_u64 v[214:215], v[104:105], 2, s[16:17]
	v_lshlrev_b64 v[236:237], 7, v[212:213]
	v_ashrrev_i32_e32 v161, 31, v160
	v_lshl_add_u64 v[106:107], v[214:215], 0, v[236:237]
	v_lshlrev_b64 v[228:229], 7, v[160:161]
	global_load_dwordx4 v[136:139], v[106:107], off
	global_load_dwordx4 v[144:147], v[106:107], off offset:16
	v_lshl_add_u64 v[106:107], v[214:215], 0, v[228:229]
	global_load_dwordx4 v[148:151], v[106:107], off
	global_load_dwordx4 v[156:159], v[106:107], off offset:16
	v_and_b32_e32 v106, 64, v209
	v_xor_b32_e32 v105, 16, v209
	v_add_u32_e32 v106, 64, v106
	v_add_u32_e32 v162, 32, v212
	v_xor_b32_e32 v107, 32, v209
	v_cmp_lt_i32_e32 vcc, v105, v106
	v_ashrrev_i32_e32 v163, 31, v162
	v_lshlrev_b64 v[222:223], 7, v[162:163]
	v_cndmask_b32_e32 v105, v209, v105, vcc
	v_cmp_lt_i32_e32 vcc, v107, v106
	v_add_u32_e32 v226, 48, v212
	s_lshl_b32 s3, s2, 8
	v_cndmask_b32_e32 v110, v209, v107, vcc
	v_lshl_add_u64 v[106:107], v[214:215], 0, v[222:223]
	v_ashrrev_i32_e32 v227, 31, v226
	s_or_b32 s3, s3, s8
	global_load_dwordx4 v[112:115], v[106:107], off
	global_load_dwordx4 v[120:123], v[106:107], off offset:16
	v_lshlrev_b64 v[220:221], 7, v[226:227]
	v_lshlrev_b32_e32 v250, 2, v105
	v_add_u32_e32 v210, s3, v104
	v_lshl_add_u64 v[104:105], v[214:215], 0, v[220:221]
	v_add_u32_e32 v164, s55, v109
	v_lshlrev_b32_e32 v165, 7, v108
	v_lshlrev_b32_e32 v249, 2, v110
	v_cmp_eq_u32_e64 s[36:37], 0, v108
	global_load_dwordx4 v[108:111], v[104:105], off
	s_nop 0
	global_load_dwordx4 v[104:107], v[104:105], off offset:16
	s_lshl_b32 s4, s4, 3
	s_add_i32 s8, s4, s2
	s_ashr_i32 s9, s8, 31
	s_lshl_b64 s[8:9], s[8:9], 17
	v_ashrrev_i32_e32 v211, 31, v210
	s_add_u32 s8, s23, s8
	v_lshl_add_u32 v164, v164, 3, v165
	v_lshlrev_b64 v[240:241], 1, v[210:211]
	s_addc_u32 s9, s24, s9
	v_ashrrev_i32_e32 v165, 31, v164
	v_lshlrev_b64 v[238:239], 12, v[212:213]
	v_lshl_add_u64 v[216:217], s[6:7], 0, v[240:241]
	v_lshl_add_u64 v[218:219], v[164:165], 1, s[8:9]
	v_lshl_add_u64 v[164:165], v[216:217], 0, v[238:239]
	global_load_dwordx4 v[184:187], v[218:219], off
	global_load_dwordx4 v[188:191], v[164:165], off
	global_load_dwordx4 v[176:179], v[218:219], off offset:1024
	s_lshl_b32 s48, s2, 2
	v_lshlrev_b64 v[234:235], 12, v[160:161]
	v_lshlrev_b64 v[224:225], 12, v[162:163]
	v_lshlrev_b64 v[226:227], 12, v[226:227]
	s_ashr_i32 s49, s48, 31
	s_waitcnt vmcnt(0)
; __device__ __forceinline__ unsigned cvt_pk_bf16(float lo, float hi) { unsigned r; asm volatile("v_cvt_pk_bf16_f32 %0, %1, %2" : "=v"(r) : "v"(lo), "v"(hi)); return r; }
; __device__ __forceinline__ float bflo(unsigned w) { return __uint_as_float(w << 16); }
; __device__ __forceinline__ float bfhi(unsigned w) { return __uint_as_float(w & 0xffff0000u); }
; __device__ __forceinline__ float sigmoidf_(float x) { return __builtin_amdgcn_rcpf(1.0f + __expf(-x)); }
;     __device__ __forceinline__ void operator()(f32x4 (&acc)[2][2][4][2], const Unit& u, int wr, int wc, int fr, int fq) const {
;     ...
;             for (int m = 0; m < 4; ++m) { const int row = row0 + ai * HALF + m * 16;
; #pragma unroll
;                 for (int bj = 0; bj < 2; ++bj) { const size_t o = (size_t)row * DM + col0 + bj * HALF; hw[m][bj] = *(const u32x4*)(hb + o); pw[m][bj] = *(const u32x4*)(ppf + (((ai * 4 + m) * 2 + bj) << 9)); }
;                 rstd[m] = row_rstd(ssq_in, row, fq); }
; #pragma unroll
;             for (int m = 0; m < 4; ++m) { const int row = row0 + ai * HALF + m * 16; const size_t off = (size_t)row * DM + col0; float s = 0.f;
; #pragma unroll
;                 for (int bj = 0; bj < 2; ++bj) { const f32x4 z0 = acc[ai][bj][m][0] * rstd[m], z1 = acc[ai][bj][m][1] * rstd[m]; const u32x4 h2 = hw[m][bj], p2 = pw[m][bj]; f32x4 v0, v1;
;                     v0[0] = bflo(h2.x) + sigmoidf_(z0[0]) * bflo(p2.x); v0[1] = bfhi(h2.x) + sigmoidf_(z0[1]) * bfhi(p2.x);
;                     v0[2] = bflo(h2.y) + sigmoidf_(z0[2]) * bflo(p2.y); v0[3] = bfhi(h2.y) + sigmoidf_(z0[3]) * bfhi(p2.y);
;                     v1[0] = bflo(h2.z) + sigmoidf_(z1[0]) * bflo(p2.z); v1[1] = bfhi(h2.z) + sigmoidf_(z1[1]) * bfhi(p2.z);
;                     v1[2] = bflo(h2.w) + sigmoidf_(z1[2]) * bflo(p2.w); v1[3] = bfhi(h2.w) + sigmoidf_(z1[3]) * bfhi(p2.w);
;                     u32x4 w; w.x = cvt_pk_bf16(v0[0], v0[1]); w.y = cvt_pk_bf16(v0[2], v0[3]); w.z = cvt_pk_bf16(v1[0], v1[1]); w.w = cvt_pk_bf16(v1[2], v1[3]);
;                     *(u32x4*)(out + off + bj * HALF) = w;
;                     s += ((v0[0] * v0[0] + v0[1] * v0[1]) + (v0[2] * v0[2] + v0[3] * v0[3])) + ((v1[0] * v1[0] + v1[1] * v1[1]) + (v1[2] * v1[2] + v1[3] * v1[3])); }
	v_mov_b32_e32 v166, v136
	v_mov_b32_e32 v167, v144
	v_mov_b32_e32 v144, v137
	v_mov_b32_e32 v136, v138
	v_mov_b32_e32 v137, v146
	v_mov_b32_e32 v146, v139
	v_pk_add_f32 v[138:139], v[166:167], v[144:145]
	v_pk_add_f32 v[136:137], v[136:137], v[146:147]
	v_mov_b32_e32 v144, v148
	v_mov_b32_e32 v145, v156
	v_mov_b32_e32 v156, v149
	v_mov_b32_e32 v146, v150
	v_mov_b32_e32 v147, v158
	v_mov_b32_e32 v158, v151
	v_pk_add_f32 v[136:137], v[138:139], v[136:137]
	v_pk_add_f32 v[138:139], v[144:145], v[156:157]
	v_pk_add_f32 v[144:145], v[146:147], v[158:159]
	v_lshl_add_u64 v[150:151], v[216:217], 0, v[234:235]
	v_pk_add_f32 v[138:139], v[138:139], v[144:145]
	v_mov_b32_e32 v145, v136
	v_mov_b32_e32 v144, v138
	v_mov_b32_e32 v136, v139
	v_pk_add_f32 v[136:137], v[144:145], v[136:137]
	ds_bpermute_b32 v139, v250, v137
	ds_bpermute_b32 v138, v250, v136
	v_mov_b32_e32 v232, v112
	v_mov_b32_e32 v233, v120
	v_mov_b32_e32 v120, v113
	v_pk_add_f32 v[112:113], v[232:233], v[120:121]
	s_waitcnt lgkmcnt(0)
	v_pk_add_f32 v[146:147], v[136:137], v[138:139]
	global_load_dwordx4 v[168:171], v[218:219], off offset:2048
	global_load_dwordx4 v[136:139], v[218:219], off offset:3072
	global_load_dwordx4 v[180:183], v[164:165], off offset:256
	ds_bpermute_b32 v149, v249, v147
	ds_bpermute_b32 v148, v249, v146
	v_mov_b32_e32 v120, v114
	v_mov_b32_e32 v121, v122
	v_mov_b32_e32 v122, v115
	v_pk_add_f32 v[114:115], v[120:121], v[122:123]
	s_waitcnt lgkmcnt(0)
	v_pk_add_f32 v[146:147], v[146:147], v[148:149]
	v_mov_b32_e32 v120, v108
	v_pk_fma_f32 v[242:243], v[146:147], s[38:39], v[208:209] op_sel_hi:[1,0,0]
	v_mov_b32_e32 v121, v104
	v_mul_f32_e32 v146, 0x4b800000, v243
	v_cmp_gt_f32_e64 s[2:3], s52, v243
	v_mov_b32_e32 v104, v109
	v_mov_b32_e32 v108, v110
	v_cndmask_b32_e64 v146, v243, v146, s[2:3]
	v_rsq_f32_e32 v146, v146
	v_mov_b32_e32 v109, v106
	v_mov_b32_e32 v106, v111
	v_pk_add_f32 v[104:105], v[120:121], v[104:105]
	v_mul_f32_e32 v147, 0x45800000, v146
	v_cndmask_b32_e64 v244, v146, v147, s[2:3]
	v_pk_add_f32 v[106:107], v[108:109], v[106:107]
	v_pk_mul_f32 v[152:153], v[152:153], v[244:245] op_sel_hi:[1,0]
	s_movk_i32 s2, 0x1000
	v_pk_add_f32 v[112:113], v[112:113], v[114:115]
	v_pk_add_f32 v[104:105], v[104:105], v[106:107]
	v_mul_f32_e32 v152, 0xbfb8aa3b, v152
	v_lshl_add_u64 v[144:145], v[216:217], 0, v[224:225]
	v_add_co_u32_e64 v230, s[2:3], s2, v218
	v_lshl_add_u64 v[114:115], v[216:217], 0, v[226:227]
	v_mov_b32_e32 v106, v104
	v_mov_b32_e32 v107, v112
	v_mov_b32_e32 v112, v105
	v_exp_f32_e32 v152, v152
	v_mul_f32_e32 v153, 0xbfb8aa3b, v153
	global_load_dwordx4 v[172:175], v[150:151], off
	global_load_dwordx4 v[156:159], v[150:151], off offset:256
	v_addc_co_u32_e64 v231, s[2:3], 0, v219, s[2:3]
	global_load_dwordx4 v[160:163], v[144:145], off
	s_nop 0
	global_load_dwordx4 v[144:147], v[144:145], off offset:256
	s_nop 0
	global_load_dwordx4 v[164:167], v[230:231], off
	global_load_dwordx4 v[148:151], v[230:231], off offset:1024
	v_pk_add_f32 v[232:233], v[106:107], v[112:113]
	global_load_dwordx4 v[120:123], v[114:115], off
	global_load_dwordx4 v[108:111], v[114:115], off offset:256
	s_nop 0
	global_load_dwordx4 v[112:115], v[230:231], off offset:2048
	global_load_dwordx4 v[104:107], v[230:231], off offset:3072
	v_exp_f32_e32 v153, v153
	v_add_f32_e32 v152, 1.0, v152
	v_rcp_f32_e32 v152, v152
	v_lshlrev_b32_e32 v213, 16, v188
	v_add_f32_e32 v153, 1.0, v153
	v_rcp_f32_e32 v153, v153
	v_lshlrev_b32_e32 v243, 16, v184
	v_pk_mul_f32 v[154:155], v[154:155], v[244:245] op_sel_hi:[1,0]
	v_fmac_f32_e32 v213, v152, v243
	v_and_b32_e32 v152, 0xffff0000, v188
	v_and_b32_e32 v184, 0xffff0000, v184
	v_fmac_f32_e32 v152, v153, v184
	v_mul_f32_e32 v153, 0xbfb8aa3b, v154
	v_pk_mul_f32 v[140:141], v[140:141], v[244:245] op_sel_hi:[1,0]
	v_exp_f32_e32 v153, v153
	v_mul_f32_e32 v155, 0xbfb8aa3b, v155
	v_exp_f32_e32 v155, v155
	v_mul_f32_e32 v140, 0xbfb8aa3b, v140
	v_exp_f32_e32 v140, v140
	v_mul_f32_e32 v141, 0xbfb8aa3b, v141
	v_exp_f32_e32 v141, v141
	v_add_f32_e32 v153, 1.0, v153
	v_rcp_f32_e32 v153, v153
	v_add_f32_e32 v155, 1.0, v155
	v_rcp_f32_e32 v155, v155
	v_add_f32_e32 v140, 1.0, v140
	v_rcp_f32_e32 v140, v140
	v_add_f32_e32 v141, 1.0, v141
	v_lshlrev_b32_e32 v154, 16, v189
	v_lshlrev_b32_e32 v184, 16, v185
	v_rcp_f32_e32 v141, v141
	v_fmac_f32_e32 v154, v153, v184
	v_and_b32_e32 v153, 0xffff0000, v189
	v_and_b32_e32 v184, 0xffff0000, v185
	v_fmac_f32_e32 v153, v155, v184
	v_lshlrev_b32_e32 v155, 16, v190
	v_lshlrev_b32_e32 v184, 16, v186
	v_pk_mul_f32 v[142:143], v[142:143], v[244:245] op_sel_hi:[1,0]
	v_fmac_f32_e32 v155, v140, v184
	v_and_b32_e32 v184, 0xffff0000, v190
	v_and_b32_e32 v140, 0xffff0000, v186
	v_fmac_f32_e32 v184, v141, v140
	v_mul_f32_e32 v140, 0xbfb8aa3b, v142
	v_exp_f32_e32 v140, v140
	v_mul_f32_e32 v141, 0xbfb8aa3b, v143
	v_exp_f32_e32 v141, v141
	v_pk_mul_f32 v[132:133], v[132:133], v[244:245] op_sel_hi:[1,0]
	v_add_f32_e32 v140, 1.0, v140
	v_rcp_f32_e32 v140, v140
	v_add_f32_e32 v141, 1.0, v141
	v_rcp_f32_e32 v141, v141
	v_mul_f32_e32 v132, 0xbfb8aa3b, v132
	v_exp_f32_e32 v132, v132
	v_mul_f32_e32 v133, 0xbfb8aa3b, v133
	v_lshlrev_b32_e32 v185, 16, v191
	v_lshlrev_b32_e32 v142, 16, v187
	v_exp_f32_e32 v133, v133
	v_fmac_f32_e32 v185, v140, v142
	v_and_b32_e32 v186, 0xffff0000, v191
	v_and_b32_e32 v140, 0xffff0000, v187
	v_fmac_f32_e32 v186, v141, v140
	v_cvt_pk_bf16_f32 v140, v213, v152
	v_cvt_pk_bf16_f32 v141, v154, v153
	v_mul_f32_e32 v152, v152, v152
	v_mul_f32_e32 v153, v153, v153
	v_fmac_f32_e32 v152, v213, v213
	v_fmac_f32_e32 v153, v154, v154
	v_add_f32_e32 v132, 1.0, v132
	v_add_f32_e32 v152, v152, v153
	v_mul_f32_e32 v153, v184, v184
	v_mul_f32_e32 v154, v186, v186
	v_rcp_f32_e32 v132, v132
	v_add_f32_e32 v133, 1.0, v133
	v_fmac_f32_e32 v153, v155, v155
	v_fmac_f32_e32 v154, v185, v185
	v_rcp_f32_e32 v133, v133
	v_add_f32_e32 v153, v153, v154
	v_add_f32_e32 v152, v152, v153
	s_waitcnt vmcnt(10)
; __device__ __forceinline__ unsigned cvt_pk_bf16(float lo, float hi) { unsigned r; asm volatile("v_cvt_pk_bf16_f32 %0, %1, %2" : "=v"(r) : "v"(lo), "v"(hi)); return r; }
; __device__ __forceinline__ float bflo(unsigned w) { return __uint_as_float(w << 16); }
; __device__ __forceinline__ float bfhi(unsigned w) { return __uint_as_float(w & 0xffff0000u); }
; __device__ __forceinline__ float sigmoidf_(float x) { return __builtin_amdgcn_rcpf(1.0f + __expf(-x)); }
;     __device__ __forceinline__ void operator()(f32x4 (&acc)[2][2][4][2], const Unit& u, int wr, int wc, int fr, int fq) const {
;     ...
;             for (int m = 0; m < 4; ++m) { const int row = row0 + ai * HALF + m * 16; const size_t off = (size_t)row * DM + col0; float s = 0.f;
; #pragma unroll
;                 for (int bj = 0; bj < 2; ++bj) { const f32x4 z0 = acc[ai][bj][m][0] * rstd[m], z1 = acc[ai][bj][m][1] * rstd[m]; const u32x4 h2 = hw[m][bj], p2 = pw[m][bj]; f32x4 v0, v1;
;                     v0[0] = bflo(h2.x) + sigmoidf_(z0[0]) * bflo(p2.x); v0[1] = bfhi(h2.x) + sigmoidf_(z0[1]) * bfhi(p2.x);
;                     v0[2] = bflo(h2.y) + sigmoidf_(z0[2]) * bflo(p2.y); v0[3] = bfhi(h2.y) + sigmoidf_(z0[3]) * bfhi(p2.y);
;                     v1[0] = bflo(h2.z) + sigmoidf_(z1[0]) * bflo(p2.z); v1[1] = bfhi(h2.z) + sigmoidf_(z1[1]) * bfhi(p2.z);
;                     v1[2] = bflo(h2.w) + sigmoidf_(z1[2]) * bflo(p2.w); v1[3] = bfhi(h2.w) + sigmoidf_(z1[3]) * bfhi(p2.w);
;                     u32x4 w; w.x = cvt_pk_bf16(v0[0], v0[1]); w.y = cvt_pk_bf16(v0[2], v0[3]); w.z = cvt_pk_bf16(v1[0], v1[1]); w.w = cvt_pk_bf16(v1[2], v1[3]);
;                     *(u32x4*)(out + off + bj * HALF) = w;
;                     s += ((v0[0] * v0[0] + v0[1] * v0[1]) + (v0[2] * v0[2] + v0[3] * v0[3])) + ((v1[0] * v1[0] + v1[1] * v1[1]) + (v1[2] * v1[2] + v1[3] * v1[3])); }
;                 s += __shfl_xor(s, 16); s += __shfl_xor(s, 32);
;                 if (fq == 0) ssq[(size_t)row * 32 + u.pn * 4 + wc] = s; }
	v_lshlrev_b32_e32 v153, 16, v180
	v_lshlrev_b32_e32 v154, 16, v176
	v_pk_mul_f32 v[134:135], v[134:135], v[244:245] op_sel_hi:[1,0]
	v_fmac_f32_e32 v153, v132, v154
	v_and_b32_e32 v132, 0xffff0000, v180
	v_and_b32_e32 v154, 0xffff0000, v176
	v_fmac_f32_e32 v132, v133, v154
	v_mul_f32_e32 v133, 0xbfb8aa3b, v134
	v_pk_mul_f32 v[128:129], v[128:129], v[244:245] op_sel_hi:[1,0]
	v_exp_f32_e32 v133, v133
	v_mul_f32_e32 v134, 0xbfb8aa3b, v135
	v_exp_f32_e32 v134, v134
	v_mul_f32_e32 v128, 0xbfb8aa3b, v128
	v_exp_f32_e32 v128, v128
	v_mul_f32_e32 v129, 0xbfb8aa3b, v129
	v_exp_f32_e32 v129, v129
	v_add_f32_e32 v133, 1.0, v133
	v_rcp_f32_e32 v133, v133
	v_add_f32_e32 v134, 1.0, v134
	v_rcp_f32_e32 v134, v134
	v_add_f32_e32 v128, 1.0, v128
	v_rcp_f32_e32 v128, v128
	v_add_f32_e32 v129, 1.0, v129
	v_lshlrev_b32_e32 v154, 16, v181
	v_lshlrev_b32_e32 v135, 16, v177
	v_rcp_f32_e32 v129, v129
	v_fmac_f32_e32 v154, v133, v135
	v_and_b32_e32 v133, 0xffff0000, v181
	v_and_b32_e32 v135, 0xffff0000, v177
	v_cvt_pk_bf16_f32 v142, v155, v184
	v_fmac_f32_e32 v133, v134, v135
	v_lshlrev_b32_e32 v155, 16, v182
	v_lshlrev_b32_e32 v134, 16, v178
	v_pk_mul_f32 v[130:131], v[130:131], v[244:245] op_sel_hi:[1,0]
	v_fmac_f32_e32 v155, v128, v134
	v_and_b32_e32 v176, 0xffff0000, v182
	v_and_b32_e32 v128, 0xffff0000, v178
	v_fmac_f32_e32 v176, v129, v128
	v_mul_f32_e32 v128, 0xbfb8aa3b, v130
	v_exp_f32_e32 v128, v128
	v_mul_f32_e32 v129, 0xbfb8aa3b, v131
	v_exp_f32_e32 v129, v129
	v_lshlrev_b32_e32 v177, 16, v183
	v_add_f32_e32 v128, 1.0, v128
	v_rcp_f32_e32 v128, v128
	v_add_f32_e32 v129, 1.0, v129
	v_rcp_f32_e32 v129, v129
	v_lshlrev_b32_e32 v130, 16, v179
	v_fmac_f32_e32 v177, v128, v130
	v_and_b32_e32 v178, 0xffff0000, v183
	v_and_b32_e32 v128, 0xffff0000, v179
	v_fmac_f32_e32 v178, v129, v128
	v_mul_f32_e32 v128, v132, v132
	v_mul_f32_e32 v129, v133, v133
	v_fmac_f32_e32 v128, v153, v153
	v_fmac_f32_e32 v129, v154, v154
	v_add_f32_e32 v128, v128, v129
	v_mul_f32_e32 v129, v176, v176
	v_mul_f32_e32 v130, v178, v178
	v_fmac_f32_e32 v129, v155, v155
	v_fmac_f32_e32 v130, v177, v177
	v_add_f32_e32 v129, v129, v130
	v_add_f32_e32 v128, v128, v129
	v_add_f32_e32 v131, v152, v128
	ds_bpermute_b32 v253, v250, v233
	ds_bpermute_b32 v252, v250, v232
	ds_bpermute_b32 v152, v250, v131
	v_lshl_add_u64 v[128:129], s[0:1], 0, v[238:239]
	v_lshl_add_u64 v[134:135], v[128:129], 0, v[240:241]
	v_cmp_gt_f32_e32 vcc, s52, v242
	s_waitcnt lgkmcnt(1)
	v_pk_add_f32 v[230:231], v[232:233], v[252:253]
	s_waitcnt lgkmcnt(0)
	v_add_f32_e32 v128, v131, v152
	ds_bpermute_b32 v233, v249, v231
	ds_bpermute_b32 v232, v249, v230
	ds_bpermute_b32 v129, v249, v128
	v_cvt_pk_bf16_f32 v143, v185, v186
	global_store_dwordx4 v[134:135], v[140:143], off
	v_cvt_pk_bf16_f32 v130, v153, v132
	v_cvt_pk_bf16_f32 v131, v154, v133
	v_cvt_pk_bf16_f32 v132, v155, v176
	v_cvt_pk_bf16_f32 v133, v177, v178
	global_store_dwordx4 v[134:135], v[130:133], off offset:256
	s_and_saveexec_b64 s[2:3], s[36:37]
	s_cbranch_execz .LBB0_1009
	v_lshl_add_u64 v[130:131], s[28:29], 0, v[236:237]
	v_lshl_add_u64 v[130:131], s[48:49], 2, v[130:131]
	s_lshl_b32 s4, s27, 2
	v_lshl_add_u64 v[130:131], v[130:131], 0, s[4:5]
	s_waitcnt lgkmcnt(0)
	v_add_f32_e32 v128, v128, v129
	global_store_dword v[130:131], v128, off
